# K-loop handoff (barrier above last MFMA, prio 2) + P7 gate-line touch prefetch in mid and epilogue
# baseline (speedup 1.0000x reference)
; __device__ __forceinline__ float bf_lo(unsigned w) { return __uint_as_float(w << 16); }
; __device__ __forceinline__ float bf_hi(unsigned w) { return __uint_as_float(w & 0xffff0000u); }
;     __device__ __forceinline__ void mid(f32x4 (&acc)[2][2][4][2], const Unit& u, int wr, int wc, int fr, int fq) const {
;         int row0 = u.pm * BM + wr * 64 + fr, col0 = u.pn * BM + wc * 32 + 8 * fq;
;         asm volatile("" : "+v"(row0), "+v"(col0));
; #pragma unroll
;         for (int bj = 0; bj < 2; ++bj) { const f32x4 a0 = *(const f32x4*)(bias + col0 + bj * HALF), a1 = *(const f32x4*)(bias + col0 + bj * HALF + 4), b0 = *(const f32x4*)(bias + nb + col0 + bj * HALF), b1 = *(const f32x4*)(bias + nb + col0 + bj * HALF + 4);
; #pragma unroll
;             for (int ai = 0; ai < 2; ++ai)
; #pragma unroll
;                 for (int m = 0; m < 4; ++m) { const size_t r = (size_t)(row0 + ai * HALF + m * 16);
;                     const u32x4 ga = *(const u32x4*)(GA + r * ldg + col0 + bj * HALF), gb = *(const u32x4*)(GB + r * ldg + col0 + bj * HALF);
;                     const float xa[8] = {bf_lo(ga.x) + a0[0], bf_hi(ga.x) + a0[1], bf_lo(ga.y) + a0[2], bf_hi(ga.y) + a0[3], bf_lo(ga.z) + a1[0], bf_hi(ga.z) + a1[1], bf_lo(ga.w) + a1[2], bf_hi(ga.w) + a1[3]};
;                     const float xb[8] = {bf_lo(gb.x) + b0[0], bf_hi(gb.x) + b0[1], bf_lo(gb.y) + b0[2], bf_hi(gb.y) + b0[3], bf_lo(gb.z) + b1[0], bf_hi(gb.z) + b1[1], bf_lo(gb.w) + b1[2], bf_hi(gb.w) + b1[3]};
; #pragma unroll
;                     for (int j = 0; j < 4; ++j) { acc[ai][bj][m][0][j] *= (1.0f + __expf(-fmaxf(xb[j], GB_MIN))) * __builtin_amdgcn_rcpf(1.0f + __expf(-xa[j]));
;                         acc[ai][bj][m][1][j] *= (1.0f + __expf(-fmaxf(xb[4 + j], GB_MIN))) * __builtin_amdgcn_rcpf(1.0f + __expf(-xa[4 + j])); }
.LBB0_619:
	v_mov_b32_e32 v4, v156
	v_mov_b32_e32 v3, v154
	v_mov_b64_e32 v[182:183], s[10:11]
	v_ashrrev_i32_e32 v5, 31, v4
	v_mad_i64_i32 v[134:135], s[44:45], v3, s81, v[182:183]
	v_lshlrev_b64 v[180:181], 1, v[4:5]
	v_lshl_add_u64 v[188:189], v[134:135], 0, v[180:181]
	v_mov_b64_e32 v[192:193], s[12:13]
	global_load_dwordx4 v[160:163], v[188:189], off
	v_mad_i64_i32 v[134:135], s[44:45], v3, s81, v[192:193]
	v_lshlrev_b64 v[4:5], 2, v[4:5]
	v_lshl_add_u64 v[184:185], v[134:135], 0, v[180:181]
	v_lshl_add_u64 v[190:191], s[48:49], 0, v[4:5]
	global_load_dwordx4 v[164:167], v[184:185], off
	global_load_dwordx4 v[146:149], v[190:191], off
	global_load_dwordx4 v[142:145], v[190:191], off offset:16
	v_lshl_add_u64 v[186:187], s[16:17], 0, v[4:5]
	global_load_dwordx4 v[138:141], v[186:187], off
	global_load_dwordx4 v[134:137], v[186:187], off offset:16
	v_add_u32_e32 v155, 16, v3
	v_mad_i64_i32 v[4:5], s[44:45], v155, s81, v[182:183]
	v_mad_i64_i32 v[168:169], s[44:45], v155, s81, v[192:193]
	v_lshl_add_u64 v[158:159], v[4:5], 0, v[180:181]
	v_lshl_add_u64 v[4:5], v[168:169], 0, v[180:181]
	global_load_dwordx4 v[168:171], v[158:159], off
	global_load_dwordx4 v[172:175], v[4:5], off
	v_mov_b32_e32 v231, 0
	global_load_dword v232, v[188:189], off offset:256
	v_mov_b32_e32 v230, 0xa0000
	v_lshl_add_u64 v[228:229], v[188:189], 0, v[230:231]
	global_load_dword v232, v[228:229], off
	global_load_dword v232, v[228:229], off offset:256
	v_mov_b32_e32 v230, 0x140000
	v_lshl_add_u64 v[228:229], v[188:189], 0, v[230:231]
	global_load_dword v232, v[228:229], off
	global_load_dword v232, v[228:229], off offset:256
	v_mov_b32_e32 v230, 0x1e0000
	v_lshl_add_u64 v[228:229], v[188:189], 0, v[230:231]
	global_load_dword v232, v[228:229], off
	global_load_dword v232, v[228:229], off offset:256
	v_mov_b32_e32 v230, 0x500000
	v_lshl_add_u64 v[228:229], v[188:189], 0, v[230:231]
	global_load_dword v232, v[228:229], off
	global_load_dword v232, v[228:229], off offset:256
	v_mov_b32_e32 v230, 0x5a0000
	v_lshl_add_u64 v[228:229], v[188:189], 0, v[230:231]
	global_load_dword v232, v[228:229], off
	global_load_dword v232, v[228:229], off offset:256
	v_mov_b32_e32 v230, 0x640000
	v_lshl_add_u64 v[228:229], v[188:189], 0, v[230:231]
	global_load_dword v232, v[228:229], off
	global_load_dword v232, v[228:229], off offset:256
	v_mov_b32_e32 v230, 0x6e0000
	v_lshl_add_u64 v[228:229], v[188:189], 0, v[230:231]
	global_load_dword v232, v[228:229], off
	global_load_dword v232, v[228:229], off offset:256
	v_mov_b32_e32 v231, 0
	global_load_dword v232, v[184:185], off offset:256
	v_mov_b32_e32 v230, 0xa0000
	v_lshl_add_u64 v[228:229], v[184:185], 0, v[230:231]
	global_load_dword v232, v[228:229], off
	global_load_dword v232, v[228:229], off offset:256
	v_mov_b32_e32 v230, 0x140000
	v_lshl_add_u64 v[228:229], v[184:185], 0, v[230:231]
	global_load_dword v232, v[228:229], off
	global_load_dword v232, v[228:229], off offset:256
	v_mov_b32_e32 v230, 0x1e0000
	v_lshl_add_u64 v[228:229], v[184:185], 0, v[230:231]
	global_load_dword v232, v[228:229], off
	global_load_dword v232, v[228:229], off offset:256
	v_mov_b32_e32 v230, 0x500000
	v_lshl_add_u64 v[228:229], v[184:185], 0, v[230:231]
	global_load_dword v232, v[228:229], off
	global_load_dword v232, v[228:229], off offset:256
	v_mov_b32_e32 v230, 0x5a0000
	v_lshl_add_u64 v[228:229], v[184:185], 0, v[230:231]
	global_load_dword v232, v[228:229], off
	global_load_dword v232, v[228:229], off offset:256
	v_mov_b32_e32 v230, 0x640000
	v_lshl_add_u64 v[228:229], v[184:185], 0, v[230:231]
	global_load_dword v232, v[228:229], off
	global_load_dword v232, v[228:229], off offset:256
	v_mov_b32_e32 v230, 0x6e0000
	v_lshl_add_u64 v[228:229], v[184:185], 0, v[230:231]
	global_load_dword v232, v[228:229], off
	global_load_dword v232, v[228:229], off offset:256
	s_waitcnt vmcnt(37)
	v_lshlrev_b32_e32 v155, 16, v160
	v_and_b32_e32 v157, 0xffff0000, v160
	v_lshlrev_b32_e32 v160, 16, v161
	v_and_b32_e32 v161, 0xffff0000, v161
	v_lshlrev_b32_e32 v176, 16, v162
	v_and_b32_e32 v162, 0xffff0000, v162
	s_waitcnt vmcnt(35)
	v_add_f32_e32 v155, v146, v155
	v_mul_f32_e32 v155, 0xbfb8aa3b, v155
	v_exp_f32_e32 v155, v155
	v_lshlrev_b32_e32 v177, 16, v163
	v_and_b32_e32 v163, 0xffff0000, v163
	v_lshlrev_b32_e32 v178, 16, v164
	v_and_b32_e32 v164, 0xffff0000, v164
	v_lshlrev_b32_e32 v201, 16, v166
	v_and_b32_e32 v166, 0xffff0000, v166
	v_add_f32_e32 v157, v147, v157
	v_add_f32_e32 v160, v148, v160
	v_add_f32_e32 v203, v149, v161
	s_waitcnt vmcnt(34)
	v_add_f32_e32 v161, v142, v176
	v_lshlrev_b32_e32 v202, 16, v167
	v_and_b32_e32 v167, 0xffff0000, v167
	v_add_f32_e32 v162, v143, v162
	v_add_f32_e32 v205, v145, v163
	s_waitcnt vmcnt(33)
	v_add_f32_e32 v163, v138, v178
	v_add_f32_e32 v164, v139, v164
	s_waitcnt vmcnt(32)
; __device__ __forceinline__ float bf_lo(unsigned w) { return __uint_as_float(w << 16); }
; __device__ __forceinline__ float bf_hi(unsigned w) { return __uint_as_float(w & 0xffff0000u); }
;     __device__ __forceinline__ void mid(f32x4 (&acc)[2][2][4][2], const Unit& u, int wr, int wc, int fr, int fq) const {
;     ...
;                 for (int m = 0; m < 4; ++m) { const size_t r = (size_t)(row0 + ai * HALF + m * 16);
;                     const u32x4 ga = *(const u32x4*)(GA + r * ldg + col0 + bj * HALF), gb = *(const u32x4*)(GB + r * ldg + col0 + bj * HALF);
;                     const float xa[8] = {bf_lo(ga.x) + a0[0], bf_hi(ga.x) + a0[1], bf_lo(ga.y) + a0[2], bf_hi(ga.y) + a0[3], bf_lo(ga.z) + a1[0], bf_hi(ga.z) + a1[1], bf_lo(ga.w) + a1[2], bf_hi(ga.w) + a1[3]};
;                     const float xb[8] = {bf_lo(gb.x) + b0[0], bf_hi(gb.x) + b0[1], bf_lo(gb.y) + b0[2], bf_hi(gb.y) + b0[3], bf_lo(gb.z) + b1[0], bf_hi(gb.z) + b1[1], bf_lo(gb.w) + b1[2], bf_hi(gb.w) + b1[3]};
; #pragma unroll
;                     for (int j = 0; j < 4; ++j) { acc[ai][bj][m][0][j] *= (1.0f + __expf(-fmaxf(xb[j], GB_MIN))) * __builtin_amdgcn_rcpf(1.0f + __expf(-xa[j]));
;                         acc[ai][bj][m][1][j] *= (1.0f + __expf(-fmaxf(xb[4 + j], GB_MIN))) * __builtin_amdgcn_rcpf(1.0f + __expf(-xa[4 + j])); }
	v_add_f32_e32 v166, v135, v166
	v_mul_f32_e32 v161, 0xbfb8aa3b, v161
	v_mul_f32_e32 v157, 0xbfb8aa3b, v157
	v_mul_f32_e32 v160, 0xbfb8aa3b, v160
	v_lshlrev_b32_e32 v179, 16, v165
	v_and_b32_e32 v165, 0xffff0000, v165
	v_add_f32_e32 v206, v137, v167
	v_max_f32_e32 v163, 0xc2700000, v163
	v_max_f32_e32 v164, 0xc2700000, v164
	v_max_f32_e32 v166, 0xc2700000, v166
	v_mul_f32_e32 v162, 0xbfb8aa3b, v162
	v_exp_f32_e32 v167, v161
	v_exp_f32_e32 v157, v157
	v_exp_f32_e32 v178, v160
	v_add_f32_e32 v176, v140, v179
	v_add_f32_e32 v179, v141, v165
	v_add_f32_e32 v165, v134, v201
	v_mul_f32_e32 v163, 0xbfb8aa3b, v163
	v_mul_f32_e32 v161, 0xbfb8aa3b, v164
	v_mul_f32_e32 v164, 0xbfb8aa3b, v166
	v_exp_f32_e32 v166, v162
	v_add_f32_e32 v155, 1.0, v155
	v_max_f32_e32 v165, 0xc2700000, v165
	v_exp_f32_e32 v160, v163
	v_exp_f32_e32 v163, v164
	v_rcp_f32_e32 v164, v155
	v_max_f32_e32 v155, 0xc2700000, v176
	v_mul_f32_e32 v165, 0xbfb8aa3b, v165
	v_mul_f32_e32 v155, 0xbfb8aa3b, v155
	v_add_f32_e32 v177, v144, v177
	v_add_f32_e32 v201, v136, v202
	v_exp_f32_e32 v162, v165
	v_add_f32_e32 v165, 1.0, v167
	v_add_f32_e32 v157, 1.0, v157
	v_exp_f32_e32 v176, v155
	v_add_f32_e32 v155, 1.0, v178
	v_add_f32_e32 v167, 1.0, v166
	v_rcp_f32_e32 v166, v165
	v_rcp_f32_e32 v165, v157
	v_rcp_f32_e32 v178, v155
	v_mul_f32_e32 v155, 0xbfb8aa3b, v177
	v_max_f32_e32 v157, 0xc2700000, v201
	v_exp_f32_e32 v155, v155
	v_mul_f32_e32 v157, 0xbfb8aa3b, v157
	v_mul_f32_e32 v177, 0xbfb8aa3b, v203
	v_exp_f32_e32 v202, v157
	v_max_f32_e32 v157, 0xc2700000, v179
	v_exp_f32_e32 v179, v177
	v_mul_f32_e32 v157, 0xbfb8aa3b, v157
	v_exp_f32_e32 v177, v157
	v_mul_f32_e32 v157, 0xbfb8aa3b, v205
	v_add_f32_e32 v155, 1.0, v155
	v_exp_f32_e32 v157, v157
	v_rcp_f32_e32 v204, v155
	v_add_f32_e32 v155, 1.0, v179
	v_exp_f32_e32 v161, v161
	v_rcp_f32_e32 v179, v155
	v_max_f32_e32 v155, 0xc2700000, v206
	v_mul_f32_e32 v155, 0xbfb8aa3b, v155
	v_exp_f32_e32 v203, v155
	v_add_f32_e32 v155, 1.0, v157
	v_rcp_f32_e32 v205, v155
	v_pk_add_f32 v[160:161], v[160:161], 1.0 op_sel_hi:[1,0]
	v_pk_add_f32 v[176:177], v[176:177], 1.0 op_sel_hi:[1,0]
	v_pk_mul_f32 v[160:161], v[164:165], v[160:161]
	v_pk_mul_f32 v[164:165], v[178:179], v[176:177]
	v_pk_mul_f32 v[130:131], v[130:131], v[160:161]
	v_pk_add_f32 v[160:161], v[202:203], 1.0 op_sel_hi:[1,0]
	v_rcp_f32_e32 v167, v167
	v_pk_mul_f32 v[160:161], v[204:205], v[160:161]
	s_waitcnt vmcnt(31)
	v_lshlrev_b32_e32 v155, 16, v168
	v_pk_mul_f32 v[128:129], v[128:129], v[160:161]
	v_lshlrev_b32_e32 v160, 16, v169
	v_add_f32_e32 v201, v148, v160
	v_and_b32_e32 v160, 0xffff0000, v169
	v_add_f32_e32 v203, v149, v160
	v_lshlrev_b32_e32 v160, 16, v170
	v_add_f32_e32 v176, v142, v160
	v_and_b32_e32 v160, 0xffff0000, v170
	v_add_f32_e32 v177, v143, v160
	v_lshlrev_b32_e32 v160, 16, v171
	v_add_f32_e32 v205, v144, v160
	v_and_b32_e32 v160, 0xffff0000, v171
	v_add_f32_e32 v207, v145, v160
	s_waitcnt vmcnt(30)
	v_lshlrev_b32_e32 v160, 16, v172
	v_and_b32_e32 v157, 0xffff0000, v168
	v_add_f32_e32 v168, v138, v160
	v_and_b32_e32 v160, 0xffff0000, v172
	v_add_f32_e32 v179, v139, v160
	v_lshlrev_b32_e32 v160, 16, v173
	v_pk_add_f32 v[162:163], v[162:163], 1.0 op_sel_hi:[1,0]
	v_add_f32_e32 v202, v140, v160
	v_and_b32_e32 v160, 0xffff0000, v173
	v_add_u32_e32 v170, 32, v3
	v_pk_mul_f32 v[162:163], v[166:167], v[162:163]
	v_add_f32_e32 v208, v141, v160
	v_mad_i64_i32 v[160:161], s[44:45], v170, s81, v[182:183]
	v_pk_mul_f32 v[126:127], v[126:127], v[162:163]
	v_lshl_add_u64 v[162:163], v[160:161], 0, v[180:181]
	v_and_b32_e32 v160, 0xffff0000, v174
	v_pk_mul_f32 v[132:133], v[132:133], v[164:165]
	global_load_dwordx4 v[164:167], v[162:163], off
	v_add_f32_e32 v204, v135, v160
	v_lshlrev_b32_e32 v160, 16, v175
	v_add_f32_e32 v206, v136, v160
	v_and_b32_e32 v160, 0xffff0000, v175
	v_add_f32_e32 v209, v137, v160
	v_max_f32_e32 v160, 0xc2700000, v168
	v_mul_f32_e32 v160, 0xbfb8aa3b, v160
	v_exp_f32_e32 v172, v160
	v_mad_i64_i32 v[160:161], s[44:45], v170, s81, v[192:193]
	v_lshlrev_b32_e32 v169, 16, v174
	v_lshl_add_u64 v[160:161], v[160:161], 0, v[180:181]
	v_add_f32_e32 v173, v134, v169
	global_load_dwordx4 v[168:171], v[160:161], off
	v_add_f32_e32 v155, v146, v155
	v_mul_f32_e32 v155, 0xbfb8aa3b, v155
	v_exp_f32_e32 v155, v155
	v_add_f32_e32 v157, v147, v157
	v_max_f32_e32 v173, 0xc2700000, v173
	v_mul_f32_e32 v173, 0xbfb8aa3b, v173
	v_add_f32_e32 v155, 1.0, v155
	v_rcp_f32_e32 v174, v155
	v_mul_f32_e32 v155, 0xbfb8aa3b, v176
	v_exp_f32_e32 v155, v155
	v_exp_f32_e32 v176, v173
	v_add_f32_e32 v155, 1.0, v155
	v_rcp_f32_e32 v178, v155
	v_mul_f32_e32 v155, 0xbfb8aa3b, v157
	v_exp_f32_e32 v155, v155
	v_max_f32_e32 v157, 0xc2700000, v179
	v_mul_f32_e32 v157, 0xbfb8aa3b, v157
	v_exp_f32_e32 v173, v157
	v_add_f32_e32 v155, 1.0, v155
	v_rcp_f32_e32 v175, v155
	v_mul_f32_e32 v155, 0xbfb8aa3b, v177
	v_exp_f32_e32 v155, v155
	v_max_f32_e32 v157, 0xc2700000, v204
	v_mul_f32_e32 v157, 0xbfb8aa3b, v157
	v_exp_f32_e32 v177, v157
	v_add_f32_e32 v155, 1.0, v155
	v_rcp_f32_e32 v179, v155
	v_mul_f32_e32 v155, 0xbfb8aa3b, v201
	v_exp_f32_e32 v155, v155
	v_max_f32_e32 v157, 0xc2700000, v202
	v_mul_f32_e32 v157, 0xbfb8aa3b, v157
	v_exp_f32_e32 v202, v157
	v_add_f32_e32 v155, 1.0, v155
	v_rcp_f32_e32 v204, v155
	v_mul_f32_e32 v155, 0xbfb8aa3b, v205
	v_exp_f32_e32 v155, v155
	v_max_f32_e32 v157, 0xc2700000, v206
	v_mul_f32_e32 v201, 0xbfb8aa3b, v203
	v_mul_f32_e32 v157, 0xbfb8aa3b, v157
	v_exp_f32_e32 v201, v201
	v_exp_f32_e32 v206, v157
	v_max_f32_e32 v157, 0xc2700000, v208
	v_mul_f32_e32 v157, 0xbfb8aa3b, v157
	v_add_f32_e32 v155, 1.0, v155
	v_exp_f32_e32 v203, v157
	v_mul_f32_e32 v157, 0xbfb8aa3b, v207
	v_rcp_f32_e32 v208, v155
	v_add_f32_e32 v155, 1.0, v201
	v_exp_f32_e32 v157, v157
	v_rcp_f32_e32 v205, v155
	v_max_f32_e32 v155, 0xc2700000, v209
	v_mul_f32_e32 v155, 0xbfb8aa3b, v155
	v_exp_f32_e32 v207, v155
	v_add_f32_e32 v155, 1.0, v157
	v_pk_add_f32 v[172:173], v[172:173], 1.0 op_sel_hi:[1,0]
	v_rcp_f32_e32 v209, v155
	v_pk_mul_f32 v[172:173], v[174:175], v[172:173]
	v_pk_add_f32 v[202:203], v[202:203], 1.0 op_sel_hi:[1,0]
	v_pk_mul_f32 v[122:123], v[122:123], v[172:173]
	v_pk_add_f32 v[172:173], v[206:207], 1.0 op_sel_hi:[1,0]
	v_pk_mul_f32 v[174:175], v[204:205], v[202:203]
	v_pk_mul_f32 v[172:173], v[208:209], v[172:173]
	v_pk_mul_f32 v[124:125], v[124:125], v[174:175]
	s_waitcnt vmcnt(1)
; __device__ __forceinline__ float bf_lo(unsigned w) { return __uint_as_float(w << 16); }
; __device__ __forceinline__ float bf_hi(unsigned w) { return __uint_as_float(w & 0xffff0000u); }
;     __device__ __forceinline__ void mid(f32x4 (&acc)[2][2][4][2], const Unit& u, int wr, int wc, int fr, int fq) const {
;     ...
;                 for (int m = 0; m < 4; ++m) { const size_t r = (size_t)(row0 + ai * HALF + m * 16);
;                     const u32x4 ga = *(const u32x4*)(GA + r * ldg + col0 + bj * HALF), gb = *(const u32x4*)(GB + r * ldg + col0 + bj * HALF);
;                     const float xa[8] = {bf_lo(ga.x) + a0[0], bf_hi(ga.x) + a0[1], bf_lo(ga.y) + a0[2], bf_hi(ga.y) + a0[3], bf_lo(ga.z) + a1[0], bf_hi(ga.z) + a1[1], bf_lo(ga.w) + a1[2], bf_hi(ga.w) + a1[3]};
;                     const float xb[8] = {bf_lo(gb.x) + b0[0], bf_hi(gb.x) + b0[1], bf_lo(gb.y) + b0[2], bf_hi(gb.y) + b0[3], bf_lo(gb.z) + b1[0], bf_hi(gb.z) + b1[1], bf_lo(gb.w) + b1[2], bf_hi(gb.w) + b1[3]};
; #pragma unroll
;                     for (int j = 0; j < 4; ++j) { acc[ai][bj][m][0][j] *= (1.0f + __expf(-fmaxf(xb[j], GB_MIN))) * __builtin_amdgcn_rcpf(1.0f + __expf(-xa[j]));
;                         acc[ai][bj][m][1][j] *= (1.0f + __expf(-fmaxf(xb[4 + j], GB_MIN))) * __builtin_amdgcn_rcpf(1.0f + __expf(-xa[4 + j])); }
;                     asm volatile("" ::: "memory"); } }
	v_lshlrev_b32_e32 v155, 16, v164
	v_and_b32_e32 v157, 0xffff0000, v164
	v_lshlrev_b32_e32 v164, 16, v165
	v_add_f32_e32 v201, v148, v164
	v_and_b32_e32 v164, 0xffff0000, v165
	v_add_f32_e32 v207, v149, v164
	v_lshlrev_b32_e32 v164, 16, v166
	v_add_f32_e32 v202, v142, v164
	v_and_b32_e32 v164, 0xffff0000, v166
	v_add_f32_e32 v203, v143, v164
	v_lshlrev_b32_e32 v164, 16, v167
	v_add_f32_e32 v209, v144, v164
	v_and_b32_e32 v164, 0xffff0000, v167
	v_add_f32_e32 v211, v145, v164
	s_waitcnt vmcnt(0)
	v_lshlrev_b32_e32 v164, 16, v168
	v_pk_add_f32 v[174:175], v[176:177], 1.0 op_sel_hi:[1,0]
	v_add_f32_e32 v176, v138, v164
	v_and_b32_e32 v164, 0xffff0000, v168
	v_add_f32_e32 v205, v139, v164
	v_lshlrev_b32_e32 v164, 16, v169
	v_add_f32_e32 v206, v140, v164
	v_and_b32_e32 v164, 0xffff0000, v169
	v_add_u32_e32 v169, 48, v3
	v_add_f32_e32 v212, v141, v164
	v_mad_i64_i32 v[164:165], s[44:45], v169, s81, v[182:183]
	v_pk_mul_f32 v[174:175], v[178:179], v[174:175]
	v_lshl_add_u64 v[166:167], v[164:165], 0, v[180:181]
	v_and_b32_e32 v164, 0xffff0000, v170
	v_pk_mul_f32 v[120:121], v[120:121], v[172:173]
	v_pk_mul_f32 v[118:119], v[118:119], v[174:175]
	global_load_dwordx4 v[172:175], v[166:167], off
	v_add_f32_e32 v208, v135, v164
	v_lshlrev_b32_e32 v164, 16, v171
	v_add_f32_e32 v210, v136, v164
	v_and_b32_e32 v164, 0xffff0000, v171
	v_add_f32_e32 v213, v137, v164
	v_max_f32_e32 v164, 0xc2700000, v176
	v_lshlrev_b32_e32 v168, 16, v170
	v_mul_f32_e32 v164, 0xbfb8aa3b, v164
	v_add_f32_e32 v204, v134, v168
	v_exp_f32_e32 v168, v164
	v_mad_i64_i32 v[164:165], s[44:45], v169, s81, v[192:193]
	v_lshl_add_u64 v[164:165], v[164:165], 0, v[180:181]
	global_load_dwordx4 v[176:179], v[164:165], off
	v_add_f32_e32 v155, v146, v155
	v_mul_f32_e32 v155, 0xbfb8aa3b, v155
	v_exp_f32_e32 v155, v155
	v_add_f32_e32 v157, v147, v157
	v_max_f32_e32 v169, 0xc2700000, v204
	v_mul_f32_e32 v169, 0xbfb8aa3b, v169
	v_add_f32_e32 v155, 1.0, v155
	v_rcp_f32_e32 v170, v155
	v_mul_f32_e32 v155, 0xbfb8aa3b, v202
	v_exp_f32_e32 v155, v155
	v_exp_f32_e32 v202, v169
	v_add_f32_e32 v155, 1.0, v155
	v_rcp_f32_e32 v204, v155
	v_mul_f32_e32 v155, 0xbfb8aa3b, v157
	v_exp_f32_e32 v155, v155
	v_max_f32_e32 v157, 0xc2700000, v205
	v_mul_f32_e32 v157, 0xbfb8aa3b, v157
	v_exp_f32_e32 v169, v157
	v_add_f32_e32 v155, 1.0, v155
	v_rcp_f32_e32 v171, v155
	v_mul_f32_e32 v155, 0xbfb8aa3b, v203
	v_exp_f32_e32 v155, v155
	v_max_f32_e32 v157, 0xc2700000, v208
	v_mul_f32_e32 v157, 0xbfb8aa3b, v157
	v_exp_f32_e32 v203, v157
	v_add_f32_e32 v155, 1.0, v155
	v_rcp_f32_e32 v205, v155
	v_mul_f32_e32 v155, 0xbfb8aa3b, v201
	v_exp_f32_e32 v155, v155
	v_max_f32_e32 v157, 0xc2700000, v206
	v_mul_f32_e32 v157, 0xbfb8aa3b, v157
	v_exp_f32_e32 v206, v157
	v_add_f32_e32 v155, 1.0, v155
	v_rcp_f32_e32 v208, v155
	v_mul_f32_e32 v155, 0xbfb8aa3b, v209
	v_max_f32_e32 v157, 0xc2700000, v210
	v_exp_f32_e32 v155, v155
	v_mul_f32_e32 v157, 0xbfb8aa3b, v157
	v_mul_f32_e32 v201, 0xbfb8aa3b, v207
	v_exp_f32_e32 v210, v157
	v_max_f32_e32 v157, 0xc2700000, v212
	v_exp_f32_e32 v201, v201
	v_mul_f32_e32 v157, 0xbfb8aa3b, v157
	v_exp_f32_e32 v207, v157
	v_mul_f32_e32 v157, 0xbfb8aa3b, v211
	v_add_f32_e32 v155, 1.0, v155
	v_exp_f32_e32 v157, v157
	v_rcp_f32_e32 v212, v155
	v_add_f32_e32 v155, 1.0, v201
	v_rcp_f32_e32 v209, v155
	v_max_f32_e32 v155, 0xc2700000, v213
	v_mul_f32_e32 v155, 0xbfb8aa3b, v155
	v_exp_f32_e32 v211, v155
	v_add_f32_e32 v155, 1.0, v157
	v_rcp_f32_e32 v213, v155
	v_pk_add_f32 v[168:169], v[168:169], 1.0 op_sel_hi:[1,0]
	v_pk_add_f32 v[206:207], v[206:207], 1.0 op_sel_hi:[1,0]
	v_pk_mul_f32 v[168:169], v[170:171], v[168:169]
	v_pk_mul_f32 v[170:171], v[208:209], v[206:207]
	v_pk_mul_f32 v[114:115], v[114:115], v[168:169]
	v_pk_add_f32 v[168:169], v[210:211], 1.0 op_sel_hi:[1,0]
	v_pk_mul_f32 v[116:117], v[116:117], v[170:171]
	v_pk_mul_f32 v[168:169], v[212:213], v[168:169]
	v_pk_add_f32 v[170:171], v[202:203], 1.0 op_sel_hi:[1,0]
	v_pk_mul_f32 v[112:113], v[112:113], v[168:169]
	s_waitcnt vmcnt(1)
	v_lshlrev_b32_e32 v168, 16, v173
	v_add_f32_e32 v201, v148, v168
	v_and_b32_e32 v168, 0xffff0000, v173
	v_add_f32_e32 v211, v149, v168
	v_lshlrev_b32_e32 v168, 16, v174
	v_add_f32_e32 v203, v142, v168
	v_and_b32_e32 v168, 0xffff0000, v174
	v_add_f32_e32 v207, v143, v168
	v_lshlrev_b32_e32 v168, 16, v175
	v_add_f32_e32 v213, v144, v168
	v_and_b32_e32 v168, 0xffff0000, v175
	v_add_f32_e32 v215, v145, v168
	s_waitcnt vmcnt(0)
; __device__ __forceinline__ float bf_lo(unsigned w) { return __uint_as_float(w << 16); }
; __device__ __forceinline__ float bf_hi(unsigned w) { return __uint_as_float(w & 0xffff0000u); }
;     __device__ __forceinline__ void mid(f32x4 (&acc)[2][2][4][2], const Unit& u, int wr, int wc, int fr, int fq) const {
;     ...
;                 for (int m = 0; m < 4; ++m) { const size_t r = (size_t)(row0 + ai * HALF + m * 16);
;                     const u32x4 ga = *(const u32x4*)(GA + r * ldg + col0 + bj * HALF), gb = *(const u32x4*)(GB + r * ldg + col0 + bj * HALF);
;                     const float xa[8] = {bf_lo(ga.x) + a0[0], bf_hi(ga.x) + a0[1], bf_lo(ga.y) + a0[2], bf_hi(ga.y) + a0[3], bf_lo(ga.z) + a1[0], bf_hi(ga.z) + a1[1], bf_lo(ga.w) + a1[2], bf_hi(ga.w) + a1[3]};
;                     const float xb[8] = {bf_lo(gb.x) + b0[0], bf_hi(gb.x) + b0[1], bf_lo(gb.y) + b0[2], bf_hi(gb.y) + b0[3], bf_lo(gb.z) + b1[0], bf_hi(gb.z) + b1[1], bf_lo(gb.w) + b1[2], bf_hi(gb.w) + b1[3]};
; #pragma unroll
;                     for (int j = 0; j < 4; ++j) { acc[ai][bj][m][0][j] *= (1.0f + __expf(-fmaxf(xb[j], GB_MIN))) * __builtin_amdgcn_rcpf(1.0f + __expf(-xa[j]));
;                         acc[ai][bj][m][1][j] *= (1.0f + __expf(-fmaxf(xb[4 + j], GB_MIN))) * __builtin_amdgcn_rcpf(1.0f + __expf(-xa[4 + j])); }
;                     asm volatile("" ::: "memory"); } }
	v_lshlrev_b32_e32 v168, 16, v176
	v_add_f32_e32 v202, v138, v168
	v_and_b32_e32 v168, 0xffff0000, v176
	v_pk_mul_f32 v[170:171], v[204:205], v[170:171]
	v_add_f32_e32 v205, v139, v168
	v_lshlrev_b32_e32 v168, 16, v177
	v_add_f32_e32 v210, v140, v168
	v_and_b32_e32 v168, 0xffff0000, v177
	v_add_u32_e32 v177, 0x80, v3
	v_add_f32_e32 v216, v141, v168
	v_mad_i64_i32 v[168:169], s[44:45], v177, s81, v[182:183]
	v_pk_mul_f32 v[110:111], v[110:111], v[170:171]
	v_lshl_add_u64 v[170:171], v[168:169], 0, v[180:181]
	v_and_b32_e32 v168, 0xffff0000, v178
	v_lshlrev_b32_e32 v155, 16, v172
	v_and_b32_e32 v157, 0xffff0000, v172
	global_load_dwordx4 v[172:175], v[170:171], off
	v_add_f32_e32 v209, v135, v168
	v_lshlrev_b32_e32 v168, 16, v179
	v_add_f32_e32 v214, v136, v168
	v_and_b32_e32 v168, 0xffff0000, v179
	v_add_f32_e32 v217, v137, v168
	v_max_f32_e32 v168, 0xc2700000, v202
	v_mul_f32_e32 v168, 0xbfb8aa3b, v168
	v_exp_f32_e32 v202, v168
	v_mad_i64_i32 v[168:169], s[44:45], v177, s81, v[192:193]
	v_lshlrev_b32_e32 v176, 16, v178
	v_lshl_add_u64 v[168:169], v[168:169], 0, v[180:181]
	v_add_f32_e32 v206, v134, v176
	global_load_dwordx4 v[176:179], v[168:169], off
	v_add_f32_e32 v155, v146, v155
	v_mul_f32_e32 v155, 0xbfb8aa3b, v155
	v_exp_f32_e32 v155, v155
	v_add_f32_e32 v157, v147, v157
	v_add_f32_e32 v155, 1.0, v155
	v_rcp_f32_e32 v204, v155
	v_mul_f32_e32 v155, 0xbfb8aa3b, v203
	v_exp_f32_e32 v155, v155
	v_max_f32_e32 v203, 0xc2700000, v206
	v_mul_f32_e32 v203, 0xbfb8aa3b, v203
	v_exp_f32_e32 v206, v203
	v_add_f32_e32 v155, 1.0, v155
	v_rcp_f32_e32 v208, v155
	v_mul_f32_e32 v155, 0xbfb8aa3b, v157
	v_exp_f32_e32 v155, v155
	v_max_f32_e32 v157, 0xc2700000, v205
	v_mul_f32_e32 v157, 0xbfb8aa3b, v157
	v_exp_f32_e32 v203, v157
	v_add_f32_e32 v155, 1.0, v155
	v_rcp_f32_e32 v205, v155
	v_mul_f32_e32 v155, 0xbfb8aa3b, v207
	v_exp_f32_e32 v155, v155
	v_max_f32_e32 v157, 0xc2700000, v209
	v_mul_f32_e32 v157, 0xbfb8aa3b, v157
	v_exp_f32_e32 v207, v157
	v_add_f32_e32 v155, 1.0, v155
	v_rcp_f32_e32 v209, v155
	v_mul_f32_e32 v155, 0xbfb8aa3b, v201
	v_exp_f32_e32 v155, v155
	v_max_f32_e32 v157, 0xc2700000, v210
	v_mul_f32_e32 v157, 0xbfb8aa3b, v157
	v_exp_f32_e32 v210, v157
	v_add_f32_e32 v155, 1.0, v155
	v_rcp_f32_e32 v212, v155
	v_mul_f32_e32 v155, 0xbfb8aa3b, v213
	v_exp_f32_e32 v155, v155
	v_max_f32_e32 v157, 0xc2700000, v214
	v_mul_f32_e32 v201, 0xbfb8aa3b, v211
	v_mul_f32_e32 v157, 0xbfb8aa3b, v157
	v_exp_f32_e32 v201, v201
	v_exp_f32_e32 v214, v157
	v_max_f32_e32 v157, 0xc2700000, v216
	v_mul_f32_e32 v157, 0xbfb8aa3b, v157
	v_add_f32_e32 v155, 1.0, v155
	v_exp_f32_e32 v211, v157
	v_mul_f32_e32 v157, 0xbfb8aa3b, v215
	v_rcp_f32_e32 v216, v155
	v_add_f32_e32 v155, 1.0, v201
	v_exp_f32_e32 v157, v157
	v_rcp_f32_e32 v213, v155
	v_max_f32_e32 v155, 0xc2700000, v217
	v_mul_f32_e32 v155, 0xbfb8aa3b, v155
	v_exp_f32_e32 v215, v155
	v_add_f32_e32 v155, 1.0, v157
	v_pk_add_f32 v[202:203], v[202:203], 1.0 op_sel_hi:[1,0]
	v_rcp_f32_e32 v217, v155
	v_pk_mul_f32 v[202:203], v[204:205], v[202:203]
	v_pk_add_f32 v[210:211], v[210:211], 1.0 op_sel_hi:[1,0]
	v_pk_mul_f32 v[106:107], v[106:107], v[202:203]
	v_pk_add_f32 v[202:203], v[214:215], 1.0 op_sel_hi:[1,0]
	v_pk_mul_f32 v[204:205], v[212:213], v[210:211]
	v_pk_mul_f32 v[202:203], v[216:217], v[202:203]
	v_pk_mul_f32 v[108:109], v[108:109], v[204:205]
	s_waitcnt vmcnt(1)
	v_lshlrev_b32_e32 v155, 16, v172
	v_and_b32_e32 v157, 0xffff0000, v172
	v_lshlrev_b32_e32 v172, 16, v173
	v_add_f32_e32 v201, v148, v172
	v_and_b32_e32 v172, 0xffff0000, v173
	v_add_f32_e32 v215, v149, v172
	v_lshlrev_b32_e32 v172, 16, v174
	v_add_f32_e32 v210, v142, v172
	v_and_b32_e32 v172, 0xffff0000, v174
	v_add_f32_e32 v211, v143, v172
	v_lshlrev_b32_e32 v172, 16, v175
	v_add_f32_e32 v217, v144, v172
	v_and_b32_e32 v172, 0xffff0000, v175
	v_add_f32_e32 v219, v145, v172
	s_waitcnt vmcnt(0)
	v_lshlrev_b32_e32 v172, 16, v176
	v_pk_add_f32 v[204:205], v[206:207], 1.0 op_sel_hi:[1,0]
	v_add_f32_e32 v206, v138, v172
	v_and_b32_e32 v172, 0xffff0000, v176
	v_add_f32_e32 v213, v139, v172
	v_lshlrev_b32_e32 v172, 16, v177
	v_add_f32_e32 v214, v140, v172
	v_and_b32_e32 v172, 0xffff0000, v177
	v_add_u32_e32 v177, 0x90, v3
	v_add_f32_e32 v220, v141, v172
	v_mad_i64_i32 v[172:173], s[44:45], v177, s81, v[182:183]
	v_pk_mul_f32 v[204:205], v[208:209], v[204:205]
	v_lshl_add_u64 v[174:175], v[172:173], 0, v[180:181]
	v_and_b32_e32 v172, 0xffff0000, v178
	v_pk_mul_f32 v[104:105], v[104:105], v[202:203]
	v_pk_mul_f32 v[102:103], v[102:103], v[204:205]
	global_load_dwordx4 v[202:205], v[174:175], off
	v_add_f32_e32 v216, v135, v172
	v_lshlrev_b32_e32 v172, 16, v179
	v_add_f32_e32 v218, v136, v172
	v_and_b32_e32 v172, 0xffff0000, v179
	v_add_f32_e32 v221, v137, v172
	v_max_f32_e32 v172, 0xc2700000, v206
	v_lshlrev_b32_e32 v176, 16, v178
	v_mul_f32_e32 v172, 0xbfb8aa3b, v172
	v_add_f32_e32 v212, v134, v176
	v_exp_f32_e32 v176, v172
	v_mad_i64_i32 v[172:173], s[44:45], v177, s81, v[192:193]
	v_lshl_add_u64 v[172:173], v[172:173], 0, v[180:181]
	global_load_dwordx4 v[206:209], v[172:173], off
	v_add_f32_e32 v155, v146, v155
	v_mul_f32_e32 v155, 0xbfb8aa3b, v155
	v_exp_f32_e32 v155, v155
	v_add_f32_e32 v157, v147, v157
	v_max_f32_e32 v177, 0xc2700000, v212
	v_mul_f32_e32 v177, 0xbfb8aa3b, v177
	v_add_f32_e32 v155, 1.0, v155
	v_rcp_f32_e32 v178, v155
	v_mul_f32_e32 v155, 0xbfb8aa3b, v210
	v_exp_f32_e32 v155, v155
	v_exp_f32_e32 v210, v177
	v_add_f32_e32 v155, 1.0, v155
	v_rcp_f32_e32 v212, v155
	v_mul_f32_e32 v155, 0xbfb8aa3b, v157
	v_exp_f32_e32 v155, v155
	v_max_f32_e32 v157, 0xc2700000, v213
	v_mul_f32_e32 v157, 0xbfb8aa3b, v157
	v_exp_f32_e32 v177, v157
; __device__ __forceinline__ float bf_lo(unsigned w) { return __uint_as_float(w << 16); }
; __device__ __forceinline__ float bf_hi(unsigned w) { return __uint_as_float(w & 0xffff0000u); }
;     __device__ __forceinline__ void mid(f32x4 (&acc)[2][2][4][2], const Unit& u, int wr, int wc, int fr, int fq) const {
;     ...
;                 for (int m = 0; m < 4; ++m) { const size_t r = (size_t)(row0 + ai * HALF + m * 16);
;                     const u32x4 ga = *(const u32x4*)(GA + r * ldg + col0 + bj * HALF), gb = *(const u32x4*)(GB + r * ldg + col0 + bj * HALF);
;                     const float xa[8] = {bf_lo(ga.x) + a0[0], bf_hi(ga.x) + a0[1], bf_lo(ga.y) + a0[2], bf_hi(ga.y) + a0[3], bf_lo(ga.z) + a1[0], bf_hi(ga.z) + a1[1], bf_lo(ga.w) + a1[2], bf_hi(ga.w) + a1[3]};
;                     const float xb[8] = {bf_lo(gb.x) + b0[0], bf_hi(gb.x) + b0[1], bf_lo(gb.y) + b0[2], bf_hi(gb.y) + b0[3], bf_lo(gb.z) + b1[0], bf_hi(gb.z) + b1[1], bf_lo(gb.w) + b1[2], bf_hi(gb.w) + b1[3]};
; #pragma unroll
;                     for (int j = 0; j < 4; ++j) { acc[ai][bj][m][0][j] *= (1.0f + __expf(-fmaxf(xb[j], GB_MIN))) * __builtin_amdgcn_rcpf(1.0f + __expf(-xa[j]));
;                         acc[ai][bj][m][1][j] *= (1.0f + __expf(-fmaxf(xb[4 + j], GB_MIN))) * __builtin_amdgcn_rcpf(1.0f + __expf(-xa[4 + j])); }
;                     asm volatile("" ::: "memory"); } }
	v_add_f32_e32 v155, 1.0, v155
	v_rcp_f32_e32 v179, v155
	v_mul_f32_e32 v155, 0xbfb8aa3b, v211
	v_exp_f32_e32 v155, v155
	v_max_f32_e32 v157, 0xc2700000, v216
	v_mul_f32_e32 v157, 0xbfb8aa3b, v157
	v_exp_f32_e32 v211, v157
	v_add_f32_e32 v155, 1.0, v155
	v_rcp_f32_e32 v213, v155
	v_mul_f32_e32 v155, 0xbfb8aa3b, v201
	v_exp_f32_e32 v155, v155
	v_max_f32_e32 v157, 0xc2700000, v214
	v_mul_f32_e32 v157, 0xbfb8aa3b, v157
	v_exp_f32_e32 v214, v157
	v_add_f32_e32 v155, 1.0, v155
	v_rcp_f32_e32 v216, v155
	v_mul_f32_e32 v155, 0xbfb8aa3b, v217
	v_max_f32_e32 v157, 0xc2700000, v218
	v_exp_f32_e32 v155, v155
	v_mul_f32_e32 v157, 0xbfb8aa3b, v157
	v_mul_f32_e32 v201, 0xbfb8aa3b, v215
	v_exp_f32_e32 v218, v157
	v_max_f32_e32 v157, 0xc2700000, v220
	v_exp_f32_e32 v201, v201
	v_mul_f32_e32 v157, 0xbfb8aa3b, v157
	v_exp_f32_e32 v215, v157
	v_mul_f32_e32 v157, 0xbfb8aa3b, v219
	v_add_f32_e32 v155, 1.0, v155
	v_exp_f32_e32 v157, v157
	v_rcp_f32_e32 v220, v155
	v_add_f32_e32 v155, 1.0, v201
	v_rcp_f32_e32 v217, v155
	v_max_f32_e32 v155, 0xc2700000, v221
	v_mul_f32_e32 v155, 0xbfb8aa3b, v155
	v_exp_f32_e32 v219, v155
	v_add_f32_e32 v155, 1.0, v157
	v_rcp_f32_e32 v221, v155
	v_pk_add_f32 v[176:177], v[176:177], 1.0 op_sel_hi:[1,0]
	v_pk_add_f32 v[214:215], v[214:215], 1.0 op_sel_hi:[1,0]
	v_pk_mul_f32 v[176:177], v[178:179], v[176:177]
	v_pk_mul_f32 v[178:179], v[216:217], v[214:215]
	v_pk_mul_f32 v[98:99], v[98:99], v[176:177]
	v_pk_add_f32 v[176:177], v[218:219], 1.0 op_sel_hi:[1,0]
	v_pk_mul_f32 v[100:101], v[100:101], v[178:179]
	v_pk_mul_f32 v[176:177], v[220:221], v[176:177]
	v_pk_add_f32 v[178:179], v[210:211], 1.0 op_sel_hi:[1,0]
	v_pk_mul_f32 v[96:97], v[96:97], v[176:177]
	s_waitcnt vmcnt(1)
	v_lshlrev_b32_e32 v176, 16, v203
	v_add_f32_e32 v201, v148, v176
	v_and_b32_e32 v176, 0xffff0000, v203
	v_add_f32_e32 v219, v149, v176
	v_lshlrev_b32_e32 v176, 16, v204
	v_add_f32_e32 v211, v142, v176
	v_and_b32_e32 v176, 0xffff0000, v204
	v_add_f32_e32 v215, v143, v176
	v_lshlrev_b32_e32 v176, 16, v205
	v_add_f32_e32 v221, v144, v176
	v_and_b32_e32 v176, 0xffff0000, v205
	v_add_f32_e32 v223, v145, v176
	s_waitcnt vmcnt(0)
	v_lshlrev_b32_e32 v176, 16, v206
	v_add_f32_e32 v210, v138, v176
	v_and_b32_e32 v176, 0xffff0000, v206
	v_pk_mul_f32 v[178:179], v[212:213], v[178:179]
	v_add_f32_e32 v213, v139, v176
	v_lshlrev_b32_e32 v176, 16, v207
	v_add_f32_e32 v218, v140, v176
	v_and_b32_e32 v176, 0xffff0000, v207
	v_add_u32_e32 v207, 0xa0, v3
	v_add_f32_e32 v225, v141, v176
	v_mad_i64_i32 v[176:177], s[44:45], v207, s81, v[182:183]
	v_pk_mul_f32 v[94:95], v[94:95], v[178:179]
	v_lshl_add_u64 v[178:179], v[176:177], 0, v[180:181]
	v_and_b32_e32 v176, 0xffff0000, v208
	v_add_f32_e32 v217, v135, v176
	v_lshlrev_b32_e32 v176, 16, v209
	v_lshlrev_b32_e32 v155, 16, v202
	v_and_b32_e32 v157, 0xffff0000, v202
	global_load_dwordx4 v[202:205], v[178:179], off
	v_add_f32_e32 v222, v136, v176
	v_and_b32_e32 v176, 0xffff0000, v209
	v_add_f32_e32 v227, v137, v176
	v_max_f32_e32 v176, 0xc2700000, v210
	v_mul_f32_e32 v176, 0xbfb8aa3b, v176
	v_exp_f32_e32 v210, v176
	v_mad_i64_i32 v[176:177], s[44:45], v207, s81, v[192:193]
	v_lshlrev_b32_e32 v206, 16, v208
	v_lshl_add_u64 v[176:177], v[176:177], 0, v[180:181]
	v_add_f32_e32 v214, v134, v206
	global_load_dwordx4 v[206:209], v[176:177], off
	v_add_f32_e32 v155, v146, v155
	v_mul_f32_e32 v155, 0xbfb8aa3b, v155
	v_exp_f32_e32 v155, v155
	v_add_f32_e32 v157, v147, v157
	v_add_u32_e32 v3, 0xb0, v3
	v_mad_i64_i32 v[182:183], s[44:45], v3, s81, v[182:183]
	v_add_f32_e32 v155, 1.0, v155
	v_rcp_f32_e32 v212, v155
	v_mul_f32_e32 v155, 0xbfb8aa3b, v211
	v_exp_f32_e32 v155, v155
	v_max_f32_e32 v211, 0xc2700000, v214
	v_mul_f32_e32 v211, 0xbfb8aa3b, v211
	v_exp_f32_e32 v214, v211
	v_add_f32_e32 v155, 1.0, v155
	v_rcp_f32_e32 v216, v155
	v_mul_f32_e32 v155, 0xbfb8aa3b, v157
	v_exp_f32_e32 v155, v155
	v_max_f32_e32 v157, 0xc2700000, v213
	v_mul_f32_e32 v157, 0xbfb8aa3b, v157
	v_exp_f32_e32 v211, v157
	v_add_f32_e32 v155, 1.0, v155
	v_rcp_f32_e32 v213, v155
	v_mul_f32_e32 v155, 0xbfb8aa3b, v215
	v_exp_f32_e32 v155, v155
	v_max_f32_e32 v157, 0xc2700000, v217
	v_mul_f32_e32 v157, 0xbfb8aa3b, v157
	v_exp_f32_e32 v215, v157
	v_add_f32_e32 v155, 1.0, v155
	v_rcp_f32_e32 v217, v155
	v_mul_f32_e32 v155, 0xbfb8aa3b, v201
	v_exp_f32_e32 v155, v155
	v_max_f32_e32 v157, 0xc2700000, v218
	v_mul_f32_e32 v157, 0xbfb8aa3b, v157
	v_exp_f32_e32 v218, v157
	v_add_f32_e32 v155, 1.0, v155
	v_rcp_f32_e32 v220, v155
	v_mul_f32_e32 v155, 0xbfb8aa3b, v221
	v_max_f32_e32 v157, 0xc2700000, v222
	v_exp_f32_e32 v155, v155
	v_mul_f32_e32 v157, 0xbfb8aa3b, v157
	v_mul_f32_e32 v201, 0xbfb8aa3b, v219
	v_exp_f32_e32 v222, v157
	v_max_f32_e32 v157, 0xc2700000, v225
	v_exp_f32_e32 v201, v201
	v_mul_f32_e32 v157, 0xbfb8aa3b, v157
	v_exp_f32_e32 v219, v157
	v_mul_f32_e32 v157, 0xbfb8aa3b, v223
	v_add_f32_e32 v155, 1.0, v155
	v_exp_f32_e32 v157, v157
	v_rcp_f32_e32 v226, v155
	v_add_f32_e32 v155, 1.0, v201
	v_rcp_f32_e32 v221, v155
	v_max_f32_e32 v155, 0xc2700000, v227
	v_mul_f32_e32 v155, 0xbfb8aa3b, v155
	v_exp_f32_e32 v223, v155
	v_add_f32_e32 v155, 1.0, v157
	v_rcp_f32_e32 v227, v155
	v_pk_add_f32 v[218:219], v[218:219], 1.0 op_sel_hi:[1,0]
	v_pk_add_f32 v[210:211], v[210:211], 1.0 op_sel_hi:[1,0]
	v_lshl_add_u64 v[182:183], v[182:183], 0, v[180:181]
	v_pk_mul_f32 v[210:211], v[212:213], v[210:211]
	v_pk_mul_f32 v[212:213], v[220:221], v[218:219]
	v_pk_mul_f32 v[90:91], v[90:91], v[210:211]
	v_pk_mul_f32 v[92:93], v[92:93], v[212:213]
	v_pk_add_f32 v[210:211], v[222:223], 1.0 op_sel_hi:[1,0]
	v_pk_add_f32 v[212:213], v[214:215], 1.0 op_sel_hi:[1,0]
	s_waitcnt vmcnt(1)
; __device__ __forceinline__ float bf_lo(unsigned w) { return __uint_as_float(w << 16); }
; __device__ __forceinline__ float bf_hi(unsigned w) { return __uint_as_float(w & 0xffff0000u); }
;     __device__ __forceinline__ void mid(f32x4 (&acc)[2][2][4][2], const Unit& u, int wr, int wc, int fr, int fq) const {
;     ...
;                 for (int m = 0; m < 4; ++m) { const size_t r = (size_t)(row0 + ai * HALF + m * 16);
;                     const u32x4 ga = *(const u32x4*)(GA + r * ldg + col0 + bj * HALF), gb = *(const u32x4*)(GB + r * ldg + col0 + bj * HALF);
;                     const float xa[8] = {bf_lo(ga.x) + a0[0], bf_hi(ga.x) + a0[1], bf_lo(ga.y) + a0[2], bf_hi(ga.y) + a0[3], bf_lo(ga.z) + a1[0], bf_hi(ga.z) + a1[1], bf_lo(ga.w) + a1[2], bf_hi(ga.w) + a1[3]};
;                     const float xb[8] = {bf_lo(gb.x) + b0[0], bf_hi(gb.x) + b0[1], bf_lo(gb.y) + b0[2], bf_hi(gb.y) + b0[3], bf_lo(gb.z) + b1[0], bf_hi(gb.z) + b1[1], bf_lo(gb.w) + b1[2], bf_hi(gb.w) + b1[3]};
; #pragma unroll
;                     for (int j = 0; j < 4; ++j) { acc[ai][bj][m][0][j] *= (1.0f + __expf(-fmaxf(xb[j], GB_MIN))) * __builtin_amdgcn_rcpf(1.0f + __expf(-xa[j]));
;                         acc[ai][bj][m][1][j] *= (1.0f + __expf(-fmaxf(xb[4 + j], GB_MIN))) * __builtin_amdgcn_rcpf(1.0f + __expf(-xa[4 + j])); }
;                     asm volatile("" ::: "memory"); } }
	v_lshlrev_b32_e32 v155, 16, v202
	v_and_b32_e32 v157, 0xffff0000, v202
	v_and_b32_e32 v202, 0xffff0000, v203
	v_pk_mul_f32 v[212:213], v[216:217], v[212:213]
	v_pk_mul_f32 v[210:211], v[226:227], v[210:211]
	v_add_f32_e32 v217, v149, v202
	v_lshlrev_b32_e32 v202, 16, v204
	v_pk_mul_f32 v[88:89], v[88:89], v[210:211]
	v_add_f32_e32 v211, v142, v202
	v_and_b32_e32 v202, 0xffff0000, v204
	v_pk_mul_f32 v[86:87], v[86:87], v[212:213]
	v_add_f32_e32 v213, v143, v202
	v_lshlrev_b32_e32 v202, 16, v205
	v_add_f32_e32 v219, v144, v202
	v_and_b32_e32 v202, 0xffff0000, v205
	v_add_f32_e32 v221, v145, v202
	s_waitcnt vmcnt(0)
	v_lshlrev_b32_e32 v202, 16, v206
	v_add_f32_e32 v210, v138, v202
	v_and_b32_e32 v202, 0xffff0000, v206
	v_add_f32_e32 v215, v139, v202
	v_lshlrev_b32_e32 v202, 16, v207
	v_add_f32_e32 v216, v140, v202
	v_and_b32_e32 v202, 0xffff0000, v207
	v_lshlrev_b32_e32 v201, 16, v203
	v_add_f32_e32 v222, v141, v202
	global_load_dwordx4 v[202:205], v[182:183], off
	v_lshlrev_b32_e32 v206, 16, v208
	v_add_f32_e32 v212, v134, v206
	v_and_b32_e32 v206, 0xffff0000, v208
	v_add_f32_e32 v218, v135, v206
	v_lshlrev_b32_e32 v206, 16, v209
	v_add_f32_e32 v220, v136, v206
	v_and_b32_e32 v206, 0xffff0000, v209
	v_add_f32_e32 v223, v137, v206
	v_max_f32_e32 v206, 0xc2700000, v210
	v_mad_i64_i32 v[192:193], s[44:45], v3, s81, v[192:193]
	v_mul_f32_e32 v206, 0xbfb8aa3b, v206
	v_lshl_add_u64 v[180:181], v[192:193], 0, v[180:181]
	v_exp_f32_e32 v210, v206
	global_load_dwordx4 v[206:209], v[180:181], off
	v_add_f32_e32 v155, v146, v155
	v_mul_f32_e32 v155, 0xbfb8aa3b, v155
	v_exp_f32_e32 v155, v155
	v_add_f32_e32 v157, v147, v157
	v_add_f32_e32 v201, v148, v201
	v_add_f32_e32 v3, 1.0, v155
	v_rcp_f32_e32 v192, v3
	v_mul_f32_e32 v3, 0xbfb8aa3b, v211
	v_exp_f32_e32 v3, v3
	v_max_f32_e32 v155, 0xc2700000, v212
	v_mul_f32_e32 v155, 0xbfb8aa3b, v155
	v_exp_f32_e32 v212, v155
	v_add_f32_e32 v3, 1.0, v3
	v_rcp_f32_e32 v214, v3
	v_mul_f32_e32 v3, 0xbfb8aa3b, v157
	v_exp_f32_e32 v3, v3
	v_max_f32_e32 v155, 0xc2700000, v215
	v_mul_f32_e32 v155, 0xbfb8aa3b, v155
	v_exp_f32_e32 v211, v155
	v_add_f32_e32 v3, 1.0, v3
	v_rcp_f32_e32 v193, v3
	v_mul_f32_e32 v3, 0xbfb8aa3b, v213
	v_exp_f32_e32 v3, v3
	v_max_f32_e32 v155, 0xc2700000, v218
	v_mul_f32_e32 v155, 0xbfb8aa3b, v155
	v_exp_f32_e32 v213, v155
	v_add_f32_e32 v3, 1.0, v3
	v_rcp_f32_e32 v215, v3
	v_mul_f32_e32 v3, 0xbfb8aa3b, v201
	v_exp_f32_e32 v3, v3
	v_max_f32_e32 v155, 0xc2700000, v216
	v_mul_f32_e32 v155, 0xbfb8aa3b, v155
	v_exp_f32_e32 v216, v155
	v_add_f32_e32 v3, 1.0, v3
	v_rcp_f32_e32 v218, v3
	v_mul_f32_e32 v3, 0xbfb8aa3b, v219
	v_max_f32_e32 v155, 0xc2700000, v220
	v_exp_f32_e32 v3, v3
	v_mul_f32_e32 v155, 0xbfb8aa3b, v155
	v_mul_f32_e32 v157, 0xbfb8aa3b, v217
	v_exp_f32_e32 v220, v155
	v_max_f32_e32 v155, 0xc2700000, v222
	v_exp_f32_e32 v157, v157
	v_mul_f32_e32 v155, 0xbfb8aa3b, v155
	v_exp_f32_e32 v217, v155
	v_mul_f32_e32 v155, 0xbfb8aa3b, v221
	v_add_f32_e32 v3, 1.0, v3
	v_exp_f32_e32 v155, v155
	v_rcp_f32_e32 v222, v3
	v_add_f32_e32 v3, 1.0, v157
	v_rcp_f32_e32 v219, v3
	v_max_f32_e32 v3, 0xc2700000, v223
	v_mul_f32_e32 v3, 0xbfb8aa3b, v3
	v_exp_f32_e32 v221, v3
	v_add_f32_e32 v3, 1.0, v155
	v_rcp_f32_e32 v223, v3
	v_pk_add_f32 v[210:211], v[210:211], 1.0 op_sel_hi:[1,0]
	v_pk_add_f32 v[216:217], v[216:217], 1.0 op_sel_hi:[1,0]
	v_pk_mul_f32 v[192:193], v[192:193], v[210:211]
	v_pk_mul_f32 v[210:211], v[218:219], v[216:217]
	v_pk_mul_f32 v[82:83], v[82:83], v[192:193]
	v_pk_add_f32 v[192:193], v[220:221], 1.0 op_sel_hi:[1,0]
	v_pk_mul_f32 v[84:85], v[84:85], v[210:211]
	s_waitcnt vmcnt(1)
	v_lshlrev_b32_e32 v3, 16, v202
	v_add_f32_e32 v3, v146, v3
	v_and_b32_e32 v146, 0xffff0000, v202
	v_add_f32_e32 v155, v147, v146
	v_lshlrev_b32_e32 v146, 16, v203
	v_add_f32_e32 v157, v148, v146
	v_and_b32_e32 v146, 0xffff0000, v203
	v_pk_add_f32 v[210:211], v[212:213], 1.0 op_sel_hi:[1,0]
	v_pk_mul_f32 v[192:193], v[222:223], v[192:193]
	v_add_f32_e32 v201, v149, v146
	v_lshlrev_b32_e32 v146, 16, v204
	v_pk_mul_f32 v[210:211], v[214:215], v[210:211]
	v_pk_mul_f32 v[80:81], v[80:81], v[192:193]
	v_add_f32_e32 v193, v142, v146
	v_and_b32_e32 v142, 0xffff0000, v204
	v_pk_mul_f32 v[78:79], v[78:79], v[210:211]
	v_add_f32_e32 v210, v143, v142
	v_lshlrev_b32_e32 v142, 16, v205
	v_add_f32_e32 v211, v144, v142
	v_and_b32_e32 v142, 0xffff0000, v205
	v_add_f32_e32 v213, v145, v142
	s_waitcnt vmcnt(0)
; __device__ __forceinline__ float bf_lo(unsigned w) { return __uint_as_float(w << 16); }
; __device__ __forceinline__ float bf_hi(unsigned w) { return __uint_as_float(w & 0xffff0000u); }
;     __device__ __forceinline__ void mid(f32x4 (&acc)[2][2][4][2], const Unit& u, int wr, int wc, int fr, int fq) const {
;     ...
;         for (int bj = 0; bj < 2; ++bj) { const f32x4 a0 = *(const f32x4*)(bias + col0 + bj * HALF), a1 = *(const f32x4*)(bias + col0 + bj * HALF + 4), b0 = *(const f32x4*)(bias + nb + col0 + bj * HALF), b1 = *(const f32x4*)(bias + nb + col0 + bj * HALF + 4);
; #pragma unroll
;             for (int ai = 0; ai < 2; ++ai)
; #pragma unroll
;                 for (int m = 0; m < 4; ++m) { const size_t r = (size_t)(row0 + ai * HALF + m * 16);
;                     const u32x4 ga = *(const u32x4*)(GA + r * ldg + col0 + bj * HALF), gb = *(const u32x4*)(GB + r * ldg + col0 + bj * HALF);
;                     const float xa[8] = {bf_lo(ga.x) + a0[0], bf_hi(ga.x) + a0[1], bf_lo(ga.y) + a0[2], bf_hi(ga.y) + a0[3], bf_lo(ga.z) + a1[0], bf_hi(ga.z) + a1[1], bf_lo(ga.w) + a1[2], bf_hi(ga.w) + a1[3]};
;                     const float xb[8] = {bf_lo(gb.x) + b0[0], bf_hi(gb.x) + b0[1], bf_lo(gb.y) + b0[2], bf_hi(gb.y) + b0[3], bf_lo(gb.z) + b1[0], bf_hi(gb.z) + b1[1], bf_lo(gb.w) + b1[2], bf_hi(gb.w) + b1[3]};
; #pragma unroll
;                     for (int j = 0; j < 4; ++j) { acc[ai][bj][m][0][j] *= (1.0f + __expf(-fmaxf(xb[j], GB_MIN))) * __builtin_amdgcn_rcpf(1.0f + __expf(-xa[j]));
;                         acc[ai][bj][m][1][j] *= (1.0f + __expf(-fmaxf(xb[4 + j], GB_MIN))) * __builtin_amdgcn_rcpf(1.0f + __expf(-xa[4 + j])); }
;                     asm volatile("" ::: "memory"); } }
	v_lshlrev_b32_e32 v142, 16, v206
	v_add_f32_e32 v146, v138, v142
	v_and_b32_e32 v138, 0xffff0000, v206
	v_add_f32_e32 v212, v139, v138
	v_lshlrev_b32_e32 v138, 16, v207
	v_add_f32_e32 v214, v140, v138
	v_and_b32_e32 v138, 0xffff0000, v207
	v_lshlrev_b32_e32 v147, 16, v208
	v_add_f32_e32 v215, v141, v138
	global_load_dwordx4 v[202:205], v[188:189], off offset:256
	global_load_dwordx4 v[138:141], v[190:191], off offset:528
	global_load_dwordx4 v[142:145], v[190:191], off offset:512
	v_add_f32_e32 v206, v134, v147
	v_and_b32_e32 v134, 0xffff0000, v208
	v_add_f32_e32 v207, v135, v134
	v_lshlrev_b32_e32 v134, 16, v209
	v_add_f32_e32 v216, v136, v134
	v_and_b32_e32 v134, 0xffff0000, v209
	v_add_f32_e32 v217, v137, v134
	v_max_f32_e32 v134, 0xc2700000, v146
	v_mul_f32_e32 v134, 0xbfb8aa3b, v134
	v_exp_f32_e32 v192, v134
	global_load_dwordx4 v[188:191], v[184:185], off offset:256
	global_load_dwordx4 v[134:137], v[186:187], off offset:528
	global_load_dwordx4 v[146:149], v[186:187], off offset:512
	v_mul_f32_e32 v3, 0xbfb8aa3b, v3
	v_exp_f32_e32 v3, v3
	v_max_f32_e32 v185, 0xc2700000, v206
	v_mul_f32_e32 v185, 0xbfb8aa3b, v185
	v_exp_f32_e32 v186, v185
	v_add_f32_e32 v3, 1.0, v3
	v_rcp_f32_e32 v184, v3
	v_mul_f32_e32 v3, 0xbfb8aa3b, v193
	v_exp_f32_e32 v3, v3
	s_nop 0
	v_add_f32_e32 v3, 1.0, v3
	v_rcp_f32_e32 v206, v3
	v_mul_f32_e32 v3, 0xbfb8aa3b, v155
	v_exp_f32_e32 v3, v3
	v_max_f32_e32 v155, 0xc2700000, v212
	v_mul_f32_e32 v155, 0xbfb8aa3b, v155
	v_exp_f32_e32 v193, v155
	v_add_f32_e32 v3, 1.0, v3
	v_rcp_f32_e32 v185, v3
	v_mul_f32_e32 v3, 0xbfb8aa3b, v210
	v_exp_f32_e32 v3, v3
	v_max_f32_e32 v155, 0xc2700000, v207
	v_mul_f32_e32 v155, 0xbfb8aa3b, v155
	v_exp_f32_e32 v187, v155
	v_add_f32_e32 v3, 1.0, v3
	v_rcp_f32_e32 v207, v3
	v_mul_f32_e32 v3, 0xbfb8aa3b, v157
	v_exp_f32_e32 v3, v3
	v_max_f32_e32 v155, 0xc2700000, v214
	v_mul_f32_e32 v155, 0xbfb8aa3b, v155
	v_exp_f32_e32 v208, v155
	v_add_f32_e32 v3, 1.0, v3
	v_rcp_f32_e32 v210, v3
	v_mul_f32_e32 v3, 0xbfb8aa3b, v211
	v_max_f32_e32 v155, 0xc2700000, v216
	v_exp_f32_e32 v3, v3
	v_mul_f32_e32 v155, 0xbfb8aa3b, v155
	v_mul_f32_e32 v157, 0xbfb8aa3b, v201
	v_exp_f32_e32 v212, v155
	v_max_f32_e32 v155, 0xc2700000, v215
	v_exp_f32_e32 v157, v157
	v_mul_f32_e32 v155, 0xbfb8aa3b, v155
	v_exp_f32_e32 v209, v155
	v_mul_f32_e32 v155, 0xbfb8aa3b, v213
	v_add_f32_e32 v3, 1.0, v3
	v_exp_f32_e32 v155, v155
	v_rcp_f32_e32 v214, v3
	v_add_f32_e32 v3, 1.0, v157
	v_rcp_f32_e32 v211, v3
	v_max_f32_e32 v3, 0xc2700000, v217
	v_mul_f32_e32 v3, 0xbfb8aa3b, v3
	v_exp_f32_e32 v213, v3
	v_add_f32_e32 v3, 1.0, v155
	v_rcp_f32_e32 v215, v3
	v_pk_add_f32 v[192:193], v[192:193], 1.0 op_sel_hi:[1,0]
	v_pk_add_f32 v[208:209], v[208:209], 1.0 op_sel_hi:[1,0]
	v_pk_mul_f32 v[184:185], v[184:185], v[192:193]
	v_pk_mul_f32 v[192:193], v[210:211], v[208:209]
	v_pk_mul_f32 v[74:75], v[74:75], v[184:185]
	v_pk_add_f32 v[184:185], v[212:213], 1.0 op_sel_hi:[1,0]
	v_pk_mul_f32 v[76:77], v[76:77], v[192:193]
	v_pk_mul_f32 v[184:185], v[214:215], v[184:185]
	v_pk_add_f32 v[186:187], v[186:187], 1.0 op_sel_hi:[1,0]
	v_pk_mul_f32 v[72:73], v[72:73], v[184:185]
	s_waitcnt vmcnt(5)
	v_and_b32_e32 v184, 0xffff0000, v203
	v_pk_mul_f32 v[186:187], v[206:207], v[186:187]
	s_waitcnt vmcnt(3)
	v_add_f32_e32 v201, v145, v184
	v_lshlrev_b32_e32 v184, 16, v204
	v_add_f32_e32 v192, v138, v184
	v_and_b32_e32 v184, 0xffff0000, v204
	v_add_f32_e32 v193, v139, v184
	v_lshlrev_b32_e32 v184, 16, v205
	v_add_f32_e32 v207, v140, v184
	v_and_b32_e32 v184, 0xffff0000, v205
	v_add_f32_e32 v209, v141, v184
	s_waitcnt vmcnt(2)
	v_lshlrev_b32_e32 v184, 16, v188
	v_lshlrev_b32_e32 v3, 16, v202
	v_and_b32_e32 v155, 0xffff0000, v202
	s_waitcnt vmcnt(0)
	v_add_f32_e32 v202, v146, v184
	v_and_b32_e32 v184, 0xffff0000, v188
	v_lshlrev_b32_e32 v157, 16, v203
	v_add_f32_e32 v203, v147, v184
	v_lshlrev_b32_e32 v184, 16, v189
	v_pk_mul_f32 v[70:71], v[70:71], v[186:187]
	v_add_f32_e32 v204, v148, v184
	global_load_dwordx4 v[184:187], v[158:159], off offset:256
	v_and_b32_e32 v158, 0xffff0000, v189
	v_add_f32_e32 v205, v149, v158
	v_lshlrev_b32_e32 v158, 16, v190
	v_add_f32_e32 v159, v134, v158
	v_and_b32_e32 v158, 0xffff0000, v190
	v_add_f32_e32 v206, v135, v158
	v_lshlrev_b32_e32 v158, 16, v191
	v_add_f32_e32 v208, v136, v158
	v_and_b32_e32 v158, 0xffff0000, v191
	global_load_dwordx4 v[188:191], v[4:5], off offset:256
	v_add_f32_e32 v3, v142, v3
	v_mul_f32_e32 v3, 0xbfb8aa3b, v3
	v_exp_f32_e32 v3, v3
	v_add_f32_e32 v155, v143, v155
	v_add_f32_e32 v211, v137, v158
	v_max_f32_e32 v158, 0xc2700000, v202
	v_add_f32_e32 v3, 1.0, v3
	v_rcp_f32_e32 v4, v3
	v_mul_f32_e32 v3, 0xbfb8aa3b, v192
	v_exp_f32_e32 v3, v3
	v_max_f32_e32 v5, 0xc2700000, v159
	v_mul_f32_e32 v5, 0xbfb8aa3b, v5
	v_exp_f32_e32 v192, v5
	v_add_f32_e32 v3, 1.0, v3
	v_rcp_f32_e32 v202, v3
	v_mul_f32_e32 v3, 0xbfb8aa3b, v155
	v_exp_f32_e32 v3, v3
	v_max_f32_e32 v5, 0xc2700000, v203
	v_mul_f32_e32 v5, 0xbfb8aa3b, v5
	v_exp_f32_e32 v159, v5
	v_add_f32_e32 v3, 1.0, v3
	v_rcp_f32_e32 v5, v3
	v_mul_f32_e32 v3, 0xbfb8aa3b, v193
	v_exp_f32_e32 v3, v3
	v_add_f32_e32 v157, v144, v157
	v_max_f32_e32 v155, 0xc2700000, v206
	v_mul_f32_e32 v155, 0xbfb8aa3b, v155
	v_add_f32_e32 v3, 1.0, v3
	v_rcp_f32_e32 v203, v3
	v_mul_f32_e32 v3, 0xbfb8aa3b, v157
	v_exp_f32_e32 v3, v3
	v_exp_f32_e32 v193, v155
	v_max_f32_e32 v155, 0xc2700000, v204
	v_mul_f32_e32 v155, 0xbfb8aa3b, v155
	v_add_f32_e32 v3, 1.0, v3
	v_exp_f32_e32 v204, v155
	v_rcp_f32_e32 v206, v3
	v_mul_f32_e32 v3, 0xbfb8aa3b, v207
	v_max_f32_e32 v155, 0xc2700000, v208
	v_exp_f32_e32 v3, v3
	v_mul_f32_e32 v155, 0xbfb8aa3b, v155
	v_mul_f32_e32 v157, 0xbfb8aa3b, v201
	v_exp_f32_e32 v208, v155
	v_max_f32_e32 v155, 0xc2700000, v205
	v_exp_f32_e32 v157, v157
	v_mul_f32_e32 v155, 0xbfb8aa3b, v155
	v_exp_f32_e32 v205, v155
	v_mul_f32_e32 v155, 0xbfb8aa3b, v209
	v_add_f32_e32 v3, 1.0, v3
	v_exp_f32_e32 v155, v155
	v_mul_f32_e32 v158, 0xbfb8aa3b, v158
	v_rcp_f32_e32 v210, v3
	v_add_f32_e32 v3, 1.0, v157
	v_exp_f32_e32 v158, v158
	v_rcp_f32_e32 v207, v3
	v_max_f32_e32 v3, 0xc2700000, v211
	v_mul_f32_e32 v3, 0xbfb8aa3b, v3
	v_exp_f32_e32 v209, v3
	v_add_f32_e32 v3, 1.0, v155
	v_rcp_f32_e32 v211, v3
	v_pk_add_f32 v[158:159], v[158:159], 1.0 op_sel_hi:[1,0]
	v_pk_add_f32 v[204:205], v[204:205], 1.0 op_sel_hi:[1,0]
	v_pk_mul_f32 v[4:5], v[4:5], v[158:159]
	v_pk_mul_f32 v[158:159], v[206:207], v[204:205]
	v_pk_mul_f32 v[66:67], v[66:67], v[4:5]
	v_pk_add_f32 v[4:5], v[208:209], 1.0 op_sel_hi:[1,0]
	v_pk_mul_f32 v[68:69], v[68:69], v[158:159]
	v_pk_mul_f32 v[4:5], v[210:211], v[4:5]
	v_pk_add_f32 v[158:159], v[192:193], 1.0 op_sel_hi:[1,0]
	v_pk_mul_f32 v[64:65], v[64:65], v[4:5]
	s_waitcnt vmcnt(1)
; __device__ __forceinline__ float bf_lo(unsigned w) { return __uint_as_float(w << 16); }
; __device__ __forceinline__ float bf_hi(unsigned w) { return __uint_as_float(w & 0xffff0000u); }
;     __device__ __forceinline__ void mid(f32x4 (&acc)[2][2][4][2], const Unit& u, int wr, int wc, int fr, int fq) const {
;     ...
;                 for (int m = 0; m < 4; ++m) { const size_t r = (size_t)(row0 + ai * HALF + m * 16);
;                     const u32x4 ga = *(const u32x4*)(GA + r * ldg + col0 + bj * HALF), gb = *(const u32x4*)(GB + r * ldg + col0 + bj * HALF);
;                     const float xa[8] = {bf_lo(ga.x) + a0[0], bf_hi(ga.x) + a0[1], bf_lo(ga.y) + a0[2], bf_hi(ga.y) + a0[3], bf_lo(ga.z) + a1[0], bf_hi(ga.z) + a1[1], bf_lo(ga.w) + a1[2], bf_hi(ga.w) + a1[3]};
;                     const float xb[8] = {bf_lo(gb.x) + b0[0], bf_hi(gb.x) + b0[1], bf_lo(gb.y) + b0[2], bf_hi(gb.y) + b0[3], bf_lo(gb.z) + b1[0], bf_hi(gb.z) + b1[1], bf_lo(gb.w) + b1[2], bf_hi(gb.w) + b1[3]};
; #pragma unroll
;                     for (int j = 0; j < 4; ++j) { acc[ai][bj][m][0][j] *= (1.0f + __expf(-fmaxf(xb[j], GB_MIN))) * __builtin_amdgcn_rcpf(1.0f + __expf(-xa[j]));
;                         acc[ai][bj][m][1][j] *= (1.0f + __expf(-fmaxf(xb[4 + j], GB_MIN))) * __builtin_amdgcn_rcpf(1.0f + __expf(-xa[4 + j])); }
;                     asm volatile("" ::: "memory"); } }
	v_and_b32_e32 v4, 0xffff0000, v184
	v_add_f32_e32 v5, v143, v4
	v_lshlrev_b32_e32 v4, 16, v185
	v_add_f32_e32 v155, v144, v4
	v_and_b32_e32 v4, 0xffff0000, v185
	v_add_f32_e32 v157, v145, v4
	v_lshlrev_b32_e32 v4, 16, v186
	v_add_f32_e32 v192, v138, v4
	v_and_b32_e32 v4, 0xffff0000, v186
	v_pk_mul_f32 v[158:159], v[202:203], v[158:159]
	v_add_f32_e32 v193, v139, v4
	v_lshlrev_b32_e32 v4, 16, v187
	v_pk_mul_f32 v[62:63], v[62:63], v[158:159]
	v_lshlrev_b32_e32 v3, 16, v184
	v_add_f32_e32 v201, v140, v4
	v_and_b32_e32 v4, 0xffff0000, v187
	s_waitcnt vmcnt(0)
	v_and_b32_e32 v158, 0xffff0000, v188
	global_load_dwordx4 v[184:187], v[162:163], off offset:256
	v_add_f32_e32 v202, v147, v158
	v_lshlrev_b32_e32 v158, 16, v189
	v_add_f32_e32 v203, v148, v158
	v_and_b32_e32 v158, 0xffff0000, v189
	v_add_f32_e32 v206, v149, v158
	v_lshlrev_b32_e32 v158, 16, v190
	v_add_f32_e32 v163, v134, v158
	v_and_b32_e32 v158, 0xffff0000, v190
	v_add_f32_e32 v189, v135, v158
	v_lshlrev_b32_e32 v158, 16, v191
	v_add_f32_e32 v204, v136, v158
	v_and_b32_e32 v158, 0xffff0000, v191
	v_add_f32_e32 v207, v137, v158
	global_load_dwordx4 v[158:161], v[160:161], off offset:256
	v_add_f32_e32 v3, v142, v3
	v_mul_f32_e32 v3, 0xbfb8aa3b, v3
	v_exp_f32_e32 v3, v3
	v_max_f32_e32 v163, 0xc2700000, v163
	v_mul_f32_e32 v163, 0xbfb8aa3b, v163
	v_add_f32_e32 v205, v141, v4
	v_add_f32_e32 v3, 1.0, v3
	v_rcp_f32_e32 v162, v3
	v_mul_f32_e32 v3, 0xbfb8aa3b, v192
	v_exp_f32_e32 v3, v3
	v_lshlrev_b32_e32 v4, 16, v188
	v_exp_f32_e32 v188, v163
	v_mul_f32_e32 v157, 0xbfb8aa3b, v157
	v_add_f32_e32 v3, 1.0, v3
	v_rcp_f32_e32 v190, v3
	v_mul_f32_e32 v3, 0xbfb8aa3b, v5
	v_exp_f32_e32 v3, v3
	v_max_f32_e32 v5, 0xc2700000, v202
	v_exp_f32_e32 v157, v157
	v_add_f32_e32 v4, v146, v4
	v_add_f32_e32 v3, 1.0, v3
	v_rcp_f32_e32 v163, v3
	v_mul_f32_e32 v3, 0xbfb8aa3b, v193
	v_exp_f32_e32 v3, v3
	v_max_f32_e32 v4, 0xc2700000, v4
	v_mul_f32_e32 v4, 0xbfb8aa3b, v4
	v_mul_f32_e32 v5, 0xbfb8aa3b, v5
	v_add_f32_e32 v3, 1.0, v3
	v_rcp_f32_e32 v191, v3
	v_mul_f32_e32 v3, 0xbfb8aa3b, v155
	v_exp_f32_e32 v3, v3
	v_max_f32_e32 v155, 0xc2700000, v203
	v_mul_f32_e32 v155, 0xbfb8aa3b, v155
	v_exp_f32_e32 v192, v155
	v_add_f32_e32 v3, 1.0, v3
	v_rcp_f32_e32 v202, v3
	v_mul_f32_e32 v3, 0xbfb8aa3b, v201
	v_max_f32_e32 v155, 0xc2700000, v204
	v_exp_f32_e32 v3, v3
	v_mul_f32_e32 v155, 0xbfb8aa3b, v155
	v_exp_f32_e32 v204, v155
	v_max_f32_e32 v155, 0xc2700000, v206
	v_mul_f32_e32 v155, 0xbfb8aa3b, v155
	v_exp_f32_e32 v193, v155
	v_mul_f32_e32 v155, 0xbfb8aa3b, v205
	v_add_f32_e32 v3, 1.0, v3
	v_exp_f32_e32 v155, v155
	v_rcp_f32_e32 v206, v3
	v_add_f32_e32 v3, 1.0, v157
	v_exp_f32_e32 v4, v4
	v_exp_f32_e32 v5, v5
	v_rcp_f32_e32 v203, v3
	v_max_f32_e32 v3, 0xc2700000, v207
	v_mul_f32_e32 v3, 0xbfb8aa3b, v3
	v_exp_f32_e32 v205, v3
	v_add_f32_e32 v3, 1.0, v155
	v_rcp_f32_e32 v207, v3
	v_max_f32_e32 v189, 0xc2700000, v189
	v_pk_add_f32 v[4:5], v[4:5], 1.0 op_sel_hi:[1,0]
	v_mul_f32_e32 v189, 0xbfb8aa3b, v189
	v_pk_mul_f32 v[4:5], v[162:163], v[4:5]
	v_exp_f32_e32 v189, v189
	v_pk_mul_f32 v[58:59], v[58:59], v[4:5]
	v_pk_add_f32 v[4:5], v[204:205], 1.0 op_sel_hi:[1,0]
	v_pk_add_f32 v[192:193], v[192:193], 1.0 op_sel_hi:[1,0]
	v_pk_mul_f32 v[4:5], v[206:207], v[4:5]
	v_pk_mul_f32 v[162:163], v[202:203], v[192:193]
	v_pk_mul_f32 v[56:57], v[56:57], v[4:5]
	s_waitcnt vmcnt(1)
	v_and_b32_e32 v4, 0xffff0000, v184
	v_add_f32_e32 v5, v143, v4
	v_lshlrev_b32_e32 v4, 16, v185
	v_pk_mul_f32 v[60:61], v[60:61], v[162:163]
	v_pk_add_f32 v[162:163], v[188:189], 1.0 op_sel_hi:[1,0]
	v_add_f32_e32 v155, v144, v4
	v_and_b32_e32 v4, 0xffff0000, v185
	v_pk_mul_f32 v[162:163], v[190:191], v[162:163]
	v_add_f32_e32 v157, v145, v4
	v_lshlrev_b32_e32 v4, 16, v186
	v_pk_mul_f32 v[54:55], v[54:55], v[162:163]
	v_add_f32_e32 v163, v138, v4
	v_and_b32_e32 v4, 0xffff0000, v186
	v_add_f32_e32 v188, v139, v4
	v_lshlrev_b32_e32 v4, 16, v187
	v_add_f32_e32 v189, v140, v4
	v_and_b32_e32 v4, 0xffff0000, v187
	v_lshlrev_b32_e32 v3, 16, v184
	v_add_f32_e32 v193, v141, v4
	s_waitcnt vmcnt(0)
	v_lshlrev_b32_e32 v4, 16, v158
	v_and_b32_e32 v158, 0xffff0000, v158
	global_load_dwordx4 v[184:187], v[166:167], off offset:256
	v_add_f32_e32 v190, v147, v158
	v_lshlrev_b32_e32 v158, 16, v159
	v_add_f32_e32 v191, v148, v158
	v_and_b32_e32 v158, 0xffff0000, v159
	v_add_f32_e32 v201, v149, v158
	v_lshlrev_b32_e32 v158, 16, v160
	v_add_f32_e32 v166, v134, v158
	v_and_b32_e32 v158, 0xffff0000, v160
	v_add_f32_e32 v167, v135, v158
	v_lshlrev_b32_e32 v158, 16, v161
	v_add_f32_e32 v192, v136, v158
	v_and_b32_e32 v158, 0xffff0000, v161
	v_add_f32_e32 v203, v137, v158
	global_load_dwordx4 v[158:161], v[164:165], off offset:256
	v_add_f32_e32 v3, v142, v3
	v_mul_f32_e32 v3, 0xbfb8aa3b, v3
	v_exp_f32_e32 v3, v3
	v_max_f32_e32 v165, 0xc2700000, v167
	v_mul_f32_e32 v157, 0xbfb8aa3b, v157
	v_exp_f32_e32 v157, v157
	v_add_f32_e32 v3, 1.0, v3
	v_rcp_f32_e32 v162, v3
	v_mul_f32_e32 v3, 0xbfb8aa3b, v163
	v_exp_f32_e32 v3, v3
	v_max_f32_e32 v163, 0xc2700000, v166
	v_mul_f32_e32 v163, 0xbfb8aa3b, v163
	v_exp_f32_e32 v164, v163
	v_add_f32_e32 v3, 1.0, v3
	v_rcp_f32_e32 v166, v3
	v_mul_f32_e32 v3, 0xbfb8aa3b, v5
	v_exp_f32_e32 v3, v3
	v_max_f32_e32 v5, 0xc2700000, v190
	v_add_f32_e32 v4, v146, v4
	v_max_f32_e32 v4, 0xc2700000, v4
	v_add_f32_e32 v3, 1.0, v3
	v_rcp_f32_e32 v163, v3
	v_mul_f32_e32 v3, 0xbfb8aa3b, v188
	v_exp_f32_e32 v3, v3
	v_mul_f32_e32 v4, 0xbfb8aa3b, v4
	v_mul_f32_e32 v5, 0xbfb8aa3b, v5
	v_exp_f32_e32 v4, v4
	v_add_f32_e32 v3, 1.0, v3
	v_rcp_f32_e32 v167, v3
	v_mul_f32_e32 v3, 0xbfb8aa3b, v155
	v_exp_f32_e32 v3, v3
	v_max_f32_e32 v155, 0xc2700000, v191
	v_mul_f32_e32 v155, 0xbfb8aa3b, v155
	v_exp_f32_e32 v188, v155
	v_add_f32_e32 v3, 1.0, v3
	v_rcp_f32_e32 v190, v3
	v_mul_f32_e32 v3, 0xbfb8aa3b, v189
	v_max_f32_e32 v155, 0xc2700000, v192
	v_exp_f32_e32 v3, v3
	v_mul_f32_e32 v155, 0xbfb8aa3b, v155
	v_exp_f32_e32 v192, v155
	v_max_f32_e32 v155, 0xc2700000, v201
	v_mul_f32_e32 v155, 0xbfb8aa3b, v155
	v_exp_f32_e32 v189, v155
	v_mul_f32_e32 v155, 0xbfb8aa3b, v193
	v_add_f32_e32 v3, 1.0, v3
	v_exp_f32_e32 v155, v155
	v_rcp_f32_e32 v202, v3
	v_add_f32_e32 v3, 1.0, v157
	v_exp_f32_e32 v5, v5
	v_rcp_f32_e32 v191, v3
	v_max_f32_e32 v3, 0xc2700000, v203
	v_mul_f32_e32 v3, 0xbfb8aa3b, v3
	v_exp_f32_e32 v193, v3
	v_add_f32_e32 v3, 1.0, v155
	v_rcp_f32_e32 v203, v3
	v_pk_add_f32 v[4:5], v[4:5], 1.0 op_sel_hi:[1,0]
	v_mul_f32_e32 v165, 0xbfb8aa3b, v165
	v_pk_mul_f32 v[4:5], v[162:163], v[4:5]
	v_exp_f32_e32 v165, v165
	v_pk_mul_f32 v[50:51], v[50:51], v[4:5]
	v_pk_add_f32 v[4:5], v[192:193], 1.0 op_sel_hi:[1,0]
	v_pk_add_f32 v[188:189], v[188:189], 1.0 op_sel_hi:[1,0]
	v_pk_mul_f32 v[4:5], v[202:203], v[4:5]
	v_pk_mul_f32 v[162:163], v[190:191], v[188:189]
	v_pk_mul_f32 v[48:49], v[48:49], v[4:5]
	s_waitcnt vmcnt(1)
; __device__ __forceinline__ float bf_lo(unsigned w) { return __uint_as_float(w << 16); }
; __device__ __forceinline__ float bf_hi(unsigned w) { return __uint_as_float(w & 0xffff0000u); }
;     __device__ __forceinline__ void mid(f32x4 (&acc)[2][2][4][2], const Unit& u, int wr, int wc, int fr, int fq) const {
;     ...
;                 for (int m = 0; m < 4; ++m) { const size_t r = (size_t)(row0 + ai * HALF + m * 16);
;                     const u32x4 ga = *(const u32x4*)(GA + r * ldg + col0 + bj * HALF), gb = *(const u32x4*)(GB + r * ldg + col0 + bj * HALF);
;                     const float xa[8] = {bf_lo(ga.x) + a0[0], bf_hi(ga.x) + a0[1], bf_lo(ga.y) + a0[2], bf_hi(ga.y) + a0[3], bf_lo(ga.z) + a1[0], bf_hi(ga.z) + a1[1], bf_lo(ga.w) + a1[2], bf_hi(ga.w) + a1[3]};
;                     const float xb[8] = {bf_lo(gb.x) + b0[0], bf_hi(gb.x) + b0[1], bf_lo(gb.y) + b0[2], bf_hi(gb.y) + b0[3], bf_lo(gb.z) + b1[0], bf_hi(gb.z) + b1[1], bf_lo(gb.w) + b1[2], bf_hi(gb.w) + b1[3]};
; #pragma unroll
;                     for (int j = 0; j < 4; ++j) { acc[ai][bj][m][0][j] *= (1.0f + __expf(-fmaxf(xb[j], GB_MIN))) * __builtin_amdgcn_rcpf(1.0f + __expf(-xa[j]));
;                         acc[ai][bj][m][1][j] *= (1.0f + __expf(-fmaxf(xb[4 + j], GB_MIN))) * __builtin_amdgcn_rcpf(1.0f + __expf(-xa[4 + j])); }
;                     asm volatile("" ::: "memory"); } }
	v_and_b32_e32 v4, 0xffff0000, v184
	v_add_f32_e32 v5, v143, v4
	v_lshlrev_b32_e32 v4, 16, v185
	v_add_f32_e32 v155, v144, v4
	v_and_b32_e32 v4, 0xffff0000, v185
	v_pk_mul_f32 v[52:53], v[52:53], v[162:163]
	v_pk_add_f32 v[162:163], v[164:165], 1.0 op_sel_hi:[1,0]
	v_add_f32_e32 v157, v145, v4
	v_lshlrev_b32_e32 v4, 16, v186
	v_pk_mul_f32 v[162:163], v[166:167], v[162:163]
	v_add_f32_e32 v167, v138, v4
	v_and_b32_e32 v4, 0xffff0000, v186
	v_lshlrev_b32_e32 v3, 16, v184
	v_add_f32_e32 v184, v139, v4
	v_lshlrev_b32_e32 v4, 16, v187
	v_add_f32_e32 v185, v140, v4
	v_and_b32_e32 v4, 0xffff0000, v187
	v_pk_mul_f32 v[46:47], v[46:47], v[162:163]
	v_add_f32_e32 v189, v141, v4
	s_waitcnt vmcnt(0)
	v_lshlrev_b32_e32 v4, 16, v158
	v_and_b32_e32 v158, 0xffff0000, v158
	global_load_dwordx4 v[162:165], v[170:171], off offset:256
	v_add_f32_e32 v186, v147, v158
	v_lshlrev_b32_e32 v158, 16, v159
	v_add_f32_e32 v187, v148, v158
	v_and_b32_e32 v158, 0xffff0000, v159
	v_add_f32_e32 v190, v149, v158
	v_lshlrev_b32_e32 v158, 16, v160
	v_add_f32_e32 v170, v134, v158
	v_and_b32_e32 v158, 0xffff0000, v160
	v_add_f32_e32 v171, v135, v158
	v_lshlrev_b32_e32 v158, 16, v161
	v_add_f32_e32 v188, v136, v158
	v_and_b32_e32 v158, 0xffff0000, v161
	v_add_f32_e32 v191, v137, v158
	global_load_dwordx4 v[158:161], v[168:169], off offset:256
	v_add_f32_e32 v3, v142, v3
	v_mul_f32_e32 v3, 0xbfb8aa3b, v3
	v_exp_f32_e32 v3, v3
	v_max_f32_e32 v169, 0xc2700000, v171
	v_mul_f32_e32 v157, 0xbfb8aa3b, v157
	v_exp_f32_e32 v157, v157
	v_add_f32_e32 v3, 1.0, v3
	v_rcp_f32_e32 v166, v3
	v_mul_f32_e32 v3, 0xbfb8aa3b, v167
	v_exp_f32_e32 v3, v3
	v_max_f32_e32 v167, 0xc2700000, v170
	v_mul_f32_e32 v167, 0xbfb8aa3b, v167
	v_exp_f32_e32 v168, v167
	v_add_f32_e32 v3, 1.0, v3
	v_rcp_f32_e32 v170, v3
	v_mul_f32_e32 v3, 0xbfb8aa3b, v5
	v_exp_f32_e32 v3, v3
	v_max_f32_e32 v5, 0xc2700000, v186
	v_add_f32_e32 v4, v146, v4
	v_max_f32_e32 v4, 0xc2700000, v4
	v_add_f32_e32 v3, 1.0, v3
	v_rcp_f32_e32 v167, v3
	v_mul_f32_e32 v3, 0xbfb8aa3b, v184
	v_exp_f32_e32 v3, v3
	v_mul_f32_e32 v4, 0xbfb8aa3b, v4
	v_mul_f32_e32 v5, 0xbfb8aa3b, v5
	v_exp_f32_e32 v4, v4
	v_add_f32_e32 v3, 1.0, v3
	v_rcp_f32_e32 v171, v3
	v_mul_f32_e32 v3, 0xbfb8aa3b, v155
	v_exp_f32_e32 v3, v3
	v_max_f32_e32 v155, 0xc2700000, v187
	v_mul_f32_e32 v155, 0xbfb8aa3b, v155
	v_exp_f32_e32 v184, v155
	v_add_f32_e32 v3, 1.0, v3
	v_rcp_f32_e32 v186, v3
	v_mul_f32_e32 v3, 0xbfb8aa3b, v185
	v_max_f32_e32 v155, 0xc2700000, v188
	v_exp_f32_e32 v3, v3
	v_mul_f32_e32 v155, 0xbfb8aa3b, v155
	v_exp_f32_e32 v188, v155
	v_max_f32_e32 v155, 0xc2700000, v190
	v_mul_f32_e32 v155, 0xbfb8aa3b, v155
	v_exp_f32_e32 v185, v155
	v_mul_f32_e32 v155, 0xbfb8aa3b, v189
	v_add_f32_e32 v3, 1.0, v3
	v_exp_f32_e32 v155, v155
	v_rcp_f32_e32 v190, v3
	v_add_f32_e32 v3, 1.0, v157
	v_exp_f32_e32 v5, v5
	v_rcp_f32_e32 v187, v3
	v_max_f32_e32 v3, 0xc2700000, v191
	v_mul_f32_e32 v3, 0xbfb8aa3b, v3
	v_exp_f32_e32 v189, v3
	v_add_f32_e32 v3, 1.0, v155
	v_rcp_f32_e32 v191, v3
	v_pk_add_f32 v[4:5], v[4:5], 1.0 op_sel_hi:[1,0]
	v_mul_f32_e32 v169, 0xbfb8aa3b, v169
	v_pk_mul_f32 v[4:5], v[166:167], v[4:5]
	v_exp_f32_e32 v169, v169
	v_pk_mul_f32 v[42:43], v[42:43], v[4:5]
	v_pk_add_f32 v[4:5], v[188:189], 1.0 op_sel_hi:[1,0]
	v_pk_add_f32 v[184:185], v[184:185], 1.0 op_sel_hi:[1,0]
	v_pk_mul_f32 v[4:5], v[190:191], v[4:5]
	v_pk_mul_f32 v[166:167], v[186:187], v[184:185]
	v_pk_mul_f32 v[40:41], v[40:41], v[4:5]
	s_waitcnt vmcnt(1)
	v_and_b32_e32 v4, 0xffff0000, v162
	v_add_f32_e32 v5, v143, v4
	v_lshlrev_b32_e32 v4, 16, v163
	v_pk_mul_f32 v[44:45], v[44:45], v[166:167]
	v_pk_add_f32 v[166:167], v[168:169], 1.0 op_sel_hi:[1,0]
	v_add_f32_e32 v155, v144, v4
	v_and_b32_e32 v4, 0xffff0000, v163
	v_pk_mul_f32 v[166:167], v[170:171], v[166:167]
	v_add_f32_e32 v157, v145, v4
	v_lshlrev_b32_e32 v4, 16, v164
	v_pk_mul_f32 v[38:39], v[38:39], v[166:167]
	v_add_f32_e32 v167, v138, v4
	v_and_b32_e32 v4, 0xffff0000, v164
	v_add_f32_e32 v169, v139, v4
	v_lshlrev_b32_e32 v4, 16, v165
	v_add_f32_e32 v184, v140, v4
	v_and_b32_e32 v4, 0xffff0000, v165
	v_lshlrev_b32_e32 v3, 16, v162
	v_add_f32_e32 v185, v141, v4
	s_waitcnt vmcnt(0)
	v_lshlrev_b32_e32 v4, 16, v158
	v_and_b32_e32 v158, 0xffff0000, v158
	global_load_dwordx4 v[162:165], v[174:175], off offset:256
	v_add_f32_e32 v171, v147, v158
	v_lshlrev_b32_e32 v158, 16, v159
	v_add_f32_e32 v186, v148, v158
	v_and_b32_e32 v158, 0xffff0000, v159
	v_add_f32_e32 v175, v149, v158
	v_lshlrev_b32_e32 v158, 16, v160
	v_add_f32_e32 v168, v134, v158
	v_and_b32_e32 v158, 0xffff0000, v160
	v_add_f32_e32 v174, v135, v158
	v_lshlrev_b32_e32 v158, 16, v161
	v_add_f32_e32 v187, v136, v158
	v_and_b32_e32 v158, 0xffff0000, v161
	v_add_f32_e32 v188, v137, v158
	global_load_dwordx4 v[158:161], v[172:173], off offset:256
	v_add_f32_e32 v3, v142, v3
	v_mul_f32_e32 v3, 0xbfb8aa3b, v3
	v_exp_f32_e32 v3, v3
	v_mul_f32_e32 v157, 0xbfb8aa3b, v157
	v_exp_f32_e32 v157, v157
	v_add_f32_e32 v4, v146, v4
	v_add_f32_e32 v3, 1.0, v3
	v_rcp_f32_e32 v166, v3
	v_mul_f32_e32 v3, 0xbfb8aa3b, v167
	v_exp_f32_e32 v3, v3
	v_max_f32_e32 v167, 0xc2700000, v168
	v_mul_f32_e32 v167, 0xbfb8aa3b, v167
	v_exp_f32_e32 v168, v167
	v_add_f32_e32 v3, 1.0, v3
	v_rcp_f32_e32 v170, v3
	v_mul_f32_e32 v3, 0xbfb8aa3b, v5
	v_exp_f32_e32 v3, v3
	v_max_f32_e32 v5, 0xc2700000, v171
	v_max_f32_e32 v4, 0xc2700000, v4
	v_mul_f32_e32 v4, 0xbfb8aa3b, v4
	v_add_f32_e32 v3, 1.0, v3
	v_rcp_f32_e32 v167, v3
	v_mul_f32_e32 v3, 0xbfb8aa3b, v169
	v_exp_f32_e32 v3, v3
	v_max_f32_e32 v169, 0xc2700000, v174
	v_mul_f32_e32 v5, 0xbfb8aa3b, v5
	v_exp_f32_e32 v4, v4
	v_add_f32_e32 v3, 1.0, v3
	v_rcp_f32_e32 v171, v3
	v_mul_f32_e32 v3, 0xbfb8aa3b, v155
	v_exp_f32_e32 v3, v3
	v_max_f32_e32 v155, 0xc2700000, v186
	v_mul_f32_e32 v155, 0xbfb8aa3b, v155
	v_exp_f32_e32 v172, v155
	v_add_f32_e32 v3, 1.0, v3
	v_rcp_f32_e32 v174, v3
	v_mul_f32_e32 v3, 0xbfb8aa3b, v184
	v_max_f32_e32 v155, 0xc2700000, v187
	v_exp_f32_e32 v3, v3
	v_mul_f32_e32 v155, 0xbfb8aa3b, v155
	v_exp_f32_e32 v184, v155
	v_max_f32_e32 v155, 0xc2700000, v175
	v_mul_f32_e32 v155, 0xbfb8aa3b, v155
	v_exp_f32_e32 v173, v155
	v_mul_f32_e32 v155, 0xbfb8aa3b, v185
	v_add_f32_e32 v3, 1.0, v3
	v_exp_f32_e32 v155, v155
	v_rcp_f32_e32 v186, v3
	v_add_f32_e32 v3, 1.0, v157
	v_exp_f32_e32 v5, v5
	v_rcp_f32_e32 v175, v3
	v_max_f32_e32 v3, 0xc2700000, v188
	v_mul_f32_e32 v3, 0xbfb8aa3b, v3
	v_exp_f32_e32 v185, v3
	v_add_f32_e32 v3, 1.0, v155
	v_rcp_f32_e32 v187, v3
	v_pk_add_f32 v[4:5], v[4:5], 1.0 op_sel_hi:[1,0]
	v_mul_f32_e32 v169, 0xbfb8aa3b, v169
	v_pk_mul_f32 v[4:5], v[166:167], v[4:5]
	v_exp_f32_e32 v169, v169
	v_pk_mul_f32 v[34:35], v[34:35], v[4:5]
	v_pk_add_f32 v[4:5], v[184:185], 1.0 op_sel_hi:[1,0]
	v_pk_add_f32 v[172:173], v[172:173], 1.0 op_sel_hi:[1,0]
	v_pk_mul_f32 v[4:5], v[186:187], v[4:5]
	v_pk_mul_f32 v[166:167], v[174:175], v[172:173]
	v_pk_mul_f32 v[32:33], v[32:33], v[4:5]
	s_waitcnt vmcnt(1)
; __device__ __forceinline__ float bf_lo(unsigned w) { return __uint_as_float(w << 16); }
; __device__ __forceinline__ float bf_hi(unsigned w) { return __uint_as_float(w & 0xffff0000u); }
;     __device__ __forceinline__ void mid(f32x4 (&acc)[2][2][4][2], const Unit& u, int wr, int wc, int fr, int fq) const {
;     ...
;                 for (int m = 0; m < 4; ++m) { const size_t r = (size_t)(row0 + ai * HALF + m * 16);
;                     const u32x4 ga = *(const u32x4*)(GA + r * ldg + col0 + bj * HALF), gb = *(const u32x4*)(GB + r * ldg + col0 + bj * HALF);
;                     const float xa[8] = {bf_lo(ga.x) + a0[0], bf_hi(ga.x) + a0[1], bf_lo(ga.y) + a0[2], bf_hi(ga.y) + a0[3], bf_lo(ga.z) + a1[0], bf_hi(ga.z) + a1[1], bf_lo(ga.w) + a1[2], bf_hi(ga.w) + a1[3]};
;                     const float xb[8] = {bf_lo(gb.x) + b0[0], bf_hi(gb.x) + b0[1], bf_lo(gb.y) + b0[2], bf_hi(gb.y) + b0[3], bf_lo(gb.z) + b1[0], bf_hi(gb.z) + b1[1], bf_lo(gb.w) + b1[2], bf_hi(gb.w) + b1[3]};
; #pragma unroll
;                     for (int j = 0; j < 4; ++j) { acc[ai][bj][m][0][j] *= (1.0f + __expf(-fmaxf(xb[j], GB_MIN))) * __builtin_amdgcn_rcpf(1.0f + __expf(-xa[j]));
;                         acc[ai][bj][m][1][j] *= (1.0f + __expf(-fmaxf(xb[4 + j], GB_MIN))) * __builtin_amdgcn_rcpf(1.0f + __expf(-xa[4 + j])); }
;                     asm volatile("" ::: "memory"); } }
	v_and_b32_e32 v4, 0xffff0000, v162
	v_add_f32_e32 v5, v143, v4
	v_lshlrev_b32_e32 v4, 16, v163
	v_pk_mul_f32 v[36:37], v[36:37], v[166:167]
	v_pk_add_f32 v[166:167], v[168:169], 1.0 op_sel_hi:[1,0]
	v_add_f32_e32 v155, v144, v4
	v_and_b32_e32 v4, 0xffff0000, v163
	v_pk_mul_f32 v[166:167], v[170:171], v[166:167]
	v_add_f32_e32 v157, v145, v4
	v_lshlrev_b32_e32 v4, 16, v164
	v_pk_mul_f32 v[30:31], v[30:31], v[166:167]
	v_add_f32_e32 v167, v138, v4
	v_and_b32_e32 v4, 0xffff0000, v164
	v_add_f32_e32 v169, v139, v4
	v_lshlrev_b32_e32 v4, 16, v165
	v_add_f32_e32 v173, v140, v4
	v_and_b32_e32 v4, 0xffff0000, v165
	v_lshlrev_b32_e32 v3, 16, v162
	v_add_f32_e32 v184, v141, v4
	s_waitcnt vmcnt(0)
	v_lshlrev_b32_e32 v4, 16, v158
	v_and_b32_e32 v158, 0xffff0000, v158
	global_load_dwordx4 v[162:165], v[178:179], off offset:256
	v_add_f32_e32 v171, v147, v158
	v_lshlrev_b32_e32 v158, 16, v159
	v_add_f32_e32 v172, v148, v158
	v_and_b32_e32 v158, 0xffff0000, v159
	v_add_f32_e32 v175, v149, v158
	v_lshlrev_b32_e32 v158, 16, v160
	v_add_f32_e32 v168, v134, v158
	v_and_b32_e32 v158, 0xffff0000, v160
	v_add_f32_e32 v174, v135, v158
	v_lshlrev_b32_e32 v158, 16, v161
	v_add_f32_e32 v178, v136, v158
	v_and_b32_e32 v158, 0xffff0000, v161
	v_add_f32_e32 v179, v137, v158
	global_load_dwordx4 v[158:161], v[176:177], off offset:256
	v_add_f32_e32 v3, v142, v3
	v_mul_f32_e32 v3, 0xbfb8aa3b, v3
	v_exp_f32_e32 v3, v3
	v_mul_f32_e32 v157, 0xbfb8aa3b, v157
	v_exp_f32_e32 v157, v157
	v_add_f32_e32 v4, v146, v4
	v_add_f32_e32 v3, 1.0, v3
	v_rcp_f32_e32 v166, v3
	v_mul_f32_e32 v3, 0xbfb8aa3b, v167
	v_exp_f32_e32 v3, v3
	v_max_f32_e32 v167, 0xc2700000, v168
	v_mul_f32_e32 v167, 0xbfb8aa3b, v167
	v_exp_f32_e32 v168, v167
	v_add_f32_e32 v3, 1.0, v3
	v_rcp_f32_e32 v170, v3
	v_mul_f32_e32 v3, 0xbfb8aa3b, v5
	v_exp_f32_e32 v3, v3
	v_max_f32_e32 v5, 0xc2700000, v171
	v_max_f32_e32 v4, 0xc2700000, v4
	v_mul_f32_e32 v4, 0xbfb8aa3b, v4
	v_add_f32_e32 v3, 1.0, v3
	v_rcp_f32_e32 v167, v3
	v_mul_f32_e32 v3, 0xbfb8aa3b, v169
	v_exp_f32_e32 v3, v3
	v_max_f32_e32 v169, 0xc2700000, v174
	v_mul_f32_e32 v5, 0xbfb8aa3b, v5
	v_exp_f32_e32 v4, v4
	v_add_f32_e32 v3, 1.0, v3
	v_rcp_f32_e32 v171, v3
	v_mul_f32_e32 v3, 0xbfb8aa3b, v155
	v_exp_f32_e32 v3, v3
	v_max_f32_e32 v155, 0xc2700000, v172
	v_mul_f32_e32 v155, 0xbfb8aa3b, v155
	v_exp_f32_e32 v172, v155
	v_add_f32_e32 v3, 1.0, v3
	v_rcp_f32_e32 v174, v3
	v_mul_f32_e32 v3, 0xbfb8aa3b, v173
	v_max_f32_e32 v155, 0xc2700000, v178
	v_exp_f32_e32 v3, v3
	v_mul_f32_e32 v155, 0xbfb8aa3b, v155
	v_exp_f32_e32 v176, v155
	v_max_f32_e32 v155, 0xc2700000, v175
	v_mul_f32_e32 v155, 0xbfb8aa3b, v155
	v_exp_f32_e32 v173, v155
	v_mul_f32_e32 v155, 0xbfb8aa3b, v184
	v_add_f32_e32 v3, 1.0, v3
	v_exp_f32_e32 v155, v155
	v_rcp_f32_e32 v178, v3
	v_add_f32_e32 v3, 1.0, v157
	v_exp_f32_e32 v5, v5
	v_rcp_f32_e32 v175, v3
	v_max_f32_e32 v3, 0xc2700000, v179
	v_mul_f32_e32 v3, 0xbfb8aa3b, v3
	v_exp_f32_e32 v177, v3
	v_add_f32_e32 v3, 1.0, v155
	v_rcp_f32_e32 v179, v3
	v_pk_add_f32 v[4:5], v[4:5], 1.0 op_sel_hi:[1,0]
	v_mul_f32_e32 v169, 0xbfb8aa3b, v169
	v_pk_mul_f32 v[4:5], v[166:167], v[4:5]
	v_exp_f32_e32 v169, v169
	v_pk_mul_f32 v[26:27], v[26:27], v[4:5]
	v_pk_add_f32 v[4:5], v[176:177], 1.0 op_sel_hi:[1,0]
	v_pk_add_f32 v[172:173], v[172:173], 1.0 op_sel_hi:[1,0]
	v_pk_mul_f32 v[4:5], v[178:179], v[4:5]
	v_pk_mul_f32 v[166:167], v[174:175], v[172:173]
	v_pk_mul_f32 v[24:25], v[24:25], v[4:5]
	s_waitcnt vmcnt(1)
	v_and_b32_e32 v4, 0xffff0000, v162
	v_add_f32_e32 v5, v143, v4
	v_lshlrev_b32_e32 v4, 16, v163
	v_pk_mul_f32 v[28:29], v[28:29], v[166:167]
	v_pk_add_f32 v[166:167], v[168:169], 1.0 op_sel_hi:[1,0]
	v_add_f32_e32 v155, v144, v4
	v_and_b32_e32 v4, 0xffff0000, v163
	v_pk_mul_f32 v[166:167], v[170:171], v[166:167]
	v_add_f32_e32 v157, v145, v4
	v_lshlrev_b32_e32 v4, 16, v164
	v_pk_mul_f32 v[22:23], v[22:23], v[166:167]
	v_add_f32_e32 v167, v138, v4
	v_and_b32_e32 v4, 0xffff0000, v164
	v_add_f32_e32 v169, v139, v4
	v_lshlrev_b32_e32 v4, 16, v165
	v_add_f32_e32 v173, v140, v4
	v_and_b32_e32 v4, 0xffff0000, v165
	v_add_f32_e32 v177, v141, v4
	s_waitcnt vmcnt(0)
; __device__ __forceinline__ float bf_lo(unsigned w) { return __uint_as_float(w << 16); }
; __device__ __forceinline__ float bf_hi(unsigned w) { return __uint_as_float(w & 0xffff0000u); }
;     __device__ __forceinline__ void mid(f32x4 (&acc)[2][2][4][2], const Unit& u, int wr, int wc, int fr, int fq) const {
;     ...
;                 for (int m = 0; m < 4; ++m) { const size_t r = (size_t)(row0 + ai * HALF + m * 16);
;                     const u32x4 ga = *(const u32x4*)(GA + r * ldg + col0 + bj * HALF), gb = *(const u32x4*)(GB + r * ldg + col0 + bj * HALF);
;                     const float xa[8] = {bf_lo(ga.x) + a0[0], bf_hi(ga.x) + a0[1], bf_lo(ga.y) + a0[2], bf_hi(ga.y) + a0[3], bf_lo(ga.z) + a1[0], bf_hi(ga.z) + a1[1], bf_lo(ga.w) + a1[2], bf_hi(ga.w) + a1[3]};
;                     const float xb[8] = {bf_lo(gb.x) + b0[0], bf_hi(gb.x) + b0[1], bf_lo(gb.y) + b0[2], bf_hi(gb.y) + b0[3], bf_lo(gb.z) + b1[0], bf_hi(gb.z) + b1[1], bf_lo(gb.w) + b1[2], bf_hi(gb.w) + b1[3]};
; #pragma unroll
;                     for (int j = 0; j < 4; ++j) { acc[ai][bj][m][0][j] *= (1.0f + __expf(-fmaxf(xb[j], GB_MIN))) * __builtin_amdgcn_rcpf(1.0f + __expf(-xa[j]));
;                         acc[ai][bj][m][1][j] *= (1.0f + __expf(-fmaxf(xb[4 + j], GB_MIN))) * __builtin_amdgcn_rcpf(1.0f + __expf(-xa[4 + j])); }
;                     asm volatile("" ::: "memory"); } }
	v_lshlrev_b32_e32 v4, 16, v158
	v_and_b32_e32 v158, 0xffff0000, v158
	v_lshlrev_b32_e32 v3, 16, v162
	v_add_f32_e32 v171, v147, v158
	v_lshlrev_b32_e32 v158, 16, v159
	global_load_dwordx4 v[162:165], v[182:183], off offset:256
	v_add_f32_e32 v172, v148, v158
	v_and_b32_e32 v158, 0xffff0000, v159
	v_add_f32_e32 v175, v149, v158
	v_lshlrev_b32_e32 v158, 16, v160
	v_add_f32_e32 v168, v134, v158
	v_and_b32_e32 v158, 0xffff0000, v160
	v_add_f32_e32 v174, v135, v158
	v_lshlrev_b32_e32 v158, 16, v161
	v_add_f32_e32 v176, v136, v158
	v_and_b32_e32 v158, 0xffff0000, v161
	v_add_f32_e32 v179, v137, v158
	global_load_dwordx4 v[158:161], v[180:181], off offset:256
	v_add_f32_e32 v3, v142, v3
	v_mul_f32_e32 v3, 0xbfb8aa3b, v3
	v_exp_f32_e32 v3, v3
	v_mul_f32_e32 v157, 0xbfb8aa3b, v157
	v_exp_f32_e32 v157, v157
	v_add_f32_e32 v4, v146, v4
	v_add_f32_e32 v3, 1.0, v3
	v_rcp_f32_e32 v166, v3
	v_mul_f32_e32 v3, 0xbfb8aa3b, v167
	v_exp_f32_e32 v3, v3
	v_max_f32_e32 v167, 0xc2700000, v168
	v_mul_f32_e32 v167, 0xbfb8aa3b, v167
	v_exp_f32_e32 v168, v167
	v_add_f32_e32 v3, 1.0, v3
	v_rcp_f32_e32 v170, v3
	v_mul_f32_e32 v3, 0xbfb8aa3b, v5
	v_exp_f32_e32 v3, v3
	v_max_f32_e32 v5, 0xc2700000, v171
	v_max_f32_e32 v4, 0xc2700000, v4
	v_mul_f32_e32 v4, 0xbfb8aa3b, v4
	v_add_f32_e32 v3, 1.0, v3
	v_rcp_f32_e32 v167, v3
	v_mul_f32_e32 v3, 0xbfb8aa3b, v169
	v_exp_f32_e32 v3, v3
	v_max_f32_e32 v169, 0xc2700000, v174
	v_mul_f32_e32 v5, 0xbfb8aa3b, v5
	v_exp_f32_e32 v4, v4
	v_add_f32_e32 v3, 1.0, v3
	v_rcp_f32_e32 v171, v3
	v_mul_f32_e32 v3, 0xbfb8aa3b, v155
	v_exp_f32_e32 v3, v3
	v_max_f32_e32 v155, 0xc2700000, v172
	v_mul_f32_e32 v155, 0xbfb8aa3b, v155
	v_exp_f32_e32 v172, v155
	v_add_f32_e32 v3, 1.0, v3
	v_rcp_f32_e32 v174, v3
	v_mul_f32_e32 v3, 0xbfb8aa3b, v173
	v_max_f32_e32 v155, 0xc2700000, v176
	v_exp_f32_e32 v3, v3
	v_mul_f32_e32 v155, 0xbfb8aa3b, v155
	v_exp_f32_e32 v176, v155
	v_max_f32_e32 v155, 0xc2700000, v175
	v_mul_f32_e32 v155, 0xbfb8aa3b, v155
	v_exp_f32_e32 v173, v155
	v_mul_f32_e32 v155, 0xbfb8aa3b, v177
	v_add_f32_e32 v3, 1.0, v3
	v_exp_f32_e32 v155, v155
	v_rcp_f32_e32 v178, v3
	v_add_f32_e32 v3, 1.0, v157
	v_exp_f32_e32 v5, v5
	v_rcp_f32_e32 v175, v3
	v_max_f32_e32 v3, 0xc2700000, v179
	v_mul_f32_e32 v3, 0xbfb8aa3b, v3
	v_exp_f32_e32 v177, v3
	v_add_f32_e32 v3, 1.0, v155
	v_rcp_f32_e32 v179, v3
	v_pk_add_f32 v[4:5], v[4:5], 1.0 op_sel_hi:[1,0]
	v_mul_f32_e32 v169, 0xbfb8aa3b, v169
	v_pk_mul_f32 v[4:5], v[166:167], v[4:5]
	v_exp_f32_e32 v169, v169
	v_pk_mul_f32 v[18:19], v[18:19], v[4:5]
	v_pk_add_f32 v[4:5], v[176:177], 1.0 op_sel_hi:[1,0]
	v_pk_add_f32 v[172:173], v[172:173], 1.0 op_sel_hi:[1,0]
	v_pk_mul_f32 v[4:5], v[178:179], v[4:5]
	v_pk_mul_f32 v[166:167], v[174:175], v[172:173]
	v_pk_mul_f32 v[16:17], v[16:17], v[4:5]
	v_pk_mul_f32 v[20:21], v[20:21], v[166:167]
	s_waitcnt vmcnt(1)
	v_and_b32_e32 v4, 0xffff0000, v162
	v_lshlrev_b32_e32 v3, 16, v162
	v_add_f32_e32 v5, v143, v4
	v_lshlrev_b32_e32 v4, 16, v163
	v_add_f32_e32 v3, v142, v3
	v_add_f32_e32 v142, v144, v4
	v_and_b32_e32 v4, 0xffff0000, v163
	v_add_f32_e32 v143, v145, v4
	v_lshlrev_b32_e32 v4, 16, v164
	v_add_f32_e32 v138, v138, v4
	v_and_b32_e32 v4, 0xffff0000, v164
	v_add_f32_e32 v139, v139, v4
	v_lshlrev_b32_e32 v4, 16, v165
	v_mul_f32_e32 v3, 0xbfb8aa3b, v3
	v_add_f32_e32 v144, v140, v4
	s_waitcnt vmcnt(0)
	v_and_b32_e32 v140, 0xffff0000, v158
	v_exp_f32_e32 v3, v3
	v_and_b32_e32 v4, 0xffff0000, v165
	v_add_f32_e32 v140, v147, v140
	v_lshlrev_b32_e32 v147, 16, v160
	v_add_f32_e32 v145, v141, v4
	v_lshlrev_b32_e32 v4, 16, v158
	v_lshlrev_b32_e32 v141, 16, v159
	v_add_f32_e32 v147, v134, v147
	v_and_b32_e32 v134, 0xffff0000, v160
	v_add_f32_e32 v4, v146, v4
	v_add_f32_e32 v141, v148, v141
	v_and_b32_e32 v146, 0xffff0000, v159
	v_add_f32_e32 v148, v135, v134
	v_lshlrev_b32_e32 v134, 16, v161
	v_add_f32_e32 v146, v149, v146
	v_add_f32_e32 v149, v136, v134
	v_and_b32_e32 v134, 0xffff0000, v161
	v_add_f32_e32 v3, 1.0, v3
	v_add_f32_e32 v155, v137, v134
	v_rcp_f32_e32 v134, v3
	v_mul_f32_e32 v3, 0xbfb8aa3b, v138
	v_exp_f32_e32 v3, v3
	v_max_f32_e32 v135, 0xc2700000, v147
	v_mul_f32_e32 v135, 0xbfb8aa3b, v135
	v_exp_f32_e32 v136, v135
	v_add_f32_e32 v3, 1.0, v3
	v_rcp_f32_e32 v138, v3
	v_mul_f32_e32 v3, 0xbfb8aa3b, v5
	v_exp_f32_e32 v3, v3
	v_mul_f32_e32 v143, 0xbfb8aa3b, v143
	v_max_f32_e32 v5, 0xc2700000, v140
	v_max_f32_e32 v140, 0xc2700000, v141
	v_add_f32_e32 v3, 1.0, v3
	v_rcp_f32_e32 v135, v3
	v_mul_f32_e32 v3, 0xbfb8aa3b, v139
	v_exp_f32_e32 v3, v3
	v_max_f32_e32 v141, 0xc2700000, v149
	v_exp_f32_e32 v143, v143
	v_mul_f32_e32 v141, 0xbfb8aa3b, v141
	v_add_f32_e32 v3, 1.0, v3
	v_rcp_f32_e32 v139, v3
	v_mul_f32_e32 v3, 0xbfb8aa3b, v142
	v_exp_f32_e32 v3, v3
	v_max_f32_e32 v4, 0xc2700000, v4
	v_mul_f32_e32 v4, 0xbfb8aa3b, v4
	v_mul_f32_e32 v5, 0xbfb8aa3b, v5
	v_add_f32_e32 v3, 1.0, v3
	v_rcp_f32_e32 v142, v3
	v_mul_f32_e32 v3, 0xbfb8aa3b, v144
	v_exp_f32_e32 v3, v3
	v_exp_f32_e32 v144, v141
	v_max_f32_e32 v141, 0xc2700000, v146
	v_mul_f32_e32 v140, 0xbfb8aa3b, v140
	v_add_f32_e32 v3, 1.0, v3
	v_mul_f32_e32 v141, 0xbfb8aa3b, v141
	v_exp_f32_e32 v4, v4
	v_exp_f32_e32 v5, v5
	v_exp_f32_e32 v140, v140
	v_exp_f32_e32 v141, v141
	v_rcp_f32_e32 v146, v3
	v_add_f32_e32 v3, 1.0, v143
	v_rcp_f32_e32 v143, v3
	v_pk_add_f32 v[140:141], v[140:141], 1.0 op_sel_hi:[1,0]
	v_pk_add_f32 v[4:5], v[4:5], 1.0 op_sel_hi:[1,0]
	v_max_f32_e32 v137, 0xc2700000, v148
	v_pk_mul_f32 v[4:5], v[134:135], v[4:5]
	v_pk_mul_f32 v[134:135], v[142:143], v[140:141]
	v_max_f32_e32 v3, 0xc2700000, v155
	v_pk_mul_f32 v[12:13], v[12:13], v[134:135]
	v_mul_f32_e32 v134, 0xbfb8aa3b, v145
	v_exp_f32_e32 v134, v134
	v_mul_f32_e32 v137, 0xbfb8aa3b, v137
	v_mul_f32_e32 v3, 0xbfb8aa3b, v3
	v_exp_f32_e32 v137, v137
	v_exp_f32_e32 v145, v3
	v_add_f32_e32 v3, 1.0, v134
	v_rcp_f32_e32 v147, v3
	v_pk_add_f32 v[166:167], v[168:169], 1.0 op_sel_hi:[1,0]
	v_pk_mul_f32 v[10:11], v[10:11], v[4:5]
	v_pk_add_f32 v[4:5], v[144:145], 1.0 op_sel_hi:[1,0]
	v_pk_add_f32 v[134:135], v[136:137], 1.0 op_sel_hi:[1,0]
	v_pk_mul_f32 v[166:167], v[170:171], v[166:167]
	v_pk_mul_f32 v[134:135], v[138:139], v[134:135]
	v_pk_mul_f32 v[4:5], v[146:147], v[4:5]
	v_pk_mul_f32 v[14:15], v[14:15], v[166:167]
	v_pk_mul_f32 v[8:9], v[8:9], v[4:5]
	v_pk_mul_f32 v[6:7], v[6:7], v[134:135]

; __device__ __forceinline__ unsigned cvt_pk_bf16(float lo, float hi) { unsigned r; asm volatile("v_cvt_pk_bf16_f32 %0, %1, %2" : "=v"(r) : "v"(lo), "v"(hi)); return r; }
; __device__ __forceinline__ float bf_lo(unsigned w) { return __uint_as_float(w << 16); }
; __device__ __forceinline__ float bf_hi(unsigned w) { return __uint_as_float(w & 0xffff0000u); }
; __device__ __forceinline__ float sigmoid_f(float x) { return __builtin_amdgcn_rcpf(1.0f + __expf(-x)); }
;     __device__ __forceinline__ void operator()(const f32x4 (&acc)[2][2][4][2], const Unit& u, int wr, int wc, int fr, int fq) const {
;         const int row0 = u.pm * BM + wr * 64 + fr, col0 = u.pn * BM + wc * 32 + 8 * fq;
; #pragma unroll
;         for (int bj = 0; bj < 2; ++bj) { const f32x4 b0 = *(const f32x4*)(bias + nb + col0 + bj * HALF), b1 = *(const f32x4*)(bias + nb + col0 + bj * HALF + 4);
; #pragma unroll
;             for (int ai = 0; ai < 2; ++ai)
; #pragma unroll
;                 for (int m = 0; m < 4; ++m) { const size_t r = (size_t)(row0 + ai * HALF + m * 16);
;                     const u32x4 g = *(const u32x4*)(GB + r * ldg + col0 + bj * HALF);
;                     f32x4 s0, s1;
;                     s0[0] = sigmoid_f(fmaxf(bf_lo(g.x) + b0[0], GB_MIN)); s0[1] = sigmoid_f(fmaxf(bf_hi(g.x) + b0[1], GB_MIN)); s0[2] = sigmoid_f(fmaxf(bf_lo(g.y) + b0[2], GB_MIN)); s0[3] = sigmoid_f(fmaxf(bf_hi(g.y) + b0[3], GB_MIN));
;                     s1[0] = sigmoid_f(fmaxf(bf_lo(g.z) + b1[0], GB_MIN)); s1[1] = sigmoid_f(fmaxf(bf_hi(g.z) + b1[1], GB_MIN)); s1[2] = sigmoid_f(fmaxf(bf_lo(g.w) + b1[2], GB_MIN)); s1[3] = sigmoid_f(fmaxf(bf_hi(g.w) + b1[3], GB_MIN));
;                     const f32x4 v0 = s0 * acc[ai][bj][m][0], v1 = s1 * acc[ai][bj][m][1];
;                     u32x4 w; w.x = cvt_pk_bf16(v0[0], v0[1]); w.y = cvt_pk_bf16(v0[2], v0[3]); w.z = cvt_pk_bf16(v1[0], v1[1]); w.w = cvt_pk_bf16(v1[2], v1[3]);
;                     *(u32x4*)(O + r * ldc + col0 + bj * HALF) = w; } }
.LBB0_624:
	v_ashrrev_i32_e32 v157, 31, v156
	v_mov_b64_e32 v[158:159], s[12:13]
	v_mad_i64_i32 v[4:5], s[42:43], v154, s81, v[158:159]
	v_lshlrev_b64 v[146:147], 1, v[156:157]
	v_lshl_add_u64 v[148:149], v[4:5], 0, v[146:147]
	global_load_dwordx4 v[160:163], v[148:149], off
	v_lshl_add_u64 v[144:145], v[156:157], 2, s[16:17]
	global_load_dwordx4 v[138:141], v[144:145], off
	global_load_dwordx4 v[134:137], v[144:145], off offset:16
	v_mov_b32_e32 v231, 0
	global_load_dword v232, v[148:149], off offset:256
	v_mov_b32_e32 v230, 0xa0000
	v_lshl_add_u64 v[228:229], v[148:149], 0, v[230:231]
	global_load_dword v232, v[228:229], off
	global_load_dword v232, v[228:229], off offset:256
	v_mov_b32_e32 v230, 0x140000
	v_lshl_add_u64 v[228:229], v[148:149], 0, v[230:231]
	global_load_dword v232, v[228:229], off
	global_load_dword v232, v[228:229], off offset:256
	v_mov_b32_e32 v230, 0x1e0000
	v_lshl_add_u64 v[228:229], v[148:149], 0, v[230:231]
	global_load_dword v232, v[228:229], off
	global_load_dword v232, v[228:229], off offset:256
	v_mov_b32_e32 v230, 0x500000
	v_lshl_add_u64 v[228:229], v[148:149], 0, v[230:231]
	global_load_dword v232, v[228:229], off
	global_load_dword v232, v[228:229], off offset:256
	v_mov_b32_e32 v230, 0x5a0000
	v_lshl_add_u64 v[228:229], v[148:149], 0, v[230:231]
	global_load_dword v232, v[228:229], off
	global_load_dword v232, v[228:229], off offset:256
	v_mov_b32_e32 v230, 0x640000
	v_lshl_add_u64 v[228:229], v[148:149], 0, v[230:231]
	global_load_dword v232, v[228:229], off
	global_load_dword v232, v[228:229], off offset:256
	v_mov_b32_e32 v230, 0x6e0000
	v_lshl_add_u64 v[228:229], v[148:149], 0, v[230:231]
	global_load_dword v232, v[228:229], off
	global_load_dword v232, v[228:229], off offset:256
	v_ashrrev_i32_e32 v155, 31, v154
	v_or_b32_e32 v156, 16, v154
	v_lshlrev_b64 v[4:5], 13, v[154:155]
	v_mad_i64_i32 v[142:143], s[42:43], v156, s81, v[158:159]
	v_lshl_add_u64 v[164:165], s[6:7], 0, v[4:5]
	v_lshl_add_u64 v[4:5], v[142:143], 0, v[146:147]
	v_lshl_add_u64 v[142:143], v[164:165], 0, v[146:147]
	s_andn2_b64 vcc, exec, s[0:1]
	s_mov_b64 s[0:1], -1
	s_waitcnt vmcnt(17)
	v_lshlrev_b32_e32 v3, 16, v160
	v_and_b32_e32 v155, 0xffff0000, v160
	v_lshlrev_b32_e32 v157, 16, v161
	v_and_b32_e32 v160, 0xffff0000, v161
	v_lshlrev_b32_e32 v161, 16, v162
	v_and_b32_e32 v162, 0xffff0000, v162
	v_lshlrev_b32_e32 v164, 16, v163
	v_and_b32_e32 v163, 0xffff0000, v163
	s_waitcnt vmcnt(16)
	v_add_f32_e32 v3, v138, v3
	v_add_f32_e32 v155, v139, v155
	v_add_f32_e32 v160, v141, v160
	s_waitcnt vmcnt(15)
	v_add_f32_e32 v161, v134, v161
	v_add_f32_e32 v162, v135, v162
	v_add_f32_e32 v164, v136, v164
	v_add_f32_e32 v163, v137, v163
	v_add_f32_e32 v157, v140, v157
	v_max_f32_e32 v3, 0xc2700000, v3
	v_max_f32_e32 v155, 0xc2700000, v155
	v_max_f32_e32 v160, 0xc2700000, v160
	v_max_f32_e32 v161, 0xc2700000, v161
	v_max_f32_e32 v162, 0xc2700000, v162
	v_max_f32_e32 v164, 0xc2700000, v164
	v_max_f32_e32 v163, 0xc2700000, v163
	v_max_f32_e32 v157, 0xc2700000, v157
	v_mul_f32_e32 v3, 0xbfb8aa3b, v3
	v_mul_f32_e32 v155, 0xbfb8aa3b, v155
	v_mul_f32_e32 v160, 0xbfb8aa3b, v160
	v_mul_f32_e32 v161, 0xbfb8aa3b, v161
	v_mul_f32_e32 v162, 0xbfb8aa3b, v162
	v_mul_f32_e32 v164, 0xbfb8aa3b, v164
	v_mul_f32_e32 v163, 0xbfb8aa3b, v163
	v_mul_f32_e32 v157, 0xbfb8aa3b, v157
	v_exp_f32_e32 v3, v3
	v_exp_f32_e32 v155, v155
	v_exp_f32_e32 v160, v160
	v_exp_f32_e32 v161, v161
	v_exp_f32_e32 v162, v162
	v_exp_f32_e32 v164, v164
	v_exp_f32_e32 v163, v163
	v_exp_f32_e32 v157, v157
	v_add_f32_e32 v3, 1.0, v3
	v_add_f32_e32 v155, 1.0, v155
	v_add_f32_e32 v165, 1.0, v160
	v_add_f32_e32 v166, 1.0, v161
	v_add_f32_e32 v168, 1.0, v162
	v_add_f32_e32 v167, 1.0, v164
	v_add_f32_e32 v169, 1.0, v163
	v_add_f32_e32 v157, 1.0, v157
	v_rcp_f32_e32 v160, v3
	v_rcp_f32_e32 v161, v155
	v_rcp_f32_e32 v163, v165
	v_rcp_f32_e32 v164, v166
	v_rcp_f32_e32 v166, v167
	v_rcp_f32_e32 v167, v169
	v_rcp_f32_e32 v165, v168
	v_rcp_f32_e32 v162, v157
	v_pk_mul_f32 v[130:131], v[130:131], v[160:161]
	v_pk_mul_f32 v[160:161], v[128:129], v[166:167]
	v_pk_mul_f32 v[128:129], v[126:127], v[164:165]
	v_pk_mul_f32 v[132:133], v[132:133], v[162:163]
	v_cvt_pk_bf16_f32 v126, v130, v131
	v_ashrrev_i32_e32 v157, 31, v156
	v_cvt_pk_bf16_f32 v127, v132, v133
	v_cvt_pk_bf16_f32 v128, v128, v129
	v_cvt_pk_bf16_f32 v129, v160, v161
	global_store_dwordx4 v[142:143], v[126:129], off
	global_load_dwordx4 v[130:133], v[4:5], off
	v_or_b32_e32 v160, 32, v154
	v_lshlrev_b64 v[128:129], 13, v[156:157]
	v_lshl_add_u64 v[128:129], s[6:7], 0, v[128:129]
	v_mad_i64_i32 v[126:127], s[42:43], v160, s81, v[158:159]
	v_lshl_add_u64 v[128:129], v[128:129], 0, v[146:147]
	v_lshl_add_u64 v[126:127], v[126:127], 0, v[146:147]
	s_waitcnt vmcnt(0)
; __device__ __forceinline__ unsigned cvt_pk_bf16(float lo, float hi) { unsigned r; asm volatile("v_cvt_pk_bf16_f32 %0, %1, %2" : "=v"(r) : "v"(lo), "v"(hi)); return r; }
; __device__ __forceinline__ float bf_lo(unsigned w) { return __uint_as_float(w << 16); }
; __device__ __forceinline__ float bf_hi(unsigned w) { return __uint_as_float(w & 0xffff0000u); }
; __device__ __forceinline__ float sigmoid_f(float x) { return __builtin_amdgcn_rcpf(1.0f + __expf(-x)); }
;     __device__ __forceinline__ void operator()(const f32x4 (&acc)[2][2][4][2], const Unit& u, int wr, int wc, int fr, int fq) const {
;     ...
;                 for (int m = 0; m < 4; ++m) { const size_t r = (size_t)(row0 + ai * HALF + m * 16);
;                     const u32x4 g = *(const u32x4*)(GB + r * ldg + col0 + bj * HALF);
;                     f32x4 s0, s1;
;                     s0[0] = sigmoid_f(fmaxf(bf_lo(g.x) + b0[0], GB_MIN)); s0[1] = sigmoid_f(fmaxf(bf_hi(g.x) + b0[1], GB_MIN)); s0[2] = sigmoid_f(fmaxf(bf_lo(g.y) + b0[2], GB_MIN)); s0[3] = sigmoid_f(fmaxf(bf_hi(g.y) + b0[3], GB_MIN));
;                     s1[0] = sigmoid_f(fmaxf(bf_lo(g.z) + b1[0], GB_MIN)); s1[1] = sigmoid_f(fmaxf(bf_hi(g.z) + b1[1], GB_MIN)); s1[2] = sigmoid_f(fmaxf(bf_lo(g.w) + b1[2], GB_MIN)); s1[3] = sigmoid_f(fmaxf(bf_hi(g.w) + b1[3], GB_MIN));
;                     const f32x4 v0 = s0 * acc[ai][bj][m][0], v1 = s1 * acc[ai][bj][m][1];
;                     u32x4 w; w.x = cvt_pk_bf16(v0[0], v0[1]); w.y = cvt_pk_bf16(v0[2], v0[3]); w.z = cvt_pk_bf16(v1[0], v1[1]); w.w = cvt_pk_bf16(v1[2], v1[3]);
;                     *(u32x4*)(O + r * ldc + col0 + bj * HALF) = w; } }
	v_lshlrev_b32_e32 v3, 16, v130
	v_and_b32_e32 v130, 0xffff0000, v130
	v_lshlrev_b32_e32 v155, 16, v131
	v_and_b32_e32 v131, 0xffff0000, v131
	v_lshlrev_b32_e32 v156, 16, v132
	v_and_b32_e32 v132, 0xffff0000, v132
	v_lshlrev_b32_e32 v157, 16, v133
	v_and_b32_e32 v133, 0xffff0000, v133
	v_add_f32_e32 v3, v138, v3
	v_add_f32_e32 v130, v139, v130
	v_add_f32_e32 v131, v141, v131
	v_add_f32_e32 v156, v134, v156
	v_add_f32_e32 v132, v135, v132
	v_add_f32_e32 v157, v136, v157
	v_add_f32_e32 v133, v137, v133
	v_add_f32_e32 v155, v140, v155
	v_max_f32_e32 v3, 0xc2700000, v3
	v_max_f32_e32 v130, 0xc2700000, v130
	v_max_f32_e32 v131, 0xc2700000, v131
	v_max_f32_e32 v156, 0xc2700000, v156
	v_max_f32_e32 v132, 0xc2700000, v132
	v_max_f32_e32 v157, 0xc2700000, v157
	v_max_f32_e32 v133, 0xc2700000, v133
	v_max_f32_e32 v155, 0xc2700000, v155
	v_mul_f32_e32 v3, 0xbfb8aa3b, v3
	v_mul_f32_e32 v130, 0xbfb8aa3b, v130
	v_mul_f32_e32 v131, 0xbfb8aa3b, v131
	v_mul_f32_e32 v156, 0xbfb8aa3b, v156
	v_mul_f32_e32 v132, 0xbfb8aa3b, v132
	v_mul_f32_e32 v157, 0xbfb8aa3b, v157
	v_mul_f32_e32 v133, 0xbfb8aa3b, v133
	v_mul_f32_e32 v155, 0xbfb8aa3b, v155
	v_exp_f32_e32 v3, v3
	v_exp_f32_e32 v130, v130
	v_exp_f32_e32 v131, v131
	v_exp_f32_e32 v156, v156
	v_exp_f32_e32 v132, v132
	v_exp_f32_e32 v157, v157
	v_exp_f32_e32 v133, v133
	v_exp_f32_e32 v155, v155
	v_add_f32_e32 v3, 1.0, v3
	v_add_f32_e32 v161, 1.0, v130
	v_add_f32_e32 v162, 1.0, v131
	v_add_f32_e32 v156, 1.0, v156
	v_add_f32_e32 v164, 1.0, v132
	v_add_f32_e32 v157, 1.0, v157
	v_add_f32_e32 v163, 1.0, v133
	v_add_f32_e32 v155, 1.0, v155
	v_rcp_f32_e32 v130, v3
	v_rcp_f32_e32 v131, v161
	v_rcp_f32_e32 v133, v162
	v_rcp_f32_e32 v156, v156
	v_rcp_f32_e32 v162, v157
	v_rcp_f32_e32 v163, v163
	v_rcp_f32_e32 v157, v164
	v_rcp_f32_e32 v132, v155
	v_pk_mul_f32 v[122:123], v[122:123], v[130:131]
	v_pk_mul_f32 v[130:131], v[120:121], v[162:163]
	v_pk_mul_f32 v[120:121], v[118:119], v[156:157]
	v_pk_mul_f32 v[124:125], v[124:125], v[132:133]
	v_cvt_pk_bf16_f32 v118, v122, v123
	v_ashrrev_i32_e32 v161, 31, v160
	v_cvt_pk_bf16_f32 v119, v124, v125
	v_cvt_pk_bf16_f32 v120, v120, v121
	v_cvt_pk_bf16_f32 v121, v130, v131
	global_store_dwordx4 v[128:129], v[118:121], off
	global_load_dwordx4 v[122:125], v[126:127], off
	v_or_b32_e32 v130, 48, v154
	v_lshlrev_b64 v[120:121], 13, v[160:161]
	v_lshl_add_u64 v[120:121], s[6:7], 0, v[120:121]
	v_mad_i64_i32 v[118:119], s[42:43], v130, s81, v[158:159]
	v_lshl_add_u64 v[120:121], v[120:121], 0, v[146:147]
	v_lshl_add_u64 v[118:119], v[118:119], 0, v[146:147]
	s_waitcnt vmcnt(0)
	v_lshlrev_b32_e32 v3, 16, v122
	v_and_b32_e32 v122, 0xffff0000, v122
	v_lshlrev_b32_e32 v131, 16, v123
	v_and_b32_e32 v123, 0xffff0000, v123
	v_lshlrev_b32_e32 v132, 16, v124
	v_and_b32_e32 v124, 0xffff0000, v124
	v_lshlrev_b32_e32 v133, 16, v125
	v_and_b32_e32 v125, 0xffff0000, v125
	v_add_f32_e32 v3, v138, v3
	v_add_f32_e32 v122, v139, v122
	v_add_f32_e32 v123, v141, v123
	v_add_f32_e32 v132, v134, v132
	v_add_f32_e32 v124, v135, v124
	v_add_f32_e32 v133, v136, v133
	v_add_f32_e32 v125, v137, v125
	v_add_f32_e32 v131, v140, v131
	v_max_f32_e32 v3, 0xc2700000, v3
	v_max_f32_e32 v122, 0xc2700000, v122
	v_max_f32_e32 v123, 0xc2700000, v123
	v_max_f32_e32 v132, 0xc2700000, v132
	v_max_f32_e32 v124, 0xc2700000, v124
	v_max_f32_e32 v133, 0xc2700000, v133
	v_max_f32_e32 v125, 0xc2700000, v125
	v_max_f32_e32 v131, 0xc2700000, v131
	v_mul_f32_e32 v3, 0xbfb8aa3b, v3
	v_mul_f32_e32 v122, 0xbfb8aa3b, v122
	v_mul_f32_e32 v123, 0xbfb8aa3b, v123
	v_mul_f32_e32 v132, 0xbfb8aa3b, v132
	v_mul_f32_e32 v124, 0xbfb8aa3b, v124
	v_mul_f32_e32 v133, 0xbfb8aa3b, v133
	v_mul_f32_e32 v125, 0xbfb8aa3b, v125
	v_mul_f32_e32 v131, 0xbfb8aa3b, v131
	v_exp_f32_e32 v3, v3
	v_exp_f32_e32 v122, v122
	v_exp_f32_e32 v123, v123
	v_exp_f32_e32 v132, v132
	v_exp_f32_e32 v124, v124
	v_exp_f32_e32 v133, v133
	v_exp_f32_e32 v125, v125
	v_exp_f32_e32 v131, v131
	v_add_f32_e32 v3, 1.0, v3
	v_add_f32_e32 v155, 1.0, v122
	v_add_f32_e32 v156, 1.0, v123
	v_add_f32_e32 v132, 1.0, v132
	v_add_f32_e32 v160, 1.0, v124
	v_add_f32_e32 v133, 1.0, v133
	v_add_f32_e32 v157, 1.0, v125
	v_add_f32_e32 v131, 1.0, v131
	v_rcp_f32_e32 v122, v3
	v_rcp_f32_e32 v123, v155
	v_rcp_f32_e32 v125, v156
	v_rcp_f32_e32 v132, v132
	v_rcp_f32_e32 v156, v133
	v_rcp_f32_e32 v157, v157
	v_rcp_f32_e32 v133, v160
	v_rcp_f32_e32 v124, v131
	v_pk_mul_f32 v[114:115], v[114:115], v[122:123]
	v_pk_mul_f32 v[122:123], v[112:113], v[156:157]
	v_pk_mul_f32 v[112:113], v[110:111], v[132:133]
	v_pk_mul_f32 v[116:117], v[116:117], v[124:125]
	v_cvt_pk_bf16_f32 v110, v114, v115
	v_ashrrev_i32_e32 v131, 31, v130
	v_cvt_pk_bf16_f32 v111, v116, v117
	v_cvt_pk_bf16_f32 v112, v112, v113
	v_cvt_pk_bf16_f32 v113, v122, v123
	global_store_dwordx4 v[120:121], v[110:113], off
	global_load_dwordx4 v[122:125], v[118:119], off
	v_add_u32_e32 v114, 0x80, v154
	v_lshlrev_b64 v[112:113], 13, v[130:131]
	v_lshl_add_u64 v[112:113], s[6:7], 0, v[112:113]
	v_mad_i64_i32 v[110:111], s[42:43], v114, s81, v[158:159]
	v_lshl_add_u64 v[112:113], v[112:113], 0, v[146:147]
	v_lshl_add_u64 v[110:111], v[110:111], 0, v[146:147]
	s_waitcnt vmcnt(0)
; __device__ __forceinline__ unsigned cvt_pk_bf16(float lo, float hi) { unsigned r; asm volatile("v_cvt_pk_bf16_f32 %0, %1, %2" : "=v"(r) : "v"(lo), "v"(hi)); return r; }
; __device__ __forceinline__ float bf_lo(unsigned w) { return __uint_as_float(w << 16); }
; __device__ __forceinline__ float bf_hi(unsigned w) { return __uint_as_float(w & 0xffff0000u); }
; __device__ __forceinline__ float sigmoid_f(float x) { return __builtin_amdgcn_rcpf(1.0f + __expf(-x)); }
;     __device__ __forceinline__ void operator()(const f32x4 (&acc)[2][2][4][2], const Unit& u, int wr, int wc, int fr, int fq) const {
;     ...
;                 for (int m = 0; m < 4; ++m) { const size_t r = (size_t)(row0 + ai * HALF + m * 16);
;                     const u32x4 g = *(const u32x4*)(GB + r * ldg + col0 + bj * HALF);
;                     f32x4 s0, s1;
;                     s0[0] = sigmoid_f(fmaxf(bf_lo(g.x) + b0[0], GB_MIN)); s0[1] = sigmoid_f(fmaxf(bf_hi(g.x) + b0[1], GB_MIN)); s0[2] = sigmoid_f(fmaxf(bf_lo(g.y) + b0[2], GB_MIN)); s0[3] = sigmoid_f(fmaxf(bf_hi(g.y) + b0[3], GB_MIN));
;                     s1[0] = sigmoid_f(fmaxf(bf_lo(g.z) + b1[0], GB_MIN)); s1[1] = sigmoid_f(fmaxf(bf_hi(g.z) + b1[1], GB_MIN)); s1[2] = sigmoid_f(fmaxf(bf_lo(g.w) + b1[2], GB_MIN)); s1[3] = sigmoid_f(fmaxf(bf_hi(g.w) + b1[3], GB_MIN));
;                     const f32x4 v0 = s0 * acc[ai][bj][m][0], v1 = s1 * acc[ai][bj][m][1];
;                     u32x4 w; w.x = cvt_pk_bf16(v0[0], v0[1]); w.y = cvt_pk_bf16(v0[2], v0[3]); w.z = cvt_pk_bf16(v1[0], v1[1]); w.w = cvt_pk_bf16(v1[2], v1[3]);
;                     *(u32x4*)(O + r * ldc + col0 + bj * HALF) = w; } }
	v_lshlrev_b32_e32 v3, 16, v122
	v_and_b32_e32 v115, 0xffff0000, v122
	v_lshlrev_b32_e32 v116, 16, v123
	v_and_b32_e32 v117, 0xffff0000, v123
	v_lshlrev_b32_e32 v122, 16, v124
	v_and_b32_e32 v123, 0xffff0000, v124
	v_lshlrev_b32_e32 v124, 16, v125
	v_and_b32_e32 v125, 0xffff0000, v125
	v_add_f32_e32 v3, v138, v3
	v_add_f32_e32 v115, v139, v115
	v_add_f32_e32 v116, v140, v116
	v_add_f32_e32 v117, v141, v117
	v_add_f32_e32 v122, v134, v122
	v_add_f32_e32 v123, v135, v123
	v_add_f32_e32 v124, v136, v124
	v_add_f32_e32 v125, v137, v125
	v_max_f32_e32 v3, 0xc2700000, v3
	v_max_f32_e32 v115, 0xc2700000, v115
	v_max_f32_e32 v116, 0xc2700000, v116
	v_max_f32_e32 v117, 0xc2700000, v117
	v_max_f32_e32 v122, 0xc2700000, v122
	v_max_f32_e32 v123, 0xc2700000, v123
	v_max_f32_e32 v124, 0xc2700000, v124
	v_max_f32_e32 v125, 0xc2700000, v125
	v_mul_f32_e32 v3, 0xbfb8aa3b, v3
	v_mul_f32_e32 v115, 0xbfb8aa3b, v115
	v_mul_f32_e32 v116, 0xbfb8aa3b, v116
	v_mul_f32_e32 v117, 0xbfb8aa3b, v117
	v_mul_f32_e32 v122, 0xbfb8aa3b, v122
	v_mul_f32_e32 v123, 0xbfb8aa3b, v123
	v_mul_f32_e32 v124, 0xbfb8aa3b, v124
	v_mul_f32_e32 v125, 0xbfb8aa3b, v125
	v_exp_f32_e32 v3, v3
	v_exp_f32_e32 v115, v115
	v_exp_f32_e32 v116, v116
	v_exp_f32_e32 v117, v117
	v_exp_f32_e32 v122, v122
	v_exp_f32_e32 v123, v123
	v_exp_f32_e32 v124, v124
	v_exp_f32_e32 v125, v125
	v_add_f32_e32 v3, 1.0, v3
	v_add_f32_e32 v115, 1.0, v115
	v_add_f32_e32 v130, 1.0, v116
	v_add_f32_e32 v131, 1.0, v117
	v_add_f32_e32 v132, 1.0, v122
	v_add_f32_e32 v133, 1.0, v123
	v_add_f32_e32 v155, 1.0, v124
	v_add_f32_e32 v125, 1.0, v125
	v_rcp_f32_e32 v116, v3
	v_rcp_f32_e32 v117, v115
	v_rcp_f32_e32 v122, v130
	v_rcp_f32_e32 v123, v131
	v_rcp_f32_e32 v124, v132
	v_rcp_f32_e32 v130, v155
	v_rcp_f32_e32 v131, v125
	v_rcp_f32_e32 v125, v133
	v_pk_mul_f32 v[106:107], v[106:107], v[116:117]
	v_pk_mul_f32 v[108:109], v[108:109], v[122:123]
	v_pk_mul_f32 v[116:117], v[104:105], v[130:131]
	v_pk_mul_f32 v[104:105], v[102:103], v[124:125]
	v_cvt_pk_bf16_f32 v102, v106, v107
	v_cvt_pk_bf16_f32 v103, v108, v109
	v_ashrrev_i32_e32 v115, 31, v114
	v_cvt_pk_bf16_f32 v104, v104, v105
	v_cvt_pk_bf16_f32 v105, v116, v117
	global_store_dwordx4 v[112:113], v[102:105], off
	global_load_dwordx4 v[106:109], v[110:111], off
	v_add_u32_e32 v116, 0x90, v154
	v_lshlrev_b64 v[104:105], 13, v[114:115]
	v_lshl_add_u64 v[104:105], s[6:7], 0, v[104:105]
	v_mad_i64_i32 v[102:103], s[42:43], v116, s81, v[158:159]
	v_lshl_add_u64 v[104:105], v[104:105], 0, v[146:147]
	v_lshl_add_u64 v[102:103], v[102:103], 0, v[146:147]
	s_waitcnt vmcnt(0)
	v_lshlrev_b32_e32 v3, 16, v106
	v_and_b32_e32 v106, 0xffff0000, v106
	v_lshlrev_b32_e32 v114, 16, v107
	v_and_b32_e32 v107, 0xffff0000, v107
	v_lshlrev_b32_e32 v115, 16, v108
	v_and_b32_e32 v108, 0xffff0000, v108
	v_lshlrev_b32_e32 v117, 16, v109
	v_and_b32_e32 v109, 0xffff0000, v109
	v_add_f32_e32 v3, v138, v3
	v_add_f32_e32 v106, v139, v106
	v_add_f32_e32 v114, v140, v114
	v_add_f32_e32 v107, v141, v107
	v_add_f32_e32 v115, v134, v115
	v_add_f32_e32 v108, v135, v108
	v_add_f32_e32 v117, v136, v117
	v_add_f32_e32 v109, v137, v109
	v_max_f32_e32 v3, 0xc2700000, v3
	v_max_f32_e32 v106, 0xc2700000, v106
	v_max_f32_e32 v114, 0xc2700000, v114
	v_max_f32_e32 v107, 0xc2700000, v107
	v_max_f32_e32 v115, 0xc2700000, v115
	v_max_f32_e32 v108, 0xc2700000, v108
	v_max_f32_e32 v117, 0xc2700000, v117
	v_max_f32_e32 v109, 0xc2700000, v109
	v_mul_f32_e32 v3, 0xbfb8aa3b, v3
	v_mul_f32_e32 v106, 0xbfb8aa3b, v106
	v_mul_f32_e32 v114, 0xbfb8aa3b, v114
	v_mul_f32_e32 v107, 0xbfb8aa3b, v107
	v_mul_f32_e32 v115, 0xbfb8aa3b, v115
	v_mul_f32_e32 v108, 0xbfb8aa3b, v108
	v_mul_f32_e32 v117, 0xbfb8aa3b, v117
	v_mul_f32_e32 v109, 0xbfb8aa3b, v109
	v_exp_f32_e32 v3, v3
	v_exp_f32_e32 v106, v106
	v_exp_f32_e32 v114, v114
	v_exp_f32_e32 v107, v107
	v_exp_f32_e32 v115, v115
	v_exp_f32_e32 v108, v108
	v_exp_f32_e32 v117, v117
	v_exp_f32_e32 v109, v109
	v_add_f32_e32 v3, 1.0, v3
	v_add_f32_e32 v122, 1.0, v106
	v_add_f32_e32 v114, 1.0, v114
	v_add_f32_e32 v123, 1.0, v107
	v_add_f32_e32 v115, 1.0, v115
	v_add_f32_e32 v124, 1.0, v108
	v_add_f32_e32 v117, 1.0, v117
	v_add_f32_e32 v125, 1.0, v109
	v_rcp_f32_e32 v106, v3
	v_rcp_f32_e32 v107, v122
	v_rcp_f32_e32 v108, v114
	v_rcp_f32_e32 v109, v123
	v_rcp_f32_e32 v114, v115
	v_rcp_f32_e32 v122, v117
	v_rcp_f32_e32 v123, v125
	v_rcp_f32_e32 v115, v124
	v_pk_mul_f32 v[98:99], v[98:99], v[106:107]
	v_pk_mul_f32 v[100:101], v[100:101], v[108:109]
	v_pk_mul_f32 v[106:107], v[96:97], v[122:123]
	v_pk_mul_f32 v[96:97], v[94:95], v[114:115]
	v_cvt_pk_bf16_f32 v94, v98, v99
	v_cvt_pk_bf16_f32 v95, v100, v101
	v_ashrrev_i32_e32 v117, 31, v116
	v_cvt_pk_bf16_f32 v96, v96, v97
	v_cvt_pk_bf16_f32 v97, v106, v107
	global_store_dwordx4 v[104:105], v[94:97], off
	global_load_dwordx4 v[98:101], v[102:103], off
	v_add_u32_e32 v106, 0xa0, v154
	v_lshlrev_b64 v[96:97], 13, v[116:117]
	v_lshl_add_u64 v[96:97], s[6:7], 0, v[96:97]
	v_mad_i64_i32 v[94:95], s[42:43], v106, s81, v[158:159]
	v_lshl_add_u64 v[96:97], v[96:97], 0, v[146:147]
	v_lshl_add_u64 v[94:95], v[94:95], 0, v[146:147]
	s_waitcnt vmcnt(0)
; __device__ __forceinline__ unsigned cvt_pk_bf16(float lo, float hi) { unsigned r; asm volatile("v_cvt_pk_bf16_f32 %0, %1, %2" : "=v"(r) : "v"(lo), "v"(hi)); return r; }
; __device__ __forceinline__ float bf_lo(unsigned w) { return __uint_as_float(w << 16); }
; __device__ __forceinline__ float bf_hi(unsigned w) { return __uint_as_float(w & 0xffff0000u); }
; __device__ __forceinline__ float sigmoid_f(float x) { return __builtin_amdgcn_rcpf(1.0f + __expf(-x)); }
;     __device__ __forceinline__ void operator()(const f32x4 (&acc)[2][2][4][2], const Unit& u, int wr, int wc, int fr, int fq) const {
;     ...
;                 for (int m = 0; m < 4; ++m) { const size_t r = (size_t)(row0 + ai * HALF + m * 16);
;                     const u32x4 g = *(const u32x4*)(GB + r * ldg + col0 + bj * HALF);
;                     f32x4 s0, s1;
;                     s0[0] = sigmoid_f(fmaxf(bf_lo(g.x) + b0[0], GB_MIN)); s0[1] = sigmoid_f(fmaxf(bf_hi(g.x) + b0[1], GB_MIN)); s0[2] = sigmoid_f(fmaxf(bf_lo(g.y) + b0[2], GB_MIN)); s0[3] = sigmoid_f(fmaxf(bf_hi(g.y) + b0[3], GB_MIN));
;                     s1[0] = sigmoid_f(fmaxf(bf_lo(g.z) + b1[0], GB_MIN)); s1[1] = sigmoid_f(fmaxf(bf_hi(g.z) + b1[1], GB_MIN)); s1[2] = sigmoid_f(fmaxf(bf_lo(g.w) + b1[2], GB_MIN)); s1[3] = sigmoid_f(fmaxf(bf_hi(g.w) + b1[3], GB_MIN));
;                     const f32x4 v0 = s0 * acc[ai][bj][m][0], v1 = s1 * acc[ai][bj][m][1];
;                     u32x4 w; w.x = cvt_pk_bf16(v0[0], v0[1]); w.y = cvt_pk_bf16(v0[2], v0[3]); w.z = cvt_pk_bf16(v1[0], v1[1]); w.w = cvt_pk_bf16(v1[2], v1[3]);
;                     *(u32x4*)(O + r * ldc + col0 + bj * HALF) = w; } }
	v_lshlrev_b32_e32 v3, 16, v98
	v_and_b32_e32 v98, 0xffff0000, v98
	v_lshlrev_b32_e32 v107, 16, v99
	v_and_b32_e32 v99, 0xffff0000, v99
	v_lshlrev_b32_e32 v108, 16, v100
	v_and_b32_e32 v100, 0xffff0000, v100
	v_lshlrev_b32_e32 v109, 16, v101
	v_and_b32_e32 v101, 0xffff0000, v101
	v_add_f32_e32 v3, v138, v3
	v_add_f32_e32 v98, v139, v98
	v_add_f32_e32 v99, v141, v99
	v_add_f32_e32 v108, v134, v108
	v_add_f32_e32 v100, v135, v100
	v_add_f32_e32 v109, v136, v109
	v_add_f32_e32 v101, v137, v101
	v_add_f32_e32 v107, v140, v107
	v_max_f32_e32 v3, 0xc2700000, v3
	v_max_f32_e32 v98, 0xc2700000, v98
	v_max_f32_e32 v99, 0xc2700000, v99
	v_max_f32_e32 v108, 0xc2700000, v108
	v_max_f32_e32 v100, 0xc2700000, v100
	v_max_f32_e32 v109, 0xc2700000, v109
	v_max_f32_e32 v101, 0xc2700000, v101
	v_max_f32_e32 v107, 0xc2700000, v107
	v_mul_f32_e32 v3, 0xbfb8aa3b, v3
	v_mul_f32_e32 v98, 0xbfb8aa3b, v98
	v_mul_f32_e32 v99, 0xbfb8aa3b, v99
	v_mul_f32_e32 v108, 0xbfb8aa3b, v108
	v_mul_f32_e32 v100, 0xbfb8aa3b, v100
	v_mul_f32_e32 v109, 0xbfb8aa3b, v109
	v_mul_f32_e32 v101, 0xbfb8aa3b, v101
	v_mul_f32_e32 v107, 0xbfb8aa3b, v107
	v_exp_f32_e32 v3, v3
	v_exp_f32_e32 v98, v98
	v_exp_f32_e32 v99, v99
	v_exp_f32_e32 v108, v108
	v_exp_f32_e32 v100, v100
	v_exp_f32_e32 v109, v109
	v_exp_f32_e32 v101, v101
	v_exp_f32_e32 v107, v107
	v_add_f32_e32 v3, 1.0, v3
	v_add_f32_e32 v114, 1.0, v98
	v_add_f32_e32 v115, 1.0, v99
	v_add_f32_e32 v108, 1.0, v108
	v_add_f32_e32 v116, 1.0, v100
	v_add_f32_e32 v109, 1.0, v109
	v_add_f32_e32 v117, 1.0, v101
	v_add_f32_e32 v107, 1.0, v107
	v_rcp_f32_e32 v98, v3
	v_rcp_f32_e32 v99, v114
	v_rcp_f32_e32 v101, v115
	v_rcp_f32_e32 v108, v108
	v_rcp_f32_e32 v114, v109
	v_rcp_f32_e32 v115, v117
	v_rcp_f32_e32 v109, v116
	v_rcp_f32_e32 v100, v107
	v_pk_mul_f32 v[90:91], v[90:91], v[98:99]
	v_pk_mul_f32 v[98:99], v[88:89], v[114:115]
	v_pk_mul_f32 v[88:89], v[86:87], v[108:109]
	v_pk_mul_f32 v[92:93], v[92:93], v[100:101]
	v_cvt_pk_bf16_f32 v86, v90, v91
	v_ashrrev_i32_e32 v107, 31, v106
	v_cvt_pk_bf16_f32 v87, v92, v93
	v_cvt_pk_bf16_f32 v88, v88, v89
	v_cvt_pk_bf16_f32 v89, v98, v99
	global_store_dwordx4 v[96:97], v[86:89], off
	global_load_dwordx4 v[90:93], v[94:95], off
	v_add_u32_e32 v98, 0xb0, v154
	v_lshlrev_b64 v[88:89], 13, v[106:107]
	v_lshl_add_u64 v[88:89], s[6:7], 0, v[88:89]
	v_mad_i64_i32 v[86:87], s[42:43], v98, s81, v[158:159]
	v_lshl_add_u64 v[88:89], v[88:89], 0, v[146:147]
	v_lshl_add_u64 v[86:87], v[86:87], 0, v[146:147]
	s_waitcnt vmcnt(0)
	v_lshlrev_b32_e32 v3, 16, v90
	v_and_b32_e32 v90, 0xffff0000, v90
	v_lshlrev_b32_e32 v99, 16, v91
	v_and_b32_e32 v91, 0xffff0000, v91
	v_lshlrev_b32_e32 v100, 16, v92
	v_and_b32_e32 v92, 0xffff0000, v92
	v_lshlrev_b32_e32 v101, 16, v93
	v_and_b32_e32 v93, 0xffff0000, v93
	v_add_f32_e32 v3, v138, v3
	v_add_f32_e32 v90, v139, v90
	v_add_f32_e32 v91, v141, v91
	v_add_f32_e32 v100, v134, v100
	v_add_f32_e32 v92, v135, v92
	v_add_f32_e32 v101, v136, v101
	v_add_f32_e32 v93, v137, v93
	v_add_f32_e32 v99, v140, v99
	v_max_f32_e32 v3, 0xc2700000, v3
	v_max_f32_e32 v90, 0xc2700000, v90
	v_max_f32_e32 v91, 0xc2700000, v91
	v_max_f32_e32 v100, 0xc2700000, v100
	v_max_f32_e32 v92, 0xc2700000, v92
	v_max_f32_e32 v101, 0xc2700000, v101
	v_max_f32_e32 v93, 0xc2700000, v93
	v_max_f32_e32 v99, 0xc2700000, v99
	v_mul_f32_e32 v3, 0xbfb8aa3b, v3
	v_mul_f32_e32 v90, 0xbfb8aa3b, v90
	v_mul_f32_e32 v91, 0xbfb8aa3b, v91
	v_mul_f32_e32 v100, 0xbfb8aa3b, v100
	v_mul_f32_e32 v92, 0xbfb8aa3b, v92
	v_mul_f32_e32 v101, 0xbfb8aa3b, v101
	v_mul_f32_e32 v93, 0xbfb8aa3b, v93
	v_mul_f32_e32 v99, 0xbfb8aa3b, v99
	v_exp_f32_e32 v3, v3
	v_exp_f32_e32 v90, v90
	v_exp_f32_e32 v91, v91
	v_exp_f32_e32 v100, v100
	v_exp_f32_e32 v92, v92
	v_exp_f32_e32 v101, v101
	v_exp_f32_e32 v93, v93
	v_exp_f32_e32 v99, v99
	v_add_f32_e32 v3, 1.0, v3
	v_add_f32_e32 v106, 1.0, v90
	v_add_f32_e32 v107, 1.0, v91
	v_add_f32_e32 v100, 1.0, v100
	v_add_f32_e32 v108, 1.0, v92
	v_add_f32_e32 v101, 1.0, v101
	v_add_f32_e32 v109, 1.0, v93
	v_add_f32_e32 v99, 1.0, v99
	v_rcp_f32_e32 v90, v3
	v_rcp_f32_e32 v91, v106
	v_rcp_f32_e32 v93, v107
	v_rcp_f32_e32 v100, v100
	v_rcp_f32_e32 v106, v101
	v_rcp_f32_e32 v107, v109
	v_rcp_f32_e32 v101, v108
	v_rcp_f32_e32 v92, v99
	v_pk_mul_f32 v[82:83], v[82:83], v[90:91]
	v_pk_mul_f32 v[90:91], v[80:81], v[106:107]
	v_pk_mul_f32 v[80:81], v[78:79], v[100:101]
	v_pk_mul_f32 v[84:85], v[84:85], v[92:93]
	v_cvt_pk_bf16_f32 v78, v82, v83
	v_ashrrev_i32_e32 v99, 31, v98
	v_cvt_pk_bf16_f32 v79, v84, v85
	v_cvt_pk_bf16_f32 v80, v80, v81
	v_cvt_pk_bf16_f32 v81, v90, v91
	global_store_dwordx4 v[88:89], v[78:81], off
	global_load_dwordx4 v[78:81], v[86:87], off
	s_waitcnt vmcnt(0)
; __device__ __forceinline__ unsigned cvt_pk_bf16(float lo, float hi) { unsigned r; asm volatile("v_cvt_pk_bf16_f32 %0, %1, %2" : "=v"(r) : "v"(lo), "v"(hi)); return r; }
; __device__ __forceinline__ float bf_lo(unsigned w) { return __uint_as_float(w << 16); }
; __device__ __forceinline__ float bf_hi(unsigned w) { return __uint_as_float(w & 0xffff0000u); }
; __device__ __forceinline__ float sigmoid_f(float x) { return __builtin_amdgcn_rcpf(1.0f + __expf(-x)); }
;     __device__ __forceinline__ void operator()(const f32x4 (&acc)[2][2][4][2], const Unit& u, int wr, int wc, int fr, int fq) const {
;     ...
;         for (int bj = 0; bj < 2; ++bj) { const f32x4 b0 = *(const f32x4*)(bias + nb + col0 + bj * HALF), b1 = *(const f32x4*)(bias + nb + col0 + bj * HALF + 4);
; #pragma unroll
;             for (int ai = 0; ai < 2; ++ai)
; #pragma unroll
;                 for (int m = 0; m < 4; ++m) { const size_t r = (size_t)(row0 + ai * HALF + m * 16);
;                     const u32x4 g = *(const u32x4*)(GB + r * ldg + col0 + bj * HALF);
;                     f32x4 s0, s1;
;                     s0[0] = sigmoid_f(fmaxf(bf_lo(g.x) + b0[0], GB_MIN)); s0[1] = sigmoid_f(fmaxf(bf_hi(g.x) + b0[1], GB_MIN)); s0[2] = sigmoid_f(fmaxf(bf_lo(g.y) + b0[2], GB_MIN)); s0[3] = sigmoid_f(fmaxf(bf_hi(g.y) + b0[3], GB_MIN));
;                     s1[0] = sigmoid_f(fmaxf(bf_lo(g.z) + b1[0], GB_MIN)); s1[1] = sigmoid_f(fmaxf(bf_hi(g.z) + b1[1], GB_MIN)); s1[2] = sigmoid_f(fmaxf(bf_lo(g.w) + b1[2], GB_MIN)); s1[3] = sigmoid_f(fmaxf(bf_hi(g.w) + b1[3], GB_MIN));
;                     const f32x4 v0 = s0 * acc[ai][bj][m][0], v1 = s1 * acc[ai][bj][m][1];
;                     u32x4 w; w.x = cvt_pk_bf16(v0[0], v0[1]); w.y = cvt_pk_bf16(v0[2], v0[3]); w.z = cvt_pk_bf16(v1[0], v1[1]); w.w = cvt_pk_bf16(v1[2], v1[3]);
;                     *(u32x4*)(O + r * ldc + col0 + bj * HALF) = w; } }
	v_lshlrev_b32_e32 v3, 16, v78
	v_and_b32_e32 v78, 0xffff0000, v78
	v_lshlrev_b32_e32 v82, 16, v79
	v_and_b32_e32 v79, 0xffff0000, v79
	v_lshlrev_b32_e32 v83, 16, v80
	v_and_b32_e32 v80, 0xffff0000, v80
	v_lshlrev_b32_e32 v84, 16, v81
	v_and_b32_e32 v81, 0xffff0000, v81
	v_add_f32_e32 v3, v138, v3
	v_add_f32_e32 v78, v139, v78
	v_add_f32_e32 v82, v140, v82
	v_add_f32_e32 v79, v141, v79
	v_add_f32_e32 v83, v134, v83
	v_add_f32_e32 v80, v135, v80
	v_add_f32_e32 v84, v136, v84
	v_add_f32_e32 v81, v137, v81
	v_max_f32_e32 v3, 0xc2700000, v3
	v_max_f32_e32 v78, 0xc2700000, v78
	v_max_f32_e32 v82, 0xc2700000, v82
	v_max_f32_e32 v79, 0xc2700000, v79
	v_max_f32_e32 v83, 0xc2700000, v83
	v_max_f32_e32 v80, 0xc2700000, v80
	v_max_f32_e32 v84, 0xc2700000, v84
	v_max_f32_e32 v81, 0xc2700000, v81
	v_mul_f32_e32 v3, 0xbfb8aa3b, v3
	v_mul_f32_e32 v78, 0xbfb8aa3b, v78
	v_mul_f32_e32 v82, 0xbfb8aa3b, v82
	v_mul_f32_e32 v79, 0xbfb8aa3b, v79
	v_mul_f32_e32 v83, 0xbfb8aa3b, v83
	v_mul_f32_e32 v80, 0xbfb8aa3b, v80
	v_mul_f32_e32 v84, 0xbfb8aa3b, v84
	v_mul_f32_e32 v81, 0xbfb8aa3b, v81
	v_exp_f32_e32 v3, v3
	v_exp_f32_e32 v78, v78
	v_exp_f32_e32 v82, v82
	v_exp_f32_e32 v79, v79
	v_exp_f32_e32 v83, v83
	v_exp_f32_e32 v80, v80
	v_exp_f32_e32 v84, v84
	v_exp_f32_e32 v81, v81
	v_add_f32_e32 v3, 1.0, v3
	v_add_f32_e32 v85, 1.0, v78
	v_add_f32_e32 v82, 1.0, v82
	v_add_f32_e32 v90, 1.0, v79
	v_add_f32_e32 v83, 1.0, v83
	v_add_f32_e32 v91, 1.0, v80
	v_add_f32_e32 v84, 1.0, v84
	v_add_f32_e32 v92, 1.0, v81
	v_rcp_f32_e32 v78, v3
	v_rcp_f32_e32 v79, v85
	v_rcp_f32_e32 v80, v82
	v_rcp_f32_e32 v82, v83
	v_rcp_f32_e32 v84, v84
	v_rcp_f32_e32 v85, v92
	v_rcp_f32_e32 v83, v91
	v_rcp_f32_e32 v81, v90
	v_pk_mul_f32 v[74:75], v[74:75], v[78:79]
	v_pk_mul_f32 v[78:79], v[72:73], v[84:85]
	v_pk_mul_f32 v[72:73], v[70:71], v[82:83]
	v_cvt_pk_bf16_f32 v70, v74, v75
	v_lshlrev_b64 v[74:75], 13, v[98:99]
	v_lshl_add_u64 v[74:75], s[6:7], 0, v[74:75]
	v_pk_mul_f32 v[76:77], v[76:77], v[80:81]
	s_nop 0
	v_cvt_pk_bf16_f32 v71, v76, v77
	v_cvt_pk_bf16_f32 v72, v72, v73
	v_cvt_pk_bf16_f32 v73, v78, v79
	v_lshl_add_u64 v[78:79], v[74:75], 0, v[146:147]
	global_load_dwordx4 v[80:83], v[148:149], off offset:256
	s_waitcnt vmcnt(0)
	v_lshlrev_b32_e32 v3, 16, v80
	global_store_dwordx4 v[78:79], v[70:73], off
	global_load_dwordx4 v[74:77], v[144:145], off offset:512
	s_nop 0
	global_load_dwordx4 v[70:73], v[144:145], off offset:528
	v_and_b32_e32 v80, 0xffff0000, v80
	v_lshlrev_b32_e32 v84, 16, v81
	v_lshlrev_b32_e32 v85, 16, v82
	v_and_b32_e32 v82, 0xffff0000, v82
	v_lshlrev_b32_e32 v90, 16, v83
	v_and_b32_e32 v83, 0xffff0000, v83
	v_and_b32_e32 v81, 0xffff0000, v81
	s_waitcnt vmcnt(1)
	v_add_f32_e32 v3, v74, v3
	v_add_f32_e32 v80, v75, v80
	v_add_f32_e32 v84, v76, v84
	s_waitcnt vmcnt(0)
	v_add_f32_e32 v85, v70, v85
	v_add_f32_e32 v82, v71, v82
	v_add_f32_e32 v90, v72, v90
	v_add_f32_e32 v83, v73, v83
	v_add_f32_e32 v81, v77, v81
	v_max_f32_e32 v3, 0xc2700000, v3
	v_max_f32_e32 v80, 0xc2700000, v80
	v_max_f32_e32 v84, 0xc2700000, v84
	v_max_f32_e32 v85, 0xc2700000, v85
	v_max_f32_e32 v82, 0xc2700000, v82
	v_max_f32_e32 v90, 0xc2700000, v90
	v_max_f32_e32 v83, 0xc2700000, v83
	v_max_f32_e32 v81, 0xc2700000, v81
	v_mul_f32_e32 v3, 0xbfb8aa3b, v3
	v_mul_f32_e32 v80, 0xbfb8aa3b, v80
	v_mul_f32_e32 v84, 0xbfb8aa3b, v84
	v_mul_f32_e32 v85, 0xbfb8aa3b, v85
	v_mul_f32_e32 v82, 0xbfb8aa3b, v82
	v_mul_f32_e32 v90, 0xbfb8aa3b, v90
	v_mul_f32_e32 v83, 0xbfb8aa3b, v83
	v_mul_f32_e32 v81, 0xbfb8aa3b, v81
	v_exp_f32_e32 v3, v3
	v_exp_f32_e32 v80, v80
	v_exp_f32_e32 v84, v84
	v_exp_f32_e32 v85, v85
	v_exp_f32_e32 v82, v82
	v_exp_f32_e32 v90, v90
	v_exp_f32_e32 v83, v83
	v_exp_f32_e32 v81, v81
	v_add_f32_e32 v3, 1.0, v3
	v_add_f32_e32 v91, 1.0, v80
	v_add_f32_e32 v84, 1.0, v84
	v_add_f32_e32 v85, 1.0, v85
	v_add_f32_e32 v93, 1.0, v82
	v_add_f32_e32 v90, 1.0, v90
	v_add_f32_e32 v98, 1.0, v83
	v_add_f32_e32 v92, 1.0, v81
	v_rcp_f32_e32 v80, v3
	v_rcp_f32_e32 v81, v91
	v_rcp_f32_e32 v82, v84
	v_rcp_f32_e32 v84, v85
	v_rcp_f32_e32 v90, v90
	v_rcp_f32_e32 v91, v98
	v_rcp_f32_e32 v85, v93
	v_rcp_f32_e32 v83, v92
	v_pk_mul_f32 v[66:67], v[66:67], v[80:81]
	v_pk_mul_f32 v[80:81], v[64:65], v[90:91]
	v_pk_mul_f32 v[64:65], v[62:63], v[84:85]
	v_pk_mul_f32 v[68:69], v[68:69], v[82:83]
	v_cvt_pk_bf16_f32 v62, v66, v67
	s_nop 0
	v_cvt_pk_bf16_f32 v63, v68, v69
	v_cvt_pk_bf16_f32 v64, v64, v65
	v_cvt_pk_bf16_f32 v65, v80, v81
	global_store_dwordx4 v[142:143], v[62:65], off offset:256
	global_load_dwordx4 v[62:65], v[4:5], off offset:256
	s_waitcnt vmcnt(0)
	v_lshlrev_b32_e32 v3, 16, v62
	v_and_b32_e32 v4, 0xffff0000, v62
	v_lshlrev_b32_e32 v5, 16, v63
	v_and_b32_e32 v62, 0xffff0000, v63
	v_lshlrev_b32_e32 v63, 16, v64
	v_and_b32_e32 v64, 0xffff0000, v64
	v_lshlrev_b32_e32 v66, 16, v65
	v_and_b32_e32 v65, 0xffff0000, v65
	v_add_f32_e32 v3, v74, v3
	v_add_f32_e32 v4, v75, v4
	v_add_f32_e32 v63, v70, v63
	v_add_f32_e32 v64, v71, v64
	v_add_f32_e32 v66, v72, v66
	v_add_f32_e32 v65, v73, v65
	v_add_f32_e32 v5, v76, v5
	v_add_f32_e32 v62, v77, v62
	v_max_f32_e32 v3, 0xc2700000, v3
	v_max_f32_e32 v4, 0xc2700000, v4
	v_max_f32_e32 v63, 0xc2700000, v63
	v_max_f32_e32 v64, 0xc2700000, v64
	v_max_f32_e32 v66, 0xc2700000, v66
	v_max_f32_e32 v65, 0xc2700000, v65
	v_max_f32_e32 v5, 0xc2700000, v5
	v_max_f32_e32 v62, 0xc2700000, v62
	v_mul_f32_e32 v3, 0xbfb8aa3b, v3
	v_mul_f32_e32 v4, 0xbfb8aa3b, v4
	v_mul_f32_e32 v63, 0xbfb8aa3b, v63
	v_mul_f32_e32 v64, 0xbfb8aa3b, v64
	v_mul_f32_e32 v66, 0xbfb8aa3b, v66
	v_mul_f32_e32 v65, 0xbfb8aa3b, v65
	v_mul_f32_e32 v5, 0xbfb8aa3b, v5
	v_mul_f32_e32 v62, 0xbfb8aa3b, v62
	v_exp_f32_e32 v3, v3
	v_exp_f32_e32 v4, v4
	v_exp_f32_e32 v63, v63
	v_exp_f32_e32 v64, v64
	v_exp_f32_e32 v66, v66
	v_exp_f32_e32 v65, v65
	v_exp_f32_e32 v5, v5
	v_exp_f32_e32 v62, v62
	v_add_f32_e32 v3, 1.0, v3
	v_add_f32_e32 v67, 1.0, v4
	v_add_f32_e32 v80, 1.0, v63
	v_add_f32_e32 v81, 1.0, v64
	v_add_f32_e32 v66, 1.0, v66
	v_add_f32_e32 v65, 1.0, v65
	v_add_f32_e32 v68, 1.0, v5
	v_add_f32_e32 v69, 1.0, v62
	v_rcp_f32_e32 v4, v3
	v_rcp_f32_e32 v5, v67
	v_rcp_f32_e32 v64, v80
	v_rcp_f32_e32 v66, v66
	v_rcp_f32_e32 v67, v65
	v_rcp_f32_e32 v65, v81
	v_rcp_f32_e32 v62, v68
	v_rcp_f32_e32 v63, v69
	v_pk_mul_f32 v[4:5], v[58:59], v[4:5]
	v_pk_mul_f32 v[58:59], v[56:57], v[66:67]
	v_pk_mul_f32 v[56:57], v[54:55], v[64:65]
	v_pk_mul_f32 v[60:61], v[60:61], v[62:63]
	v_cvt_pk_bf16_f32 v54, v4, v5
	s_nop 0
	v_cvt_pk_bf16_f32 v55, v60, v61
	v_cvt_pk_bf16_f32 v56, v56, v57
	v_cvt_pk_bf16_f32 v57, v58, v59
	global_store_dwordx4 v[128:129], v[54:57], off offset:256
	global_load_dwordx4 v[54:57], v[126:127], off offset:256
	s_waitcnt vmcnt(0)
; __device__ __forceinline__ unsigned cvt_pk_bf16(float lo, float hi) { unsigned r; asm volatile("v_cvt_pk_bf16_f32 %0, %1, %2" : "=v"(r) : "v"(lo), "v"(hi)); return r; }
; __device__ __forceinline__ float bf_lo(unsigned w) { return __uint_as_float(w << 16); }
; __device__ __forceinline__ float bf_hi(unsigned w) { return __uint_as_float(w & 0xffff0000u); }
; __device__ __forceinline__ float sigmoid_f(float x) { return __builtin_amdgcn_rcpf(1.0f + __expf(-x)); }
;     __device__ __forceinline__ void operator()(const f32x4 (&acc)[2][2][4][2], const Unit& u, int wr, int wc, int fr, int fq) const {
;     ...
;                 for (int m = 0; m < 4; ++m) { const size_t r = (size_t)(row0 + ai * HALF + m * 16);
;                     const u32x4 g = *(const u32x4*)(GB + r * ldg + col0 + bj * HALF);
;                     f32x4 s0, s1;
;                     s0[0] = sigmoid_f(fmaxf(bf_lo(g.x) + b0[0], GB_MIN)); s0[1] = sigmoid_f(fmaxf(bf_hi(g.x) + b0[1], GB_MIN)); s0[2] = sigmoid_f(fmaxf(bf_lo(g.y) + b0[2], GB_MIN)); s0[3] = sigmoid_f(fmaxf(bf_hi(g.y) + b0[3], GB_MIN));
;                     s1[0] = sigmoid_f(fmaxf(bf_lo(g.z) + b1[0], GB_MIN)); s1[1] = sigmoid_f(fmaxf(bf_hi(g.z) + b1[1], GB_MIN)); s1[2] = sigmoid_f(fmaxf(bf_lo(g.w) + b1[2], GB_MIN)); s1[3] = sigmoid_f(fmaxf(bf_hi(g.w) + b1[3], GB_MIN));
;                     const f32x4 v0 = s0 * acc[ai][bj][m][0], v1 = s1 * acc[ai][bj][m][1];
;                     u32x4 w; w.x = cvt_pk_bf16(v0[0], v0[1]); w.y = cvt_pk_bf16(v0[2], v0[3]); w.z = cvt_pk_bf16(v1[0], v1[1]); w.w = cvt_pk_bf16(v1[2], v1[3]);
;                     *(u32x4*)(O + r * ldc + col0 + bj * HALF) = w; } }
	v_lshlrev_b32_e32 v3, 16, v54
	v_and_b32_e32 v4, 0xffff0000, v54
	v_lshlrev_b32_e32 v5, 16, v55
	v_and_b32_e32 v54, 0xffff0000, v55
	v_lshlrev_b32_e32 v55, 16, v56
	v_and_b32_e32 v56, 0xffff0000, v56
	v_lshlrev_b32_e32 v58, 16, v57
	v_and_b32_e32 v57, 0xffff0000, v57
	v_add_f32_e32 v3, v74, v3
	v_add_f32_e32 v4, v75, v4
	v_add_f32_e32 v55, v70, v55
	v_add_f32_e32 v56, v71, v56
	v_add_f32_e32 v58, v72, v58
	v_add_f32_e32 v57, v73, v57
	v_add_f32_e32 v5, v76, v5
	v_add_f32_e32 v54, v77, v54
	v_max_f32_e32 v3, 0xc2700000, v3
	v_max_f32_e32 v4, 0xc2700000, v4
	v_max_f32_e32 v55, 0xc2700000, v55
	v_max_f32_e32 v56, 0xc2700000, v56
	v_max_f32_e32 v58, 0xc2700000, v58
	v_max_f32_e32 v57, 0xc2700000, v57
	v_max_f32_e32 v5, 0xc2700000, v5
	v_max_f32_e32 v54, 0xc2700000, v54
	v_mul_f32_e32 v3, 0xbfb8aa3b, v3
	v_mul_f32_e32 v4, 0xbfb8aa3b, v4
	v_mul_f32_e32 v55, 0xbfb8aa3b, v55
	v_mul_f32_e32 v56, 0xbfb8aa3b, v56
	v_mul_f32_e32 v58, 0xbfb8aa3b, v58
	v_mul_f32_e32 v57, 0xbfb8aa3b, v57
	v_mul_f32_e32 v5, 0xbfb8aa3b, v5
	v_mul_f32_e32 v54, 0xbfb8aa3b, v54
	v_exp_f32_e32 v3, v3
	v_exp_f32_e32 v4, v4
	v_exp_f32_e32 v55, v55
	v_exp_f32_e32 v56, v56
	v_exp_f32_e32 v58, v58
	v_exp_f32_e32 v57, v57
	v_exp_f32_e32 v5, v5
	v_exp_f32_e32 v54, v54
	v_add_f32_e32 v3, 1.0, v3
	v_add_f32_e32 v59, 1.0, v4
	v_add_f32_e32 v62, 1.0, v55
	v_add_f32_e32 v63, 1.0, v56
	v_add_f32_e32 v58, 1.0, v58
	v_add_f32_e32 v57, 1.0, v57
	v_add_f32_e32 v60, 1.0, v5
	v_add_f32_e32 v61, 1.0, v54
	v_rcp_f32_e32 v4, v3
	v_rcp_f32_e32 v5, v59
	v_rcp_f32_e32 v56, v62
	v_rcp_f32_e32 v58, v58
	v_rcp_f32_e32 v59, v57
	v_rcp_f32_e32 v57, v63
	v_rcp_f32_e32 v54, v60
	v_rcp_f32_e32 v55, v61
	v_pk_mul_f32 v[4:5], v[50:51], v[4:5]
	v_pk_mul_f32 v[50:51], v[48:49], v[58:59]
	v_pk_mul_f32 v[48:49], v[46:47], v[56:57]
	v_pk_mul_f32 v[52:53], v[52:53], v[54:55]
	v_cvt_pk_bf16_f32 v46, v4, v5
	s_nop 0
	v_cvt_pk_bf16_f32 v47, v52, v53
	v_cvt_pk_bf16_f32 v48, v48, v49
	v_cvt_pk_bf16_f32 v49, v50, v51
	global_store_dwordx4 v[120:121], v[46:49], off offset:256
	global_load_dwordx4 v[46:49], v[118:119], off offset:256
	s_waitcnt vmcnt(0)
	v_lshlrev_b32_e32 v3, 16, v46
	v_and_b32_e32 v4, 0xffff0000, v46
	v_lshlrev_b32_e32 v5, 16, v47
	v_and_b32_e32 v46, 0xffff0000, v47
	v_lshlrev_b32_e32 v47, 16, v48
	v_and_b32_e32 v48, 0xffff0000, v48
	v_lshlrev_b32_e32 v50, 16, v49
	v_and_b32_e32 v49, 0xffff0000, v49
	v_add_f32_e32 v3, v74, v3
	v_add_f32_e32 v4, v75, v4
	v_add_f32_e32 v47, v70, v47
	v_add_f32_e32 v48, v71, v48
	v_add_f32_e32 v50, v72, v50
	v_add_f32_e32 v49, v73, v49
	v_add_f32_e32 v5, v76, v5
	v_add_f32_e32 v46, v77, v46
	v_max_f32_e32 v3, 0xc2700000, v3
	v_max_f32_e32 v4, 0xc2700000, v4
	v_max_f32_e32 v47, 0xc2700000, v47
	v_max_f32_e32 v48, 0xc2700000, v48
	v_max_f32_e32 v50, 0xc2700000, v50
	v_max_f32_e32 v49, 0xc2700000, v49
	v_max_f32_e32 v5, 0xc2700000, v5
	v_max_f32_e32 v46, 0xc2700000, v46
	v_mul_f32_e32 v3, 0xbfb8aa3b, v3
	v_mul_f32_e32 v4, 0xbfb8aa3b, v4
	v_mul_f32_e32 v47, 0xbfb8aa3b, v47
	v_mul_f32_e32 v48, 0xbfb8aa3b, v48
	v_mul_f32_e32 v50, 0xbfb8aa3b, v50
	v_mul_f32_e32 v49, 0xbfb8aa3b, v49
	v_mul_f32_e32 v5, 0xbfb8aa3b, v5
	v_mul_f32_e32 v46, 0xbfb8aa3b, v46
	v_exp_f32_e32 v3, v3
	v_exp_f32_e32 v4, v4
	v_exp_f32_e32 v47, v47
	v_exp_f32_e32 v48, v48
	v_exp_f32_e32 v50, v50
	v_exp_f32_e32 v49, v49
	v_exp_f32_e32 v5, v5
	v_exp_f32_e32 v46, v46
	v_add_f32_e32 v3, 1.0, v3
	v_add_f32_e32 v51, 1.0, v4
	v_add_f32_e32 v54, 1.0, v47
	v_add_f32_e32 v55, 1.0, v48
	v_add_f32_e32 v50, 1.0, v50
	v_add_f32_e32 v49, 1.0, v49
	v_add_f32_e32 v52, 1.0, v5
	v_add_f32_e32 v53, 1.0, v46
	v_rcp_f32_e32 v4, v3
	v_rcp_f32_e32 v5, v51
	v_rcp_f32_e32 v48, v54
	v_rcp_f32_e32 v50, v50
	v_rcp_f32_e32 v51, v49
	v_rcp_f32_e32 v49, v55
	v_rcp_f32_e32 v46, v52
	v_rcp_f32_e32 v47, v53
	v_pk_mul_f32 v[4:5], v[42:43], v[4:5]
	v_pk_mul_f32 v[42:43], v[40:41], v[50:51]
	v_pk_mul_f32 v[40:41], v[38:39], v[48:49]
	v_pk_mul_f32 v[44:45], v[44:45], v[46:47]
	v_cvt_pk_bf16_f32 v38, v4, v5
	s_nop 0
	v_cvt_pk_bf16_f32 v39, v44, v45
	v_cvt_pk_bf16_f32 v40, v40, v41
	v_cvt_pk_bf16_f32 v41, v42, v43
	global_store_dwordx4 v[112:113], v[38:41], off offset:256
	global_load_dwordx4 v[38:41], v[110:111], off offset:256
	s_waitcnt vmcnt(0)
	v_lshlrev_b32_e32 v3, 16, v38
	v_and_b32_e32 v4, 0xffff0000, v38
	v_lshlrev_b32_e32 v5, 16, v39
	v_and_b32_e32 v38, 0xffff0000, v39
	v_lshlrev_b32_e32 v39, 16, v40
	v_and_b32_e32 v40, 0xffff0000, v40
	v_lshlrev_b32_e32 v42, 16, v41
	v_and_b32_e32 v41, 0xffff0000, v41
	v_add_f32_e32 v3, v74, v3
	v_add_f32_e32 v4, v75, v4
	v_add_f32_e32 v39, v70, v39
	v_add_f32_e32 v40, v71, v40
	v_add_f32_e32 v42, v72, v42
	v_add_f32_e32 v41, v73, v41
	v_add_f32_e32 v5, v76, v5
	v_add_f32_e32 v38, v77, v38
	v_max_f32_e32 v3, 0xc2700000, v3
	v_max_f32_e32 v4, 0xc2700000, v4
	v_max_f32_e32 v39, 0xc2700000, v39
	v_max_f32_e32 v40, 0xc2700000, v40
	v_max_f32_e32 v42, 0xc2700000, v42
	v_max_f32_e32 v41, 0xc2700000, v41
	v_max_f32_e32 v5, 0xc2700000, v5
	v_max_f32_e32 v38, 0xc2700000, v38
	v_mul_f32_e32 v3, 0xbfb8aa3b, v3
	v_mul_f32_e32 v4, 0xbfb8aa3b, v4
	v_mul_f32_e32 v39, 0xbfb8aa3b, v39
	v_mul_f32_e32 v40, 0xbfb8aa3b, v40
	v_mul_f32_e32 v42, 0xbfb8aa3b, v42
	v_mul_f32_e32 v41, 0xbfb8aa3b, v41
	v_mul_f32_e32 v5, 0xbfb8aa3b, v5
	v_mul_f32_e32 v38, 0xbfb8aa3b, v38
	v_exp_f32_e32 v3, v3
	v_exp_f32_e32 v4, v4
	v_exp_f32_e32 v39, v39
	v_exp_f32_e32 v40, v40
	v_exp_f32_e32 v42, v42
	v_exp_f32_e32 v41, v41
	v_exp_f32_e32 v5, v5
	v_exp_f32_e32 v38, v38
	v_add_f32_e32 v3, 1.0, v3
	v_add_f32_e32 v43, 1.0, v4
	v_add_f32_e32 v46, 1.0, v39
	v_add_f32_e32 v47, 1.0, v40
	v_add_f32_e32 v42, 1.0, v42
	v_add_f32_e32 v41, 1.0, v41
	v_add_f32_e32 v44, 1.0, v5
	v_add_f32_e32 v45, 1.0, v38
	v_rcp_f32_e32 v4, v3
	v_rcp_f32_e32 v5, v43
	v_rcp_f32_e32 v40, v46
	v_rcp_f32_e32 v42, v42
	v_rcp_f32_e32 v43, v41
	v_rcp_f32_e32 v41, v47
	v_rcp_f32_e32 v38, v44
	v_rcp_f32_e32 v39, v45
	v_pk_mul_f32 v[4:5], v[34:35], v[4:5]
	v_pk_mul_f32 v[34:35], v[32:33], v[42:43]
	v_pk_mul_f32 v[32:33], v[30:31], v[40:41]
	v_pk_mul_f32 v[36:37], v[36:37], v[38:39]
	v_cvt_pk_bf16_f32 v30, v4, v5
	s_nop 0
	v_cvt_pk_bf16_f32 v31, v36, v37
	v_cvt_pk_bf16_f32 v32, v32, v33
	v_cvt_pk_bf16_f32 v33, v34, v35
	global_store_dwordx4 v[104:105], v[30:33], off offset:256
	global_load_dwordx4 v[30:33], v[102:103], off offset:256
	s_waitcnt vmcnt(0)
; __device__ __forceinline__ unsigned cvt_pk_bf16(float lo, float hi) { unsigned r; asm volatile("v_cvt_pk_bf16_f32 %0, %1, %2" : "=v"(r) : "v"(lo), "v"(hi)); return r; }
; __device__ __forceinline__ float bf_lo(unsigned w) { return __uint_as_float(w << 16); }
; __device__ __forceinline__ float bf_hi(unsigned w) { return __uint_as_float(w & 0xffff0000u); }
; __device__ __forceinline__ float sigmoid_f(float x) { return __builtin_amdgcn_rcpf(1.0f + __expf(-x)); }
; #define PG8_BAR __builtin_amdgcn_s_barrier()
;     __device__ __forceinline__ void operator()(const f32x4 (&acc)[2][2][4][2], const Unit& u, int wr, int wc, int fr, int fq) const {
;     ...
;                 for (int m = 0; m < 4; ++m) { const size_t r = (size_t)(row0 + ai * HALF + m * 16);
;                     const u32x4 g = *(const u32x4*)(GB + r * ldg + col0 + bj * HALF);
;                     f32x4 s0, s1;
;                     s0[0] = sigmoid_f(fmaxf(bf_lo(g.x) + b0[0], GB_MIN)); s0[1] = sigmoid_f(fmaxf(bf_hi(g.x) + b0[1], GB_MIN)); s0[2] = sigmoid_f(fmaxf(bf_lo(g.y) + b0[2], GB_MIN)); s0[3] = sigmoid_f(fmaxf(bf_hi(g.y) + b0[3], GB_MIN));
;                     s1[0] = sigmoid_f(fmaxf(bf_lo(g.z) + b1[0], GB_MIN)); s1[1] = sigmoid_f(fmaxf(bf_hi(g.z) + b1[1], GB_MIN)); s1[2] = sigmoid_f(fmaxf(bf_lo(g.w) + b1[2], GB_MIN)); s1[3] = sigmoid_f(fmaxf(bf_hi(g.w) + b1[3], GB_MIN));
;                     const f32x4 v0 = s0 * acc[ai][bj][m][0], v1 = s1 * acc[ai][bj][m][1];
;                     u32x4 w; w.x = cvt_pk_bf16(v0[0], v0[1]); w.y = cvt_pk_bf16(v0[2], v0[3]); w.z = cvt_pk_bf16(v1[0], v1[1]); w.w = cvt_pk_bf16(v1[2], v1[3]);
;                     *(u32x4*)(O + r * ldc + col0 + bj * HALF) = w; } }
; template <class Epi, class Sched, bool ALIGN_EPI = false, bool SP2 = false>
; __device__ __forceinline__ void gemm_phase(PG8_LAS unsigned char* lds, const Gemm g, const Sched& S, const Epi& E) {
;     ...
;         if (!has_next) break;
; #pragma unroll
;         for (int a = 0; a < 2; ++a)
; #pragma unroll
;             for (int b = 0; b < 2; ++b)
; #pragma unroll
;                 for (int m = 0; m < 4; ++m)
; #pragma unroll
;                     for (int n = 0; n < 2; ++n) acc[a][b][m][n] = (f32x4){0.f, 0.f, 0.f, 0.f};
;         cur = nxt; cA = nA; cB = nB; ++ui;
;         if constexpr (ALIGN_EPI) { if (wr == 1) PG8_BAR; }
;     }
	v_lshlrev_b32_e32 v3, 16, v30
	v_and_b32_e32 v4, 0xffff0000, v30
	v_lshlrev_b32_e32 v5, 16, v31
	v_and_b32_e32 v30, 0xffff0000, v31
	v_lshlrev_b32_e32 v31, 16, v32
	v_and_b32_e32 v32, 0xffff0000, v32
	v_lshlrev_b32_e32 v34, 16, v33
	v_and_b32_e32 v33, 0xffff0000, v33
	v_add_f32_e32 v3, v74, v3
	v_add_f32_e32 v4, v75, v4
	v_add_f32_e32 v31, v70, v31
	v_add_f32_e32 v32, v71, v32
	v_add_f32_e32 v34, v72, v34
	v_add_f32_e32 v33, v73, v33
	v_add_f32_e32 v5, v76, v5
	v_add_f32_e32 v30, v77, v30
	v_max_f32_e32 v3, 0xc2700000, v3
	v_max_f32_e32 v4, 0xc2700000, v4
	v_max_f32_e32 v31, 0xc2700000, v31
	v_max_f32_e32 v32, 0xc2700000, v32
	v_max_f32_e32 v34, 0xc2700000, v34
	v_max_f32_e32 v33, 0xc2700000, v33
	v_max_f32_e32 v5, 0xc2700000, v5
	v_max_f32_e32 v30, 0xc2700000, v30
	v_mul_f32_e32 v3, 0xbfb8aa3b, v3
	v_mul_f32_e32 v4, 0xbfb8aa3b, v4
	v_mul_f32_e32 v31, 0xbfb8aa3b, v31
	v_mul_f32_e32 v32, 0xbfb8aa3b, v32
	v_mul_f32_e32 v34, 0xbfb8aa3b, v34
	v_mul_f32_e32 v33, 0xbfb8aa3b, v33
	v_mul_f32_e32 v5, 0xbfb8aa3b, v5
	v_mul_f32_e32 v30, 0xbfb8aa3b, v30
	v_exp_f32_e32 v3, v3
	v_exp_f32_e32 v4, v4
	v_exp_f32_e32 v31, v31
	v_exp_f32_e32 v32, v32
	v_exp_f32_e32 v34, v34
	v_exp_f32_e32 v33, v33
	v_exp_f32_e32 v5, v5
	v_exp_f32_e32 v30, v30
	v_add_f32_e32 v3, 1.0, v3
	v_add_f32_e32 v35, 1.0, v4
	v_add_f32_e32 v38, 1.0, v31
	v_add_f32_e32 v39, 1.0, v32
	v_add_f32_e32 v34, 1.0, v34
	v_add_f32_e32 v33, 1.0, v33
	v_add_f32_e32 v36, 1.0, v5
	v_add_f32_e32 v37, 1.0, v30
	v_rcp_f32_e32 v4, v3
	v_rcp_f32_e32 v5, v35
	v_rcp_f32_e32 v32, v38
	v_rcp_f32_e32 v34, v34
	v_rcp_f32_e32 v35, v33
	v_rcp_f32_e32 v33, v39
	v_rcp_f32_e32 v30, v36
	v_rcp_f32_e32 v31, v37
	v_pk_mul_f32 v[4:5], v[26:27], v[4:5]
	v_pk_mul_f32 v[26:27], v[24:25], v[34:35]
	v_pk_mul_f32 v[24:25], v[22:23], v[32:33]
	v_pk_mul_f32 v[28:29], v[28:29], v[30:31]
	v_cvt_pk_bf16_f32 v22, v4, v5
	s_nop 0
	v_cvt_pk_bf16_f32 v23, v28, v29
	v_cvt_pk_bf16_f32 v24, v24, v25
	v_cvt_pk_bf16_f32 v25, v26, v27
	global_store_dwordx4 v[96:97], v[22:25], off offset:256
	global_load_dwordx4 v[22:25], v[94:95], off offset:256
	s_waitcnt vmcnt(0)
	v_lshlrev_b32_e32 v3, 16, v22
	v_and_b32_e32 v4, 0xffff0000, v22
	v_lshlrev_b32_e32 v5, 16, v23
	v_and_b32_e32 v22, 0xffff0000, v23
	v_lshlrev_b32_e32 v23, 16, v24
	v_and_b32_e32 v24, 0xffff0000, v24
	v_lshlrev_b32_e32 v26, 16, v25
	v_and_b32_e32 v25, 0xffff0000, v25
	v_add_f32_e32 v3, v74, v3
	v_add_f32_e32 v4, v75, v4
	v_add_f32_e32 v23, v70, v23
	v_add_f32_e32 v24, v71, v24
	v_add_f32_e32 v26, v72, v26
	v_add_f32_e32 v25, v73, v25
	v_add_f32_e32 v5, v76, v5
	v_add_f32_e32 v22, v77, v22
	v_max_f32_e32 v3, 0xc2700000, v3
	v_max_f32_e32 v4, 0xc2700000, v4
	v_max_f32_e32 v23, 0xc2700000, v23
	v_max_f32_e32 v24, 0xc2700000, v24
	v_max_f32_e32 v26, 0xc2700000, v26
	v_max_f32_e32 v25, 0xc2700000, v25
	v_max_f32_e32 v5, 0xc2700000, v5
	v_max_f32_e32 v22, 0xc2700000, v22
	v_mul_f32_e32 v3, 0xbfb8aa3b, v3
	v_mul_f32_e32 v4, 0xbfb8aa3b, v4
	v_mul_f32_e32 v23, 0xbfb8aa3b, v23
	v_mul_f32_e32 v24, 0xbfb8aa3b, v24
	v_mul_f32_e32 v26, 0xbfb8aa3b, v26
	v_mul_f32_e32 v25, 0xbfb8aa3b, v25
	v_mul_f32_e32 v5, 0xbfb8aa3b, v5
	v_mul_f32_e32 v22, 0xbfb8aa3b, v22
	v_exp_f32_e32 v3, v3
	v_exp_f32_e32 v4, v4
	v_exp_f32_e32 v23, v23
	v_exp_f32_e32 v24, v24
	v_exp_f32_e32 v26, v26
	v_exp_f32_e32 v25, v25
	v_exp_f32_e32 v5, v5
	v_exp_f32_e32 v22, v22
	v_add_f32_e32 v3, 1.0, v3
	v_add_f32_e32 v27, 1.0, v4
	v_add_f32_e32 v30, 1.0, v23
	v_add_f32_e32 v31, 1.0, v24
	v_add_f32_e32 v26, 1.0, v26
	v_add_f32_e32 v25, 1.0, v25
	v_add_f32_e32 v28, 1.0, v5
	v_add_f32_e32 v29, 1.0, v22
	v_rcp_f32_e32 v4, v3
	v_rcp_f32_e32 v5, v27
	v_rcp_f32_e32 v24, v30
	v_rcp_f32_e32 v26, v26
	v_rcp_f32_e32 v27, v25
	v_rcp_f32_e32 v25, v31
	v_rcp_f32_e32 v22, v28
	v_rcp_f32_e32 v23, v29
	v_pk_mul_f32 v[4:5], v[18:19], v[4:5]
	v_pk_mul_f32 v[18:19], v[16:17], v[26:27]
	v_pk_mul_f32 v[16:17], v[14:15], v[24:25]
	v_pk_mul_f32 v[20:21], v[20:21], v[22:23]
	v_cvt_pk_bf16_f32 v14, v4, v5
	s_nop 0
	v_cvt_pk_bf16_f32 v15, v20, v21
	v_cvt_pk_bf16_f32 v16, v16, v17
	v_cvt_pk_bf16_f32 v17, v18, v19
	global_store_dwordx4 v[88:89], v[14:17], off offset:256
	global_load_dwordx4 v[14:17], v[86:87], off offset:256
	s_waitcnt vmcnt(0)
	v_lshlrev_b32_e32 v3, 16, v14
	v_and_b32_e32 v4, 0xffff0000, v14
	v_lshlrev_b32_e32 v5, 16, v15
	v_and_b32_e32 v14, 0xffff0000, v15
	v_lshlrev_b32_e32 v15, 16, v16
	v_and_b32_e32 v16, 0xffff0000, v16
	v_lshlrev_b32_e32 v18, 16, v17
	v_and_b32_e32 v17, 0xffff0000, v17
	v_add_f32_e32 v3, v74, v3
	v_add_f32_e32 v4, v75, v4
	v_add_f32_e32 v15, v70, v15
	v_add_f32_e32 v16, v71, v16
	v_add_f32_e32 v17, v73, v17
	v_add_f32_e32 v5, v76, v5
	v_add_f32_e32 v14, v77, v14
	v_add_f32_e32 v18, v72, v18
	v_max_f32_e32 v3, 0xc2700000, v3
	v_max_f32_e32 v4, 0xc2700000, v4
	v_max_f32_e32 v15, 0xc2700000, v15
	v_max_f32_e32 v16, 0xc2700000, v16
	v_max_f32_e32 v17, 0xc2700000, v17
	v_max_f32_e32 v5, 0xc2700000, v5
	v_max_f32_e32 v14, 0xc2700000, v14
	v_max_f32_e32 v18, 0xc2700000, v18
	v_mul_f32_e32 v3, 0xbfb8aa3b, v3
	v_mul_f32_e32 v4, 0xbfb8aa3b, v4
	v_mul_f32_e32 v15, 0xbfb8aa3b, v15
	v_mul_f32_e32 v16, 0xbfb8aa3b, v16
	v_mul_f32_e32 v17, 0xbfb8aa3b, v17
	v_mul_f32_e32 v5, 0xbfb8aa3b, v5
	v_mul_f32_e32 v14, 0xbfb8aa3b, v14
	v_mul_f32_e32 v18, 0xbfb8aa3b, v18
	v_exp_f32_e32 v3, v3
	v_exp_f32_e32 v4, v4
	v_exp_f32_e32 v15, v15
	v_exp_f32_e32 v16, v16
	v_exp_f32_e32 v17, v17
	v_exp_f32_e32 v5, v5
	v_exp_f32_e32 v14, v14
	v_exp_f32_e32 v18, v18
	v_add_f32_e32 v3, 1.0, v3
	v_add_f32_e32 v19, 1.0, v4
	v_add_f32_e32 v22, 1.0, v15
	v_add_f32_e32 v23, 1.0, v16
	v_add_f32_e32 v17, 1.0, v17
	v_add_f32_e32 v20, 1.0, v5
	v_add_f32_e32 v21, 1.0, v14
	v_add_f32_e32 v18, 1.0, v18
	v_rcp_f32_e32 v4, v3
	v_rcp_f32_e32 v5, v19
	v_rcp_f32_e32 v16, v22
	v_rcp_f32_e32 v19, v17
	v_rcp_f32_e32 v17, v23
	v_rcp_f32_e32 v14, v20
	v_rcp_f32_e32 v15, v21
	v_rcp_f32_e32 v18, v18
	v_pk_mul_f32 v[4:5], v[10:11], v[4:5]
	v_pk_mul_f32 v[6:7], v[6:7], v[16:17]
	v_pk_mul_f32 v[12:13], v[12:13], v[14:15]
	v_pk_mul_f32 v[8:9], v[8:9], v[18:19]
	v_cvt_pk_bf16_f32 v4, v4, v5
	v_cvt_pk_bf16_f32 v5, v12, v13
	v_cvt_pk_bf16_f32 v6, v6, v7
	s_nop 0
	v_cvt_pk_bf16_f32 v7, v8, v9
	global_store_dwordx4 v[78:79], v[4:7], off offset:256
	s_cbranch_vccnz .LBB0_611
	s_andn2_b64 vcc, exec, s[8:9]
	s_cbranch_vccnz .LBB0_610
	s_barrier
	s_branch .LBB0_610
